# V pass: each half's residual rows are fetched into the freed row buffers during the last step of its sweep (no redundant prefetch, no exposed load before the epilogue)
# speedup vs baseline: 1.0441x; 1.0080x over previous
; DI void peer_item_v(const Params& p, int item) {
;     ...
; #pragma unroll 1
;   for (int ti = 0; ti < 8; ++ti) {
;     const size_t tok = (size_t)item * 32 + wave * 8 + ti;
;     const int e_lo = EG[tok * 128 + lane], e_hi = EG[tok * 128 + 64 + lane];
;     const int a_lo = __float_as_int(AG[tok * 128 + lane]), a_hi = __float_as_int(AG[tok * 128 + 64 + lane]);
;     float out[16];
; #pragma unroll
;     for (int i = 0; i < 16; ++i) out[i] = 0.f;
;     u32x4 vqa[8], vqb[8];
.Lvq_item:
	s_lshl_b32 s14, s10, 5
	s_add_u32 s14, s14, s56
	s_lshl_b32 s13, s14, 9
	s_add_u32 s58, s2, s13
	s_addc_u32 s59, s3, 0
	s_add_u32 s60, s4, s13
	s_addc_u32 s61, s5, 0
	v_lshrrev_b32_e32 v250, 3, v249
	v_and_b32_e32 v251, 7, v249
	v_lshlrev_b32_e32 v250, 6, v250
	v_lshl_add_u32 v250, v251, 2, v250
	s_lshr_b32 s13, s68, 8
	s_mul_i32 s13, s13, 0x13f00
	s_lshl_b32 s15, s56, 9
	s_add_u32 s13, s13, s15
	s_add_u32 s13, s13, 32
	v_add_u32_e32 v250, s13, v250
	ds_read_b32 v128, v250 offset:0
	ds_read_b32 v129, v250 offset:32
	ds_read_b32 v130, v250 offset:32768
	ds_read_b32 v131, v250 offset:32800
	ds_read_b32 v132, v250 offset:512
	ds_read_b32 v133, v250 offset:544
	ds_read_b32 v134, v250 offset:33280
	ds_read_b32 v135, v250 offset:33312
	ds_read_b32 v136, v250 offset:1024
	ds_read_b32 v137, v250 offset:1056
	ds_read_b32 v138, v250 offset:33792
	ds_read_b32 v139, v250 offset:33824
	ds_read_b32 v140, v250 offset:1536
	ds_read_b32 v141, v250 offset:1568
	ds_read_b32 v142, v250 offset:34304
	ds_read_b32 v143, v250 offset:34336
	ds_read_b32 v144, v250 offset:2048
	ds_read_b32 v145, v250 offset:2080
	ds_read_b32 v146, v250 offset:34816
	ds_read_b32 v147, v250 offset:34848
	ds_read_b32 v148, v250 offset:2560
	ds_read_b32 v149, v250 offset:2592
	ds_read_b32 v150, v250 offset:35328
	ds_read_b32 v151, v250 offset:35360
	ds_read_b32 v152, v250 offset:3072
	ds_read_b32 v153, v250 offset:3104
	ds_read_b32 v154, v250 offset:35840
	ds_read_b32 v155, v250 offset:35872
	ds_read_b32 v156, v250 offset:3584
	ds_read_b32 v157, v250 offset:3616
	ds_read_b32 v158, v250 offset:36352
	ds_read_b32 v159, v250 offset:36384
	v_add_u32_e32 v160, s57, v241
	v_mov_b32_e32 v161, 0
	v_mov_b32_e32 v162, 1
	v_lshrrev_b32_e32 v163, 3, v249
	v_and_b32_e32 v164, 7, v249
	v_lshlrev_b32_e32 v163, 6, v163
	v_lshl_add_u32 v163, v164, 2, v163
	v_add_u32_e32 v163, s57, v163
	v_add_u32_e32 v164, 32, v163
	v_subrev_u32_e32 v165, 1, v249
	v_subrev_u32_e32 v166, 2, v249
	v_subrev_u32_e32 v167, 4, v249
	v_subrev_u32_e32 v168, 8, v249
	v_subrev_u32_e32 v169, 16, v249
	v_subrev_u32_e32 v170, 32, v249
	v_lshlrev_b32_e32 v165, 2, v165
	v_lshlrev_b32_e32 v166, 2, v166
	v_lshlrev_b32_e32 v167, 2, v167
	v_lshlrev_b32_e32 v168, 2, v168
	v_lshlrev_b32_e32 v169, 2, v169
	v_lshlrev_b32_e32 v170, 2, v170
	v_mov_b32_e32 v0, 0
	v_mov_b32_e32 v1, 0
	v_mov_b32_e32 v2, 0
	v_mov_b32_e32 v3, 0
	v_mov_b32_e32 v4, 0
	v_mov_b32_e32 v5, 0
	v_mov_b32_e32 v6, 0
	v_mov_b32_e32 v7, 0
	v_mov_b32_e32 v8, 0
	v_mov_b32_e32 v9, 0
	v_mov_b32_e32 v10, 0
	v_mov_b32_e32 v11, 0
	v_mov_b32_e32 v12, 0
	v_mov_b32_e32 v13, 0
	v_mov_b32_e32 v14, 0
	v_mov_b32_e32 v15, 0
	v_mov_b32_e32 v16, 0
	v_mov_b32_e32 v17, 0
	v_mov_b32_e32 v18, 0
	v_mov_b32_e32 v19, 0
	v_mov_b32_e32 v20, 0
	v_mov_b32_e32 v21, 0
	v_mov_b32_e32 v22, 0
	v_mov_b32_e32 v23, 0
	v_mov_b32_e32 v24, 0
	v_mov_b32_e32 v25, 0
	v_mov_b32_e32 v26, 0
	v_mov_b32_e32 v27, 0
	v_mov_b32_e32 v28, 0
	v_mov_b32_e32 v29, 0
	v_mov_b32_e32 v30, 0
	v_mov_b32_e32 v31, 0
	v_mov_b32_e32 v32, 0
	v_mov_b32_e32 v33, 0
	v_mov_b32_e32 v34, 0
	v_mov_b32_e32 v35, 0
	v_mov_b32_e32 v36, 0
	v_mov_b32_e32 v37, 0
	v_mov_b32_e32 v38, 0
	v_mov_b32_e32 v39, 0
	v_mov_b32_e32 v40, 0
	v_mov_b32_e32 v41, 0
	v_mov_b32_e32 v42, 0
	v_mov_b32_e32 v43, 0
	v_mov_b32_e32 v44, 0
	v_mov_b32_e32 v45, 0
	v_mov_b32_e32 v46, 0
	v_mov_b32_e32 v47, 0
	v_mov_b32_e32 v48, 0
	v_mov_b32_e32 v49, 0
	v_mov_b32_e32 v50, 0
	v_mov_b32_e32 v51, 0
	v_mov_b32_e32 v52, 0
	v_mov_b32_e32 v53, 0
	v_mov_b32_e32 v54, 0
	v_mov_b32_e32 v55, 0
	v_mov_b32_e32 v56, 0
	v_mov_b32_e32 v57, 0
	v_mov_b32_e32 v58, 0
	v_mov_b32_e32 v59, 0
	v_mov_b32_e32 v60, 0
	v_mov_b32_e32 v61, 0
	v_mov_b32_e32 v62, 0
	v_mov_b32_e32 v63, 0
	s_waitcnt vmcnt(0) lgkmcnt(0)
	v_lshlrev_b32_e32 v128, 10, v128
	v_lshlrev_b32_e32 v129, 10, v129
	v_lshlrev_b32_e32 v132, 10, v132
	v_lshlrev_b32_e32 v133, 10, v133
	v_lshlrev_b32_e32 v136, 10, v136
	v_lshlrev_b32_e32 v137, 10, v137
	v_lshlrev_b32_e32 v140, 10, v140
	v_lshlrev_b32_e32 v141, 10, v141
	v_lshlrev_b32_e32 v144, 10, v144
	v_lshlrev_b32_e32 v145, 10, v145
	v_lshlrev_b32_e32 v148, 10, v148
	v_lshlrev_b32_e32 v149, 10, v149
	v_lshlrev_b32_e32 v152, 10, v152
	v_lshlrev_b32_e32 v153, 10, v153
	v_lshlrev_b32_e32 v156, 10, v156
	v_lshlrev_b32_e32 v157, 10, v157
	s_lshl_b32 s15, s14, 12
	s_add_u32 s62, s6, s15
	s_addc_u32 s63, s7, 0
	s_add_u32 s88, s62, 0
	s_addc_u32 s89, s63, 0
	s_add_u32 s90, s62, 4096
	s_addc_u32 s91, s63, 0
	s_add_u32 s92, s62, 8192
	s_addc_u32 s93, s63, 0
	s_add_u32 s94, s62, 12288
	s_addc_u32 s95, s63, 0
	s_mov_b32 s72, 0
	s_mov_b32 s73, 1
	s_mov_b32 s74, 2
	s_mov_b32 s75, 3
	s_mov_b32 s76, 4
	s_mov_b32 s77, 5
	s_mov_b32 s78, 6
	s_mov_b32 s79, 7
	s_mov_b32 s80, 8
	s_mov_b32 s81, 9
	s_mov_b32 s82, 10
	s_mov_b32 s83, 11
	s_mov_b32 s84, 12
	s_mov_b32 s85, 13
	s_mov_b32 s86, 14
	s_mov_b32 s87, 15
	s_nop 0
	v_readlane_b32 s48, v128, s72
	v_readlane_b32 s49, v128, s73
	v_readlane_b32 s50, v128, s74
	v_readlane_b32 s51, v128, s75
	v_readlane_b32 s52, v128, s76
	v_readlane_b32 s53, v128, s77
	v_readlane_b32 s54, v128, s78
	v_readlane_b32 s55, v128, s79
	s_add_u32 s32, s0, s48
	s_addc_u32 s33, s1, 0
	s_add_u32 s34, s0, s49
	s_addc_u32 s35, s1, 0
	s_add_u32 s36, s0, s50
	s_addc_u32 s37, s1, 0
	s_add_u32 s38, s0, s51
	s_addc_u32 s39, s1, 0
	s_add_u32 s40, s0, s52
	s_addc_u32 s41, s1, 0
	s_add_u32 s42, s0, s53
	s_addc_u32 s43, s1, 0
	s_add_u32 s44, s0, s54
	s_addc_u32 s45, s1, 0
	s_add_u32 s46, s0, s55
	s_addc_u32 s47, s1, 0
	global_load_dwordx4 v[160:163], v240, s[32:33]
	global_load_dwordx4 v[164:167], v240, s[34:35]
	global_load_dwordx4 v[168:171], v240, s[36:37]
	global_load_dwordx4 v[172:175], v240, s[38:39]
	global_load_dwordx4 v[176:179], v240, s[40:41]
	global_load_dwordx4 v[180:183], v240, s[42:43]
	global_load_dwordx4 v[184:187], v240, s[44:45]
	global_load_dwordx4 v[188:191], v240, s[46:47]
	v_readlane_b32 s48, v132, s72
	v_readlane_b32 s49, v132, s73
	v_readlane_b32 s50, v132, s74
	v_readlane_b32 s51, v132, s75
	v_readlane_b32 s52, v132, s76
	v_readlane_b32 s53, v132, s77
	v_readlane_b32 s54, v132, s78
	v_readlane_b32 s55, v132, s79
	s_add_u32 s32, s0, s48
	s_addc_u32 s33, s1, 0
	s_add_u32 s34, s0, s49
	s_addc_u32 s35, s1, 0
	s_add_u32 s36, s0, s50
	s_addc_u32 s37, s1, 0
	s_add_u32 s38, s0, s51
	s_addc_u32 s39, s1, 0
	s_add_u32 s40, s0, s52
	s_addc_u32 s41, s1, 0
	s_add_u32 s42, s0, s53
	s_addc_u32 s43, s1, 0
	s_add_u32 s44, s0, s54
	s_addc_u32 s45, s1, 0
	s_add_u32 s46, s0, s55
	s_addc_u32 s47, s1, 0
	global_load_dwordx4 v[192:195], v240, s[32:33]
	global_load_dwordx4 v[196:199], v240, s[34:35]
	global_load_dwordx4 v[200:203], v240, s[36:37]
	global_load_dwordx4 v[204:207], v240, s[38:39]
	global_load_dwordx4 v[208:211], v240, s[40:41]
	global_load_dwordx4 v[212:215], v240, s[42:43]
	global_load_dwordx4 v[216:219], v240, s[44:45]
	global_load_dwordx4 v[220:223], v240, s[46:47]
	v_readlane_b32 s48, v136, s72
	v_readlane_b32 s49, v136, s73
	v_readlane_b32 s50, v136, s74
	v_readlane_b32 s51, v136, s75
	v_readlane_b32 s52, v136, s76
	v_readlane_b32 s53, v136, s77
	v_readlane_b32 s54, v136, s78
	v_readlane_b32 s55, v136, s79
	s_add_u32 s32, s0, s48
	s_addc_u32 s33, s1, 0
	s_add_u32 s34, s0, s49
	s_addc_u32 s35, s1, 0
	s_add_u32 s36, s0, s50
	s_addc_u32 s37, s1, 0
	s_add_u32 s38, s0, s51
	s_addc_u32 s39, s1, 0
	s_add_u32 s40, s0, s52
	s_addc_u32 s41, s1, 0
	s_add_u32 s42, s0, s53
	s_addc_u32 s43, s1, 0
	s_add_u32 s44, s0, s54
	s_addc_u32 s45, s1, 0
	s_add_u32 s46, s0, s55
	s_addc_u32 s47, s1, 0
	global_load_dwordx4 v[64:67], v240, s[32:33]
	global_load_dwordx4 v[68:71], v240, s[34:35]
	global_load_dwordx4 v[72:75], v240, s[36:37]
	global_load_dwordx4 v[76:79], v240, s[38:39]
	global_load_dwordx4 v[80:83], v240, s[40:41]
	global_load_dwordx4 v[84:87], v240, s[42:43]
	global_load_dwordx4 v[88:91], v240, s[44:45]
	global_load_dwordx4 v[92:95], v240, s[46:47]
	s_mov_b32 s12, 0
.Lvq_kA:
	v_readlane_b32 s16, v130, s72
	v_readlane_b32 s18, v130, s73
	v_readlane_b32 s20, v130, s74
	v_readlane_b32 s22, v130, s75
	v_readlane_b32 s24, v130, s76
	v_readlane_b32 s26, v130, s77
	v_readlane_b32 s28, v130, s78
	v_readlane_b32 s30, v130, s79
	v_readlane_b32 s48, v140, s72
	v_readlane_b32 s49, v140, s73
	v_readlane_b32 s50, v140, s74
	v_readlane_b32 s51, v140, s75
	v_readlane_b32 s52, v140, s76
	v_readlane_b32 s53, v140, s77
	v_readlane_b32 s54, v140, s78
	v_readlane_b32 s55, v140, s79
	s_add_u32 s32, s0, s48
	s_addc_u32 s33, s1, 0
	s_add_u32 s34, s0, s49
	s_addc_u32 s35, s1, 0
	s_add_u32 s36, s0, s50
	s_addc_u32 s37, s1, 0
	s_add_u32 s38, s0, s51
	s_addc_u32 s39, s1, 0
	s_add_u32 s40, s0, s52
	s_addc_u32 s41, s1, 0
	s_add_u32 s42, s0, s53
	s_addc_u32 s43, s1, 0
	s_add_u32 s44, s0, s54
	s_addc_u32 s45, s1, 0
	s_add_u32 s46, s0, s55
	s_addc_u32 s47, s1, 0
	global_load_dwordx4 v[96:99], v240, s[32:33]
	global_load_dwordx4 v[100:103], v240, s[34:35]
	global_load_dwordx4 v[104:107], v240, s[36:37]
	global_load_dwordx4 v[108:111], v240, s[38:39]
	global_load_dwordx4 v[112:115], v240, s[40:41]
	global_load_dwordx4 v[116:119], v240, s[42:43]
	global_load_dwordx4 v[120:123], v240, s[44:45]
	global_load_dwordx4 v[124:127], v240, s[46:47]
	s_waitcnt vmcnt(24)
	v_cvt_pk_f32_fp8_e32 v[224:225], v160
	v_cvt_pk_f32_fp8_sdwa v[226:227], v160 src0_sel:WORD_1
	v_cvt_pk_f32_fp8_e32 v[228:229], v161
	v_cvt_pk_f32_fp8_sdwa v[230:231], v161 src0_sel:WORD_1
	v_cvt_pk_f32_fp8_e32 v[232:233], v162
	v_cvt_pk_f32_fp8_sdwa v[234:235], v162 src0_sel:WORD_1
	v_cvt_pk_f32_fp8_e32 v[236:237], v163
	v_cvt_pk_f32_fp8_sdwa v[238:239], v163 src0_sel:WORD_1
	v_pk_fma_f32 v[0:1], v[224:225], s[16:17], v[0:1] op_sel_hi:[1,0,1]
	v_pk_fma_f32 v[2:3], v[226:227], s[16:17], v[2:3] op_sel_hi:[1,0,1]
	v_pk_fma_f32 v[4:5], v[228:229], s[16:17], v[4:5] op_sel_hi:[1,0,1]
	v_pk_fma_f32 v[6:7], v[230:231], s[16:17], v[6:7] op_sel_hi:[1,0,1]
	v_pk_fma_f32 v[8:9], v[232:233], s[16:17], v[8:9] op_sel_hi:[1,0,1]
	v_pk_fma_f32 v[10:11], v[234:235], s[16:17], v[10:11] op_sel_hi:[1,0,1]
	v_pk_fma_f32 v[12:13], v[236:237], s[16:17], v[12:13] op_sel_hi:[1,0,1]
	v_pk_fma_f32 v[14:15], v[238:239], s[16:17], v[14:15] op_sel_hi:[1,0,1]
	v_cvt_pk_f32_fp8_e32 v[224:225], v164
	v_cvt_pk_f32_fp8_sdwa v[226:227], v164 src0_sel:WORD_1
	v_cvt_pk_f32_fp8_e32 v[228:229], v165
	v_cvt_pk_f32_fp8_sdwa v[230:231], v165 src0_sel:WORD_1
	v_cvt_pk_f32_fp8_e32 v[232:233], v166
	v_cvt_pk_f32_fp8_sdwa v[234:235], v166 src0_sel:WORD_1
	v_cvt_pk_f32_fp8_e32 v[236:237], v167
	v_cvt_pk_f32_fp8_sdwa v[238:239], v167 src0_sel:WORD_1
	v_pk_fma_f32 v[0:1], v[224:225], s[18:19], v[0:1] op_sel_hi:[1,0,1]
	v_pk_fma_f32 v[2:3], v[226:227], s[18:19], v[2:3] op_sel_hi:[1,0,1]
	v_pk_fma_f32 v[4:5], v[228:229], s[18:19], v[4:5] op_sel_hi:[1,0,1]
	v_pk_fma_f32 v[6:7], v[230:231], s[18:19], v[6:7] op_sel_hi:[1,0,1]
	v_pk_fma_f32 v[8:9], v[232:233], s[18:19], v[8:9] op_sel_hi:[1,0,1]
	v_pk_fma_f32 v[10:11], v[234:235], s[18:19], v[10:11] op_sel_hi:[1,0,1]
	v_pk_fma_f32 v[12:13], v[236:237], s[18:19], v[12:13] op_sel_hi:[1,0,1]
	v_pk_fma_f32 v[14:15], v[238:239], s[18:19], v[14:15] op_sel_hi:[1,0,1]
	v_cvt_pk_f32_fp8_e32 v[224:225], v168
	v_cvt_pk_f32_fp8_sdwa v[226:227], v168 src0_sel:WORD_1
	v_cvt_pk_f32_fp8_e32 v[228:229], v169
	v_cvt_pk_f32_fp8_sdwa v[230:231], v169 src0_sel:WORD_1
	v_cvt_pk_f32_fp8_e32 v[232:233], v170
	v_cvt_pk_f32_fp8_sdwa v[234:235], v170 src0_sel:WORD_1
	v_cvt_pk_f32_fp8_e32 v[236:237], v171
	v_cvt_pk_f32_fp8_sdwa v[238:239], v171 src0_sel:WORD_1
	v_pk_fma_f32 v[0:1], v[224:225], s[20:21], v[0:1] op_sel_hi:[1,0,1]
	v_pk_fma_f32 v[2:3], v[226:227], s[20:21], v[2:3] op_sel_hi:[1,0,1]
	v_pk_fma_f32 v[4:5], v[228:229], s[20:21], v[4:5] op_sel_hi:[1,0,1]
	v_pk_fma_f32 v[6:7], v[230:231], s[20:21], v[6:7] op_sel_hi:[1,0,1]
	v_pk_fma_f32 v[8:9], v[232:233], s[20:21], v[8:9] op_sel_hi:[1,0,1]
	v_pk_fma_f32 v[10:11], v[234:235], s[20:21], v[10:11] op_sel_hi:[1,0,1]
	v_pk_fma_f32 v[12:13], v[236:237], s[20:21], v[12:13] op_sel_hi:[1,0,1]
	v_pk_fma_f32 v[14:15], v[238:239], s[20:21], v[14:15] op_sel_hi:[1,0,1]
	v_cvt_pk_f32_fp8_e32 v[224:225], v172
	v_cvt_pk_f32_fp8_sdwa v[226:227], v172 src0_sel:WORD_1
	v_cvt_pk_f32_fp8_e32 v[228:229], v173
	v_cvt_pk_f32_fp8_sdwa v[230:231], v173 src0_sel:WORD_1
	v_cvt_pk_f32_fp8_e32 v[232:233], v174
	v_cvt_pk_f32_fp8_sdwa v[234:235], v174 src0_sel:WORD_1
	v_cvt_pk_f32_fp8_e32 v[236:237], v175
	v_cvt_pk_f32_fp8_sdwa v[238:239], v175 src0_sel:WORD_1
	v_pk_fma_f32 v[0:1], v[224:225], s[22:23], v[0:1] op_sel_hi:[1,0,1]
	v_pk_fma_f32 v[2:3], v[226:227], s[22:23], v[2:3] op_sel_hi:[1,0,1]
	v_pk_fma_f32 v[4:5], v[228:229], s[22:23], v[4:5] op_sel_hi:[1,0,1]
	v_pk_fma_f32 v[6:7], v[230:231], s[22:23], v[6:7] op_sel_hi:[1,0,1]
	v_pk_fma_f32 v[8:9], v[232:233], s[22:23], v[8:9] op_sel_hi:[1,0,1]
	v_pk_fma_f32 v[10:11], v[234:235], s[22:23], v[10:11] op_sel_hi:[1,0,1]
	v_pk_fma_f32 v[12:13], v[236:237], s[22:23], v[12:13] op_sel_hi:[1,0,1]
	v_pk_fma_f32 v[14:15], v[238:239], s[22:23], v[14:15] op_sel_hi:[1,0,1]
	v_cvt_pk_f32_fp8_e32 v[224:225], v176
	v_cvt_pk_f32_fp8_sdwa v[226:227], v176 src0_sel:WORD_1
	v_cvt_pk_f32_fp8_e32 v[228:229], v177
	v_cvt_pk_f32_fp8_sdwa v[230:231], v177 src0_sel:WORD_1
	v_cvt_pk_f32_fp8_e32 v[232:233], v178
	v_cvt_pk_f32_fp8_sdwa v[234:235], v178 src0_sel:WORD_1
	v_cvt_pk_f32_fp8_e32 v[236:237], v179
	v_cvt_pk_f32_fp8_sdwa v[238:239], v179 src0_sel:WORD_1
	v_pk_fma_f32 v[0:1], v[224:225], s[24:25], v[0:1] op_sel_hi:[1,0,1]
	v_pk_fma_f32 v[2:3], v[226:227], s[24:25], v[2:3] op_sel_hi:[1,0,1]
	v_pk_fma_f32 v[4:5], v[228:229], s[24:25], v[4:5] op_sel_hi:[1,0,1]
	v_pk_fma_f32 v[6:7], v[230:231], s[24:25], v[6:7] op_sel_hi:[1,0,1]
	v_pk_fma_f32 v[8:9], v[232:233], s[24:25], v[8:9] op_sel_hi:[1,0,1]
	v_pk_fma_f32 v[10:11], v[234:235], s[24:25], v[10:11] op_sel_hi:[1,0,1]
	v_pk_fma_f32 v[12:13], v[236:237], s[24:25], v[12:13] op_sel_hi:[1,0,1]
	v_pk_fma_f32 v[14:15], v[238:239], s[24:25], v[14:15] op_sel_hi:[1,0,1]
	v_cvt_pk_f32_fp8_e32 v[224:225], v180
	v_cvt_pk_f32_fp8_sdwa v[226:227], v180 src0_sel:WORD_1
	v_cvt_pk_f32_fp8_e32 v[228:229], v181
	v_cvt_pk_f32_fp8_sdwa v[230:231], v181 src0_sel:WORD_1
	v_cvt_pk_f32_fp8_e32 v[232:233], v182
	v_cvt_pk_f32_fp8_sdwa v[234:235], v182 src0_sel:WORD_1
	v_cvt_pk_f32_fp8_e32 v[236:237], v183
	v_cvt_pk_f32_fp8_sdwa v[238:239], v183 src0_sel:WORD_1
	v_pk_fma_f32 v[0:1], v[224:225], s[26:27], v[0:1] op_sel_hi:[1,0,1]
	v_pk_fma_f32 v[2:3], v[226:227], s[26:27], v[2:3] op_sel_hi:[1,0,1]
	v_pk_fma_f32 v[4:5], v[228:229], s[26:27], v[4:5] op_sel_hi:[1,0,1]
	v_pk_fma_f32 v[6:7], v[230:231], s[26:27], v[6:7] op_sel_hi:[1,0,1]
	v_pk_fma_f32 v[8:9], v[232:233], s[26:27], v[8:9] op_sel_hi:[1,0,1]
	v_pk_fma_f32 v[10:11], v[234:235], s[26:27], v[10:11] op_sel_hi:[1,0,1]
	v_pk_fma_f32 v[12:13], v[236:237], s[26:27], v[12:13] op_sel_hi:[1,0,1]
	v_pk_fma_f32 v[14:15], v[238:239], s[26:27], v[14:15] op_sel_hi:[1,0,1]
	v_cvt_pk_f32_fp8_e32 v[224:225], v184
	v_cvt_pk_f32_fp8_sdwa v[226:227], v184 src0_sel:WORD_1
	v_cvt_pk_f32_fp8_e32 v[228:229], v185
	v_cvt_pk_f32_fp8_sdwa v[230:231], v185 src0_sel:WORD_1
	v_cvt_pk_f32_fp8_e32 v[232:233], v186
	v_cvt_pk_f32_fp8_sdwa v[234:235], v186 src0_sel:WORD_1
	v_cvt_pk_f32_fp8_e32 v[236:237], v187
	v_cvt_pk_f32_fp8_sdwa v[238:239], v187 src0_sel:WORD_1
	v_pk_fma_f32 v[0:1], v[224:225], s[28:29], v[0:1] op_sel_hi:[1,0,1]
	v_pk_fma_f32 v[2:3], v[226:227], s[28:29], v[2:3] op_sel_hi:[1,0,1]
	v_pk_fma_f32 v[4:5], v[228:229], s[28:29], v[4:5] op_sel_hi:[1,0,1]
	v_pk_fma_f32 v[6:7], v[230:231], s[28:29], v[6:7] op_sel_hi:[1,0,1]
	v_pk_fma_f32 v[8:9], v[232:233], s[28:29], v[8:9] op_sel_hi:[1,0,1]
	v_pk_fma_f32 v[10:11], v[234:235], s[28:29], v[10:11] op_sel_hi:[1,0,1]
	v_pk_fma_f32 v[12:13], v[236:237], s[28:29], v[12:13] op_sel_hi:[1,0,1]
	v_pk_fma_f32 v[14:15], v[238:239], s[28:29], v[14:15] op_sel_hi:[1,0,1]
	v_cvt_pk_f32_fp8_e32 v[224:225], v188
	v_cvt_pk_f32_fp8_sdwa v[226:227], v188 src0_sel:WORD_1
	v_cvt_pk_f32_fp8_e32 v[228:229], v189
	v_cvt_pk_f32_fp8_sdwa v[230:231], v189 src0_sel:WORD_1
	v_cvt_pk_f32_fp8_e32 v[232:233], v190
	v_cvt_pk_f32_fp8_sdwa v[234:235], v190 src0_sel:WORD_1
	v_cvt_pk_f32_fp8_e32 v[236:237], v191
	v_cvt_pk_f32_fp8_sdwa v[238:239], v191 src0_sel:WORD_1
	v_pk_fma_f32 v[0:1], v[224:225], s[30:31], v[0:1] op_sel_hi:[1,0,1]
	v_pk_fma_f32 v[2:3], v[226:227], s[30:31], v[2:3] op_sel_hi:[1,0,1]
	v_pk_fma_f32 v[4:5], v[228:229], s[30:31], v[4:5] op_sel_hi:[1,0,1]
	v_pk_fma_f32 v[6:7], v[230:231], s[30:31], v[6:7] op_sel_hi:[1,0,1]
	v_pk_fma_f32 v[8:9], v[232:233], s[30:31], v[8:9] op_sel_hi:[1,0,1]
	v_pk_fma_f32 v[10:11], v[234:235], s[30:31], v[10:11] op_sel_hi:[1,0,1]
	v_pk_fma_f32 v[12:13], v[236:237], s[30:31], v[12:13] op_sel_hi:[1,0,1]
	v_pk_fma_f32 v[14:15], v[238:239], s[30:31], v[14:15] op_sel_hi:[1,0,1]
	v_readlane_b32 s16, v134, s72
	v_readlane_b32 s18, v134, s73
	v_readlane_b32 s20, v134, s74
	v_readlane_b32 s22, v134, s75
	v_readlane_b32 s24, v134, s76
	v_readlane_b32 s26, v134, s77
	v_readlane_b32 s28, v134, s78
	v_readlane_b32 s30, v134, s79
	v_readlane_b32 s48, v129, s72
	v_readlane_b32 s49, v129, s73
	v_readlane_b32 s50, v129, s74
	v_readlane_b32 s51, v129, s75
	v_readlane_b32 s52, v129, s76
	v_readlane_b32 s53, v129, s77
	v_readlane_b32 s54, v129, s78
	v_readlane_b32 s55, v129, s79
	s_add_u32 s32, s0, s48
	s_addc_u32 s33, s1, 0
	s_add_u32 s34, s0, s49
	s_addc_u32 s35, s1, 0
	s_add_u32 s36, s0, s50
	s_addc_u32 s37, s1, 0
	s_add_u32 s38, s0, s51
	s_addc_u32 s39, s1, 0
	s_add_u32 s40, s0, s52
	s_addc_u32 s41, s1, 0
	s_add_u32 s42, s0, s53
	s_addc_u32 s43, s1, 0
	s_add_u32 s44, s0, s54
	s_addc_u32 s45, s1, 0
	s_add_u32 s46, s0, s55
	s_addc_u32 s47, s1, 0
	global_load_dwordx4 v[160:163], v240, s[32:33]
	global_load_dwordx4 v[164:167], v240, s[34:35]
	global_load_dwordx4 v[168:171], v240, s[36:37]
	global_load_dwordx4 v[172:175], v240, s[38:39]
	global_load_dwordx4 v[176:179], v240, s[40:41]
	global_load_dwordx4 v[180:183], v240, s[42:43]
	global_load_dwordx4 v[184:187], v240, s[44:45]
	global_load_dwordx4 v[188:191], v240, s[46:47]
	s_waitcnt vmcnt(24)
	v_cvt_pk_f32_fp8_e32 v[224:225], v192
	v_cvt_pk_f32_fp8_sdwa v[226:227], v192 src0_sel:WORD_1
	v_cvt_pk_f32_fp8_e32 v[228:229], v193
	v_cvt_pk_f32_fp8_sdwa v[230:231], v193 src0_sel:WORD_1
	v_cvt_pk_f32_fp8_e32 v[232:233], v194
	v_cvt_pk_f32_fp8_sdwa v[234:235], v194 src0_sel:WORD_1
	v_cvt_pk_f32_fp8_e32 v[236:237], v195
	v_cvt_pk_f32_fp8_sdwa v[238:239], v195 src0_sel:WORD_1
	v_pk_fma_f32 v[16:17], v[224:225], s[16:17], v[16:17] op_sel_hi:[1,0,1]
	v_pk_fma_f32 v[18:19], v[226:227], s[16:17], v[18:19] op_sel_hi:[1,0,1]
	v_pk_fma_f32 v[20:21], v[228:229], s[16:17], v[20:21] op_sel_hi:[1,0,1]
	v_pk_fma_f32 v[22:23], v[230:231], s[16:17], v[22:23] op_sel_hi:[1,0,1]
	v_pk_fma_f32 v[24:25], v[232:233], s[16:17], v[24:25] op_sel_hi:[1,0,1]
	v_pk_fma_f32 v[26:27], v[234:235], s[16:17], v[26:27] op_sel_hi:[1,0,1]
	v_pk_fma_f32 v[28:29], v[236:237], s[16:17], v[28:29] op_sel_hi:[1,0,1]
	v_pk_fma_f32 v[30:31], v[238:239], s[16:17], v[30:31] op_sel_hi:[1,0,1]
	v_cvt_pk_f32_fp8_e32 v[224:225], v196
	v_cvt_pk_f32_fp8_sdwa v[226:227], v196 src0_sel:WORD_1
	v_cvt_pk_f32_fp8_e32 v[228:229], v197
	v_cvt_pk_f32_fp8_sdwa v[230:231], v197 src0_sel:WORD_1
	v_cvt_pk_f32_fp8_e32 v[232:233], v198
	v_cvt_pk_f32_fp8_sdwa v[234:235], v198 src0_sel:WORD_1
	v_cvt_pk_f32_fp8_e32 v[236:237], v199
	v_cvt_pk_f32_fp8_sdwa v[238:239], v199 src0_sel:WORD_1
	v_pk_fma_f32 v[16:17], v[224:225], s[18:19], v[16:17] op_sel_hi:[1,0,1]
	v_pk_fma_f32 v[18:19], v[226:227], s[18:19], v[18:19] op_sel_hi:[1,0,1]
	v_pk_fma_f32 v[20:21], v[228:229], s[18:19], v[20:21] op_sel_hi:[1,0,1]
	v_pk_fma_f32 v[22:23], v[230:231], s[18:19], v[22:23] op_sel_hi:[1,0,1]
	v_pk_fma_f32 v[24:25], v[232:233], s[18:19], v[24:25] op_sel_hi:[1,0,1]
	v_pk_fma_f32 v[26:27], v[234:235], s[18:19], v[26:27] op_sel_hi:[1,0,1]
	v_pk_fma_f32 v[28:29], v[236:237], s[18:19], v[28:29] op_sel_hi:[1,0,1]
	v_pk_fma_f32 v[30:31], v[238:239], s[18:19], v[30:31] op_sel_hi:[1,0,1]
	v_cvt_pk_f32_fp8_e32 v[224:225], v200
	v_cvt_pk_f32_fp8_sdwa v[226:227], v200 src0_sel:WORD_1
	v_cvt_pk_f32_fp8_e32 v[228:229], v201
	v_cvt_pk_f32_fp8_sdwa v[230:231], v201 src0_sel:WORD_1
	v_cvt_pk_f32_fp8_e32 v[232:233], v202
	v_cvt_pk_f32_fp8_sdwa v[234:235], v202 src0_sel:WORD_1
	v_cvt_pk_f32_fp8_e32 v[236:237], v203
	v_cvt_pk_f32_fp8_sdwa v[238:239], v203 src0_sel:WORD_1
	v_pk_fma_f32 v[16:17], v[224:225], s[20:21], v[16:17] op_sel_hi:[1,0,1]
	v_pk_fma_f32 v[18:19], v[226:227], s[20:21], v[18:19] op_sel_hi:[1,0,1]
	v_pk_fma_f32 v[20:21], v[228:229], s[20:21], v[20:21] op_sel_hi:[1,0,1]
	v_pk_fma_f32 v[22:23], v[230:231], s[20:21], v[22:23] op_sel_hi:[1,0,1]
	v_pk_fma_f32 v[24:25], v[232:233], s[20:21], v[24:25] op_sel_hi:[1,0,1]
	v_pk_fma_f32 v[26:27], v[234:235], s[20:21], v[26:27] op_sel_hi:[1,0,1]
	v_pk_fma_f32 v[28:29], v[236:237], s[20:21], v[28:29] op_sel_hi:[1,0,1]
	v_pk_fma_f32 v[30:31], v[238:239], s[20:21], v[30:31] op_sel_hi:[1,0,1]
	v_cvt_pk_f32_fp8_e32 v[224:225], v204
	v_cvt_pk_f32_fp8_sdwa v[226:227], v204 src0_sel:WORD_1
	v_cvt_pk_f32_fp8_e32 v[228:229], v205
	v_cvt_pk_f32_fp8_sdwa v[230:231], v205 src0_sel:WORD_1
	v_cvt_pk_f32_fp8_e32 v[232:233], v206
	v_cvt_pk_f32_fp8_sdwa v[234:235], v206 src0_sel:WORD_1
	v_cvt_pk_f32_fp8_e32 v[236:237], v207
	v_cvt_pk_f32_fp8_sdwa v[238:239], v207 src0_sel:WORD_1
	v_pk_fma_f32 v[16:17], v[224:225], s[22:23], v[16:17] op_sel_hi:[1,0,1]
	v_pk_fma_f32 v[18:19], v[226:227], s[22:23], v[18:19] op_sel_hi:[1,0,1]
	v_pk_fma_f32 v[20:21], v[228:229], s[22:23], v[20:21] op_sel_hi:[1,0,1]
	v_pk_fma_f32 v[22:23], v[230:231], s[22:23], v[22:23] op_sel_hi:[1,0,1]
	v_pk_fma_f32 v[24:25], v[232:233], s[22:23], v[24:25] op_sel_hi:[1,0,1]
	v_pk_fma_f32 v[26:27], v[234:235], s[22:23], v[26:27] op_sel_hi:[1,0,1]
	v_pk_fma_f32 v[28:29], v[236:237], s[22:23], v[28:29] op_sel_hi:[1,0,1]
	v_pk_fma_f32 v[30:31], v[238:239], s[22:23], v[30:31] op_sel_hi:[1,0,1]
	v_cvt_pk_f32_fp8_e32 v[224:225], v208
	v_cvt_pk_f32_fp8_sdwa v[226:227], v208 src0_sel:WORD_1
	v_cvt_pk_f32_fp8_e32 v[228:229], v209
	v_cvt_pk_f32_fp8_sdwa v[230:231], v209 src0_sel:WORD_1
	v_cvt_pk_f32_fp8_e32 v[232:233], v210
	v_cvt_pk_f32_fp8_sdwa v[234:235], v210 src0_sel:WORD_1
	v_cvt_pk_f32_fp8_e32 v[236:237], v211
	v_cvt_pk_f32_fp8_sdwa v[238:239], v211 src0_sel:WORD_1
	v_pk_fma_f32 v[16:17], v[224:225], s[24:25], v[16:17] op_sel_hi:[1,0,1]
	v_pk_fma_f32 v[18:19], v[226:227], s[24:25], v[18:19] op_sel_hi:[1,0,1]
	v_pk_fma_f32 v[20:21], v[228:229], s[24:25], v[20:21] op_sel_hi:[1,0,1]
	v_pk_fma_f32 v[22:23], v[230:231], s[24:25], v[22:23] op_sel_hi:[1,0,1]
	v_pk_fma_f32 v[24:25], v[232:233], s[24:25], v[24:25] op_sel_hi:[1,0,1]
	v_pk_fma_f32 v[26:27], v[234:235], s[24:25], v[26:27] op_sel_hi:[1,0,1]
	v_pk_fma_f32 v[28:29], v[236:237], s[24:25], v[28:29] op_sel_hi:[1,0,1]
	v_pk_fma_f32 v[30:31], v[238:239], s[24:25], v[30:31] op_sel_hi:[1,0,1]
	v_cvt_pk_f32_fp8_e32 v[224:225], v212
	v_cvt_pk_f32_fp8_sdwa v[226:227], v212 src0_sel:WORD_1
	v_cvt_pk_f32_fp8_e32 v[228:229], v213
	v_cvt_pk_f32_fp8_sdwa v[230:231], v213 src0_sel:WORD_1
	v_cvt_pk_f32_fp8_e32 v[232:233], v214
	v_cvt_pk_f32_fp8_sdwa v[234:235], v214 src0_sel:WORD_1
	v_cvt_pk_f32_fp8_e32 v[236:237], v215
	v_cvt_pk_f32_fp8_sdwa v[238:239], v215 src0_sel:WORD_1
	v_pk_fma_f32 v[16:17], v[224:225], s[26:27], v[16:17] op_sel_hi:[1,0,1]
	v_pk_fma_f32 v[18:19], v[226:227], s[26:27], v[18:19] op_sel_hi:[1,0,1]
	v_pk_fma_f32 v[20:21], v[228:229], s[26:27], v[20:21] op_sel_hi:[1,0,1]
	v_pk_fma_f32 v[22:23], v[230:231], s[26:27], v[22:23] op_sel_hi:[1,0,1]
	v_pk_fma_f32 v[24:25], v[232:233], s[26:27], v[24:25] op_sel_hi:[1,0,1]
	v_pk_fma_f32 v[26:27], v[234:235], s[26:27], v[26:27] op_sel_hi:[1,0,1]
	v_pk_fma_f32 v[28:29], v[236:237], s[26:27], v[28:29] op_sel_hi:[1,0,1]
	v_pk_fma_f32 v[30:31], v[238:239], s[26:27], v[30:31] op_sel_hi:[1,0,1]
	v_cvt_pk_f32_fp8_e32 v[224:225], v216
	v_cvt_pk_f32_fp8_sdwa v[226:227], v216 src0_sel:WORD_1
	v_cvt_pk_f32_fp8_e32 v[228:229], v217
	v_cvt_pk_f32_fp8_sdwa v[230:231], v217 src0_sel:WORD_1
	v_cvt_pk_f32_fp8_e32 v[232:233], v218
	v_cvt_pk_f32_fp8_sdwa v[234:235], v218 src0_sel:WORD_1
	v_cvt_pk_f32_fp8_e32 v[236:237], v219
	v_cvt_pk_f32_fp8_sdwa v[238:239], v219 src0_sel:WORD_1
	v_pk_fma_f32 v[16:17], v[224:225], s[28:29], v[16:17] op_sel_hi:[1,0,1]
	v_pk_fma_f32 v[18:19], v[226:227], s[28:29], v[18:19] op_sel_hi:[1,0,1]
	v_pk_fma_f32 v[20:21], v[228:229], s[28:29], v[20:21] op_sel_hi:[1,0,1]
	v_pk_fma_f32 v[22:23], v[230:231], s[28:29], v[22:23] op_sel_hi:[1,0,1]
	v_pk_fma_f32 v[24:25], v[232:233], s[28:29], v[24:25] op_sel_hi:[1,0,1]
	v_pk_fma_f32 v[26:27], v[234:235], s[28:29], v[26:27] op_sel_hi:[1,0,1]
	v_pk_fma_f32 v[28:29], v[236:237], s[28:29], v[28:29] op_sel_hi:[1,0,1]
	v_pk_fma_f32 v[30:31], v[238:239], s[28:29], v[30:31] op_sel_hi:[1,0,1]
	v_cvt_pk_f32_fp8_e32 v[224:225], v220
	v_cvt_pk_f32_fp8_sdwa v[226:227], v220 src0_sel:WORD_1
	v_cvt_pk_f32_fp8_e32 v[228:229], v221
	v_cvt_pk_f32_fp8_sdwa v[230:231], v221 src0_sel:WORD_1
	v_cvt_pk_f32_fp8_e32 v[232:233], v222
	v_cvt_pk_f32_fp8_sdwa v[234:235], v222 src0_sel:WORD_1
	v_cvt_pk_f32_fp8_e32 v[236:237], v223
	v_cvt_pk_f32_fp8_sdwa v[238:239], v223 src0_sel:WORD_1
	v_pk_fma_f32 v[16:17], v[224:225], s[30:31], v[16:17] op_sel_hi:[1,0,1]
	v_pk_fma_f32 v[18:19], v[226:227], s[30:31], v[18:19] op_sel_hi:[1,0,1]
	v_pk_fma_f32 v[20:21], v[228:229], s[30:31], v[20:21] op_sel_hi:[1,0,1]
	v_pk_fma_f32 v[22:23], v[230:231], s[30:31], v[22:23] op_sel_hi:[1,0,1]
	v_pk_fma_f32 v[24:25], v[232:233], s[30:31], v[24:25] op_sel_hi:[1,0,1]
	v_pk_fma_f32 v[26:27], v[234:235], s[30:31], v[26:27] op_sel_hi:[1,0,1]
	v_pk_fma_f32 v[28:29], v[236:237], s[30:31], v[28:29] op_sel_hi:[1,0,1]
	v_pk_fma_f32 v[30:31], v[238:239], s[30:31], v[30:31] op_sel_hi:[1,0,1]
	v_readlane_b32 s16, v138, s72
	v_readlane_b32 s18, v138, s73
	v_readlane_b32 s20, v138, s74
	v_readlane_b32 s22, v138, s75
	v_readlane_b32 s24, v138, s76
	v_readlane_b32 s26, v138, s77
	v_readlane_b32 s28, v138, s78
	v_readlane_b32 s30, v138, s79
	v_readlane_b32 s48, v133, s72
	v_readlane_b32 s49, v133, s73
	v_readlane_b32 s50, v133, s74
	v_readlane_b32 s51, v133, s75
	v_readlane_b32 s52, v133, s76
	v_readlane_b32 s53, v133, s77
	v_readlane_b32 s54, v133, s78
	v_readlane_b32 s55, v133, s79
	s_add_u32 s32, s0, s48
	s_addc_u32 s33, s1, 0
	s_add_u32 s34, s0, s49
	s_addc_u32 s35, s1, 0
	s_add_u32 s36, s0, s50
	s_addc_u32 s37, s1, 0
	s_add_u32 s38, s0, s51
	s_addc_u32 s39, s1, 0
	s_add_u32 s40, s0, s52
	s_addc_u32 s41, s1, 0
	s_add_u32 s42, s0, s53
	s_addc_u32 s43, s1, 0
	s_add_u32 s44, s0, s54
	s_addc_u32 s45, s1, 0
	s_add_u32 s46, s0, s55
	s_addc_u32 s47, s1, 0
	global_load_dwordx4 v[192:195], v240, s[32:33]
	global_load_dwordx4 v[196:199], v240, s[34:35]
	global_load_dwordx4 v[200:203], v240, s[36:37]
	global_load_dwordx4 v[204:207], v240, s[38:39]
	global_load_dwordx4 v[208:211], v240, s[40:41]
	global_load_dwordx4 v[212:215], v240, s[42:43]
	global_load_dwordx4 v[216:219], v240, s[44:45]
	global_load_dwordx4 v[220:223], v240, s[46:47]
	s_waitcnt vmcnt(24)
	v_cvt_pk_f32_fp8_e32 v[224:225], v64
	v_cvt_pk_f32_fp8_sdwa v[226:227], v64 src0_sel:WORD_1
	v_cvt_pk_f32_fp8_e32 v[228:229], v65
	v_cvt_pk_f32_fp8_sdwa v[230:231], v65 src0_sel:WORD_1
	v_cvt_pk_f32_fp8_e32 v[232:233], v66
	v_cvt_pk_f32_fp8_sdwa v[234:235], v66 src0_sel:WORD_1
	v_cvt_pk_f32_fp8_e32 v[236:237], v67
	v_cvt_pk_f32_fp8_sdwa v[238:239], v67 src0_sel:WORD_1
	v_pk_fma_f32 v[32:33], v[224:225], s[16:17], v[32:33] op_sel_hi:[1,0,1]
	v_pk_fma_f32 v[34:35], v[226:227], s[16:17], v[34:35] op_sel_hi:[1,0,1]
	v_pk_fma_f32 v[36:37], v[228:229], s[16:17], v[36:37] op_sel_hi:[1,0,1]
	v_pk_fma_f32 v[38:39], v[230:231], s[16:17], v[38:39] op_sel_hi:[1,0,1]
	v_pk_fma_f32 v[40:41], v[232:233], s[16:17], v[40:41] op_sel_hi:[1,0,1]
	v_pk_fma_f32 v[42:43], v[234:235], s[16:17], v[42:43] op_sel_hi:[1,0,1]
	v_pk_fma_f32 v[44:45], v[236:237], s[16:17], v[44:45] op_sel_hi:[1,0,1]
	v_pk_fma_f32 v[46:47], v[238:239], s[16:17], v[46:47] op_sel_hi:[1,0,1]
	v_cvt_pk_f32_fp8_e32 v[224:225], v68
	v_cvt_pk_f32_fp8_sdwa v[226:227], v68 src0_sel:WORD_1
	v_cvt_pk_f32_fp8_e32 v[228:229], v69
	v_cvt_pk_f32_fp8_sdwa v[230:231], v69 src0_sel:WORD_1
	v_cvt_pk_f32_fp8_e32 v[232:233], v70
	v_cvt_pk_f32_fp8_sdwa v[234:235], v70 src0_sel:WORD_1
	v_cvt_pk_f32_fp8_e32 v[236:237], v71
	v_cvt_pk_f32_fp8_sdwa v[238:239], v71 src0_sel:WORD_1
	v_pk_fma_f32 v[32:33], v[224:225], s[18:19], v[32:33] op_sel_hi:[1,0,1]
	v_pk_fma_f32 v[34:35], v[226:227], s[18:19], v[34:35] op_sel_hi:[1,0,1]
	v_pk_fma_f32 v[36:37], v[228:229], s[18:19], v[36:37] op_sel_hi:[1,0,1]
	v_pk_fma_f32 v[38:39], v[230:231], s[18:19], v[38:39] op_sel_hi:[1,0,1]
	v_pk_fma_f32 v[40:41], v[232:233], s[18:19], v[40:41] op_sel_hi:[1,0,1]
	v_pk_fma_f32 v[42:43], v[234:235], s[18:19], v[42:43] op_sel_hi:[1,0,1]
	v_pk_fma_f32 v[44:45], v[236:237], s[18:19], v[44:45] op_sel_hi:[1,0,1]
	v_pk_fma_f32 v[46:47], v[238:239], s[18:19], v[46:47] op_sel_hi:[1,0,1]
	v_cvt_pk_f32_fp8_e32 v[224:225], v72
	v_cvt_pk_f32_fp8_sdwa v[226:227], v72 src0_sel:WORD_1
	v_cvt_pk_f32_fp8_e32 v[228:229], v73
	v_cvt_pk_f32_fp8_sdwa v[230:231], v73 src0_sel:WORD_1
	v_cvt_pk_f32_fp8_e32 v[232:233], v74
	v_cvt_pk_f32_fp8_sdwa v[234:235], v74 src0_sel:WORD_1
	v_cvt_pk_f32_fp8_e32 v[236:237], v75
	v_cvt_pk_f32_fp8_sdwa v[238:239], v75 src0_sel:WORD_1
	v_pk_fma_f32 v[32:33], v[224:225], s[20:21], v[32:33] op_sel_hi:[1,0,1]
	v_pk_fma_f32 v[34:35], v[226:227], s[20:21], v[34:35] op_sel_hi:[1,0,1]
	v_pk_fma_f32 v[36:37], v[228:229], s[20:21], v[36:37] op_sel_hi:[1,0,1]
	v_pk_fma_f32 v[38:39], v[230:231], s[20:21], v[38:39] op_sel_hi:[1,0,1]
	v_pk_fma_f32 v[40:41], v[232:233], s[20:21], v[40:41] op_sel_hi:[1,0,1]
	v_pk_fma_f32 v[42:43], v[234:235], s[20:21], v[42:43] op_sel_hi:[1,0,1]
	v_pk_fma_f32 v[44:45], v[236:237], s[20:21], v[44:45] op_sel_hi:[1,0,1]
	v_pk_fma_f32 v[46:47], v[238:239], s[20:21], v[46:47] op_sel_hi:[1,0,1]
	v_cvt_pk_f32_fp8_e32 v[224:225], v76
	v_cvt_pk_f32_fp8_sdwa v[226:227], v76 src0_sel:WORD_1
	v_cvt_pk_f32_fp8_e32 v[228:229], v77
	v_cvt_pk_f32_fp8_sdwa v[230:231], v77 src0_sel:WORD_1
	v_cvt_pk_f32_fp8_e32 v[232:233], v78
	v_cvt_pk_f32_fp8_sdwa v[234:235], v78 src0_sel:WORD_1
	v_cvt_pk_f32_fp8_e32 v[236:237], v79
	v_cvt_pk_f32_fp8_sdwa v[238:239], v79 src0_sel:WORD_1
	v_pk_fma_f32 v[32:33], v[224:225], s[22:23], v[32:33] op_sel_hi:[1,0,1]
	v_pk_fma_f32 v[34:35], v[226:227], s[22:23], v[34:35] op_sel_hi:[1,0,1]
	v_pk_fma_f32 v[36:37], v[228:229], s[22:23], v[36:37] op_sel_hi:[1,0,1]
	v_pk_fma_f32 v[38:39], v[230:231], s[22:23], v[38:39] op_sel_hi:[1,0,1]
	v_pk_fma_f32 v[40:41], v[232:233], s[22:23], v[40:41] op_sel_hi:[1,0,1]
	v_pk_fma_f32 v[42:43], v[234:235], s[22:23], v[42:43] op_sel_hi:[1,0,1]
	v_pk_fma_f32 v[44:45], v[236:237], s[22:23], v[44:45] op_sel_hi:[1,0,1]
	v_pk_fma_f32 v[46:47], v[238:239], s[22:23], v[46:47] op_sel_hi:[1,0,1]
	v_cvt_pk_f32_fp8_e32 v[224:225], v80
	v_cvt_pk_f32_fp8_sdwa v[226:227], v80 src0_sel:WORD_1
	v_cvt_pk_f32_fp8_e32 v[228:229], v81
	v_cvt_pk_f32_fp8_sdwa v[230:231], v81 src0_sel:WORD_1
	v_cvt_pk_f32_fp8_e32 v[232:233], v82
	v_cvt_pk_f32_fp8_sdwa v[234:235], v82 src0_sel:WORD_1
	v_cvt_pk_f32_fp8_e32 v[236:237], v83
	v_cvt_pk_f32_fp8_sdwa v[238:239], v83 src0_sel:WORD_1
	v_pk_fma_f32 v[32:33], v[224:225], s[24:25], v[32:33] op_sel_hi:[1,0,1]
	v_pk_fma_f32 v[34:35], v[226:227], s[24:25], v[34:35] op_sel_hi:[1,0,1]
	v_pk_fma_f32 v[36:37], v[228:229], s[24:25], v[36:37] op_sel_hi:[1,0,1]
	v_pk_fma_f32 v[38:39], v[230:231], s[24:25], v[38:39] op_sel_hi:[1,0,1]
	v_pk_fma_f32 v[40:41], v[232:233], s[24:25], v[40:41] op_sel_hi:[1,0,1]
	v_pk_fma_f32 v[42:43], v[234:235], s[24:25], v[42:43] op_sel_hi:[1,0,1]
	v_pk_fma_f32 v[44:45], v[236:237], s[24:25], v[44:45] op_sel_hi:[1,0,1]
	v_pk_fma_f32 v[46:47], v[238:239], s[24:25], v[46:47] op_sel_hi:[1,0,1]
	v_cvt_pk_f32_fp8_e32 v[224:225], v84
	v_cvt_pk_f32_fp8_sdwa v[226:227], v84 src0_sel:WORD_1
	v_cvt_pk_f32_fp8_e32 v[228:229], v85
	v_cvt_pk_f32_fp8_sdwa v[230:231], v85 src0_sel:WORD_1
	v_cvt_pk_f32_fp8_e32 v[232:233], v86
	v_cvt_pk_f32_fp8_sdwa v[234:235], v86 src0_sel:WORD_1
	v_cvt_pk_f32_fp8_e32 v[236:237], v87
	v_cvt_pk_f32_fp8_sdwa v[238:239], v87 src0_sel:WORD_1
	v_pk_fma_f32 v[32:33], v[224:225], s[26:27], v[32:33] op_sel_hi:[1,0,1]
	v_pk_fma_f32 v[34:35], v[226:227], s[26:27], v[34:35] op_sel_hi:[1,0,1]
	v_pk_fma_f32 v[36:37], v[228:229], s[26:27], v[36:37] op_sel_hi:[1,0,1]
	v_pk_fma_f32 v[38:39], v[230:231], s[26:27], v[38:39] op_sel_hi:[1,0,1]
	v_pk_fma_f32 v[40:41], v[232:233], s[26:27], v[40:41] op_sel_hi:[1,0,1]
	v_pk_fma_f32 v[42:43], v[234:235], s[26:27], v[42:43] op_sel_hi:[1,0,1]
	v_pk_fma_f32 v[44:45], v[236:237], s[26:27], v[44:45] op_sel_hi:[1,0,1]
	v_pk_fma_f32 v[46:47], v[238:239], s[26:27], v[46:47] op_sel_hi:[1,0,1]
	v_cvt_pk_f32_fp8_e32 v[224:225], v88
	v_cvt_pk_f32_fp8_sdwa v[226:227], v88 src0_sel:WORD_1
	v_cvt_pk_f32_fp8_e32 v[228:229], v89
	v_cvt_pk_f32_fp8_sdwa v[230:231], v89 src0_sel:WORD_1
	v_cvt_pk_f32_fp8_e32 v[232:233], v90
	v_cvt_pk_f32_fp8_sdwa v[234:235], v90 src0_sel:WORD_1
	v_cvt_pk_f32_fp8_e32 v[236:237], v91
	v_cvt_pk_f32_fp8_sdwa v[238:239], v91 src0_sel:WORD_1
	v_pk_fma_f32 v[32:33], v[224:225], s[28:29], v[32:33] op_sel_hi:[1,0,1]
	v_pk_fma_f32 v[34:35], v[226:227], s[28:29], v[34:35] op_sel_hi:[1,0,1]
	v_pk_fma_f32 v[36:37], v[228:229], s[28:29], v[36:37] op_sel_hi:[1,0,1]
	v_pk_fma_f32 v[38:39], v[230:231], s[28:29], v[38:39] op_sel_hi:[1,0,1]
	v_pk_fma_f32 v[40:41], v[232:233], s[28:29], v[40:41] op_sel_hi:[1,0,1]
	v_pk_fma_f32 v[42:43], v[234:235], s[28:29], v[42:43] op_sel_hi:[1,0,1]
	v_pk_fma_f32 v[44:45], v[236:237], s[28:29], v[44:45] op_sel_hi:[1,0,1]
	v_pk_fma_f32 v[46:47], v[238:239], s[28:29], v[46:47] op_sel_hi:[1,0,1]
	v_cvt_pk_f32_fp8_e32 v[224:225], v92
	v_cvt_pk_f32_fp8_sdwa v[226:227], v92 src0_sel:WORD_1
	v_cvt_pk_f32_fp8_e32 v[228:229], v93
	v_cvt_pk_f32_fp8_sdwa v[230:231], v93 src0_sel:WORD_1
	v_cvt_pk_f32_fp8_e32 v[232:233], v94
	v_cvt_pk_f32_fp8_sdwa v[234:235], v94 src0_sel:WORD_1
	v_cvt_pk_f32_fp8_e32 v[236:237], v95
	v_cvt_pk_f32_fp8_sdwa v[238:239], v95 src0_sel:WORD_1
	v_pk_fma_f32 v[32:33], v[224:225], s[30:31], v[32:33] op_sel_hi:[1,0,1]
	v_pk_fma_f32 v[34:35], v[226:227], s[30:31], v[34:35] op_sel_hi:[1,0,1]
	v_pk_fma_f32 v[36:37], v[228:229], s[30:31], v[36:37] op_sel_hi:[1,0,1]
	v_pk_fma_f32 v[38:39], v[230:231], s[30:31], v[38:39] op_sel_hi:[1,0,1]
	v_pk_fma_f32 v[40:41], v[232:233], s[30:31], v[40:41] op_sel_hi:[1,0,1]
	v_pk_fma_f32 v[42:43], v[234:235], s[30:31], v[42:43] op_sel_hi:[1,0,1]
	v_pk_fma_f32 v[44:45], v[236:237], s[30:31], v[44:45] op_sel_hi:[1,0,1]
	v_pk_fma_f32 v[46:47], v[238:239], s[30:31], v[46:47] op_sel_hi:[1,0,1]
	v_readlane_b32 s16, v142, s72
	v_readlane_b32 s18, v142, s73
	v_readlane_b32 s20, v142, s74
	v_readlane_b32 s22, v142, s75
	v_readlane_b32 s24, v142, s76
	v_readlane_b32 s26, v142, s77
	v_readlane_b32 s28, v142, s78
	v_readlane_b32 s30, v142, s79
	v_readlane_b32 s48, v137, s72
	v_readlane_b32 s49, v137, s73
	v_readlane_b32 s50, v137, s74
	v_readlane_b32 s51, v137, s75
	v_readlane_b32 s52, v137, s76
	v_readlane_b32 s53, v137, s77
	v_readlane_b32 s54, v137, s78
	v_readlane_b32 s55, v137, s79
	s_add_u32 s32, s0, s48
	s_addc_u32 s33, s1, 0
	s_add_u32 s34, s0, s49
	s_addc_u32 s35, s1, 0
	s_add_u32 s36, s0, s50
	s_addc_u32 s37, s1, 0
	s_add_u32 s38, s0, s51
	s_addc_u32 s39, s1, 0
	s_add_u32 s40, s0, s52
	s_addc_u32 s41, s1, 0
	s_add_u32 s42, s0, s53
	s_addc_u32 s43, s1, 0
	s_add_u32 s44, s0, s54
	s_addc_u32 s45, s1, 0
	s_add_u32 s46, s0, s55
	s_addc_u32 s47, s1, 0
	global_load_dwordx4 v[64:67], v240, s[32:33]
	global_load_dwordx4 v[68:71], v240, s[34:35]
	global_load_dwordx4 v[72:75], v240, s[36:37]
	global_load_dwordx4 v[76:79], v240, s[38:39]
	global_load_dwordx4 v[80:83], v240, s[40:41]
	global_load_dwordx4 v[84:87], v240, s[42:43]
	global_load_dwordx4 v[88:91], v240, s[44:45]
	global_load_dwordx4 v[92:95], v240, s[46:47]
	s_waitcnt vmcnt(24)
	v_cvt_pk_f32_fp8_e32 v[224:225], v96
	v_cvt_pk_f32_fp8_sdwa v[226:227], v96 src0_sel:WORD_1
	v_cvt_pk_f32_fp8_e32 v[228:229], v97
	v_cvt_pk_f32_fp8_sdwa v[230:231], v97 src0_sel:WORD_1
	v_cvt_pk_f32_fp8_e32 v[232:233], v98
	v_cvt_pk_f32_fp8_sdwa v[234:235], v98 src0_sel:WORD_1
	v_cvt_pk_f32_fp8_e32 v[236:237], v99
	v_cvt_pk_f32_fp8_sdwa v[238:239], v99 src0_sel:WORD_1
	v_pk_fma_f32 v[48:49], v[224:225], s[16:17], v[48:49] op_sel_hi:[1,0,1]
	v_pk_fma_f32 v[50:51], v[226:227], s[16:17], v[50:51] op_sel_hi:[1,0,1]
	v_pk_fma_f32 v[52:53], v[228:229], s[16:17], v[52:53] op_sel_hi:[1,0,1]
	v_pk_fma_f32 v[54:55], v[230:231], s[16:17], v[54:55] op_sel_hi:[1,0,1]
	v_pk_fma_f32 v[56:57], v[232:233], s[16:17], v[56:57] op_sel_hi:[1,0,1]
	v_pk_fma_f32 v[58:59], v[234:235], s[16:17], v[58:59] op_sel_hi:[1,0,1]
	v_pk_fma_f32 v[60:61], v[236:237], s[16:17], v[60:61] op_sel_hi:[1,0,1]
	v_pk_fma_f32 v[62:63], v[238:239], s[16:17], v[62:63] op_sel_hi:[1,0,1]
	v_cvt_pk_f32_fp8_e32 v[224:225], v100
	v_cvt_pk_f32_fp8_sdwa v[226:227], v100 src0_sel:WORD_1
	v_cvt_pk_f32_fp8_e32 v[228:229], v101
	v_cvt_pk_f32_fp8_sdwa v[230:231], v101 src0_sel:WORD_1
	v_cvt_pk_f32_fp8_e32 v[232:233], v102
	v_cvt_pk_f32_fp8_sdwa v[234:235], v102 src0_sel:WORD_1
	v_cvt_pk_f32_fp8_e32 v[236:237], v103
	v_cvt_pk_f32_fp8_sdwa v[238:239], v103 src0_sel:WORD_1
	v_pk_fma_f32 v[48:49], v[224:225], s[18:19], v[48:49] op_sel_hi:[1,0,1]
	v_pk_fma_f32 v[50:51], v[226:227], s[18:19], v[50:51] op_sel_hi:[1,0,1]
	v_pk_fma_f32 v[52:53], v[228:229], s[18:19], v[52:53] op_sel_hi:[1,0,1]
	v_pk_fma_f32 v[54:55], v[230:231], s[18:19], v[54:55] op_sel_hi:[1,0,1]
	v_pk_fma_f32 v[56:57], v[232:233], s[18:19], v[56:57] op_sel_hi:[1,0,1]
	v_pk_fma_f32 v[58:59], v[234:235], s[18:19], v[58:59] op_sel_hi:[1,0,1]
	v_pk_fma_f32 v[60:61], v[236:237], s[18:19], v[60:61] op_sel_hi:[1,0,1]
	v_pk_fma_f32 v[62:63], v[238:239], s[18:19], v[62:63] op_sel_hi:[1,0,1]
	v_cvt_pk_f32_fp8_e32 v[224:225], v104
	v_cvt_pk_f32_fp8_sdwa v[226:227], v104 src0_sel:WORD_1
	v_cvt_pk_f32_fp8_e32 v[228:229], v105
	v_cvt_pk_f32_fp8_sdwa v[230:231], v105 src0_sel:WORD_1
	v_cvt_pk_f32_fp8_e32 v[232:233], v106
	v_cvt_pk_f32_fp8_sdwa v[234:235], v106 src0_sel:WORD_1
	v_cvt_pk_f32_fp8_e32 v[236:237], v107
	v_cvt_pk_f32_fp8_sdwa v[238:239], v107 src0_sel:WORD_1
	v_pk_fma_f32 v[48:49], v[224:225], s[20:21], v[48:49] op_sel_hi:[1,0,1]
	v_pk_fma_f32 v[50:51], v[226:227], s[20:21], v[50:51] op_sel_hi:[1,0,1]
	v_pk_fma_f32 v[52:53], v[228:229], s[20:21], v[52:53] op_sel_hi:[1,0,1]
	v_pk_fma_f32 v[54:55], v[230:231], s[20:21], v[54:55] op_sel_hi:[1,0,1]
	v_pk_fma_f32 v[56:57], v[232:233], s[20:21], v[56:57] op_sel_hi:[1,0,1]
	v_pk_fma_f32 v[58:59], v[234:235], s[20:21], v[58:59] op_sel_hi:[1,0,1]
	v_pk_fma_f32 v[60:61], v[236:237], s[20:21], v[60:61] op_sel_hi:[1,0,1]
	v_pk_fma_f32 v[62:63], v[238:239], s[20:21], v[62:63] op_sel_hi:[1,0,1]
	v_cvt_pk_f32_fp8_e32 v[224:225], v108
	v_cvt_pk_f32_fp8_sdwa v[226:227], v108 src0_sel:WORD_1
	v_cvt_pk_f32_fp8_e32 v[228:229], v109
	v_cvt_pk_f32_fp8_sdwa v[230:231], v109 src0_sel:WORD_1
	v_cvt_pk_f32_fp8_e32 v[232:233], v110
	v_cvt_pk_f32_fp8_sdwa v[234:235], v110 src0_sel:WORD_1
	v_cvt_pk_f32_fp8_e32 v[236:237], v111
	v_cvt_pk_f32_fp8_sdwa v[238:239], v111 src0_sel:WORD_1
	v_pk_fma_f32 v[48:49], v[224:225], s[22:23], v[48:49] op_sel_hi:[1,0,1]
	v_pk_fma_f32 v[50:51], v[226:227], s[22:23], v[50:51] op_sel_hi:[1,0,1]
	v_pk_fma_f32 v[52:53], v[228:229], s[22:23], v[52:53] op_sel_hi:[1,0,1]
	v_pk_fma_f32 v[54:55], v[230:231], s[22:23], v[54:55] op_sel_hi:[1,0,1]
	v_pk_fma_f32 v[56:57], v[232:233], s[22:23], v[56:57] op_sel_hi:[1,0,1]
	v_pk_fma_f32 v[58:59], v[234:235], s[22:23], v[58:59] op_sel_hi:[1,0,1]
	v_pk_fma_f32 v[60:61], v[236:237], s[22:23], v[60:61] op_sel_hi:[1,0,1]
	v_pk_fma_f32 v[62:63], v[238:239], s[22:23], v[62:63] op_sel_hi:[1,0,1]
	v_cvt_pk_f32_fp8_e32 v[224:225], v112
	v_cvt_pk_f32_fp8_sdwa v[226:227], v112 src0_sel:WORD_1
	v_cvt_pk_f32_fp8_e32 v[228:229], v113
	v_cvt_pk_f32_fp8_sdwa v[230:231], v113 src0_sel:WORD_1
	v_cvt_pk_f32_fp8_e32 v[232:233], v114
	v_cvt_pk_f32_fp8_sdwa v[234:235], v114 src0_sel:WORD_1
	v_cvt_pk_f32_fp8_e32 v[236:237], v115
	v_cvt_pk_f32_fp8_sdwa v[238:239], v115 src0_sel:WORD_1
	v_pk_fma_f32 v[48:49], v[224:225], s[24:25], v[48:49] op_sel_hi:[1,0,1]
	v_pk_fma_f32 v[50:51], v[226:227], s[24:25], v[50:51] op_sel_hi:[1,0,1]
	v_pk_fma_f32 v[52:53], v[228:229], s[24:25], v[52:53] op_sel_hi:[1,0,1]
	v_pk_fma_f32 v[54:55], v[230:231], s[24:25], v[54:55] op_sel_hi:[1,0,1]
	v_pk_fma_f32 v[56:57], v[232:233], s[24:25], v[56:57] op_sel_hi:[1,0,1]
	v_pk_fma_f32 v[58:59], v[234:235], s[24:25], v[58:59] op_sel_hi:[1,0,1]
	v_pk_fma_f32 v[60:61], v[236:237], s[24:25], v[60:61] op_sel_hi:[1,0,1]
	v_pk_fma_f32 v[62:63], v[238:239], s[24:25], v[62:63] op_sel_hi:[1,0,1]
	v_cvt_pk_f32_fp8_e32 v[224:225], v116
	v_cvt_pk_f32_fp8_sdwa v[226:227], v116 src0_sel:WORD_1
	v_cvt_pk_f32_fp8_e32 v[228:229], v117
	v_cvt_pk_f32_fp8_sdwa v[230:231], v117 src0_sel:WORD_1
	v_cvt_pk_f32_fp8_e32 v[232:233], v118
	v_cvt_pk_f32_fp8_sdwa v[234:235], v118 src0_sel:WORD_1
	v_cvt_pk_f32_fp8_e32 v[236:237], v119
	v_cvt_pk_f32_fp8_sdwa v[238:239], v119 src0_sel:WORD_1
	v_pk_fma_f32 v[48:49], v[224:225], s[26:27], v[48:49] op_sel_hi:[1,0,1]
	v_pk_fma_f32 v[50:51], v[226:227], s[26:27], v[50:51] op_sel_hi:[1,0,1]
	v_pk_fma_f32 v[52:53], v[228:229], s[26:27], v[52:53] op_sel_hi:[1,0,1]
	v_pk_fma_f32 v[54:55], v[230:231], s[26:27], v[54:55] op_sel_hi:[1,0,1]
	v_pk_fma_f32 v[56:57], v[232:233], s[26:27], v[56:57] op_sel_hi:[1,0,1]
	v_pk_fma_f32 v[58:59], v[234:235], s[26:27], v[58:59] op_sel_hi:[1,0,1]
	v_pk_fma_f32 v[60:61], v[236:237], s[26:27], v[60:61] op_sel_hi:[1,0,1]
	v_pk_fma_f32 v[62:63], v[238:239], s[26:27], v[62:63] op_sel_hi:[1,0,1]
	v_cvt_pk_f32_fp8_e32 v[224:225], v120
	v_cvt_pk_f32_fp8_sdwa v[226:227], v120 src0_sel:WORD_1
	v_cvt_pk_f32_fp8_e32 v[228:229], v121
	v_cvt_pk_f32_fp8_sdwa v[230:231], v121 src0_sel:WORD_1
	v_cvt_pk_f32_fp8_e32 v[232:233], v122
	v_cvt_pk_f32_fp8_sdwa v[234:235], v122 src0_sel:WORD_1
	v_cvt_pk_f32_fp8_e32 v[236:237], v123
	v_cvt_pk_f32_fp8_sdwa v[238:239], v123 src0_sel:WORD_1
	v_pk_fma_f32 v[48:49], v[224:225], s[28:29], v[48:49] op_sel_hi:[1,0,1]
	v_pk_fma_f32 v[50:51], v[226:227], s[28:29], v[50:51] op_sel_hi:[1,0,1]
	v_pk_fma_f32 v[52:53], v[228:229], s[28:29], v[52:53] op_sel_hi:[1,0,1]
	v_pk_fma_f32 v[54:55], v[230:231], s[28:29], v[54:55] op_sel_hi:[1,0,1]
	v_pk_fma_f32 v[56:57], v[232:233], s[28:29], v[56:57] op_sel_hi:[1,0,1]
	v_pk_fma_f32 v[58:59], v[234:235], s[28:29], v[58:59] op_sel_hi:[1,0,1]
	v_pk_fma_f32 v[60:61], v[236:237], s[28:29], v[60:61] op_sel_hi:[1,0,1]
	v_pk_fma_f32 v[62:63], v[238:239], s[28:29], v[62:63] op_sel_hi:[1,0,1]
	v_cvt_pk_f32_fp8_e32 v[224:225], v124
	v_cvt_pk_f32_fp8_sdwa v[226:227], v124 src0_sel:WORD_1
	v_cvt_pk_f32_fp8_e32 v[228:229], v125
	v_cvt_pk_f32_fp8_sdwa v[230:231], v125 src0_sel:WORD_1
	v_cvt_pk_f32_fp8_e32 v[232:233], v126
	v_cvt_pk_f32_fp8_sdwa v[234:235], v126 src0_sel:WORD_1
	v_cvt_pk_f32_fp8_e32 v[236:237], v127
	v_cvt_pk_f32_fp8_sdwa v[238:239], v127 src0_sel:WORD_1
	v_pk_fma_f32 v[48:49], v[224:225], s[30:31], v[48:49] op_sel_hi:[1,0,1]
	v_pk_fma_f32 v[50:51], v[226:227], s[30:31], v[50:51] op_sel_hi:[1,0,1]
	v_pk_fma_f32 v[52:53], v[228:229], s[30:31], v[52:53] op_sel_hi:[1,0,1]
	v_pk_fma_f32 v[54:55], v[230:231], s[30:31], v[54:55] op_sel_hi:[1,0,1]
	v_pk_fma_f32 v[56:57], v[232:233], s[30:31], v[56:57] op_sel_hi:[1,0,1]
	v_pk_fma_f32 v[58:59], v[234:235], s[30:31], v[58:59] op_sel_hi:[1,0,1]
	v_pk_fma_f32 v[60:61], v[236:237], s[30:31], v[60:61] op_sel_hi:[1,0,1]
	v_pk_fma_f32 v[62:63], v[238:239], s[30:31], v[62:63] op_sel_hi:[1,0,1]
	v_readlane_b32 s16, v131, s72
	v_readlane_b32 s18, v131, s73
	v_readlane_b32 s20, v131, s74
	v_readlane_b32 s22, v131, s75
	v_readlane_b32 s24, v131, s76
	v_readlane_b32 s26, v131, s77
	v_readlane_b32 s28, v131, s78
	v_readlane_b32 s30, v131, s79
	v_readlane_b32 s48, v141, s72
	v_readlane_b32 s49, v141, s73
	v_readlane_b32 s50, v141, s74
	v_readlane_b32 s51, v141, s75
	v_readlane_b32 s52, v141, s76
	v_readlane_b32 s53, v141, s77
	v_readlane_b32 s54, v141, s78
	v_readlane_b32 s55, v141, s79
	s_add_u32 s32, s0, s48
	s_addc_u32 s33, s1, 0
	s_add_u32 s34, s0, s49
	s_addc_u32 s35, s1, 0
	s_add_u32 s36, s0, s50
	s_addc_u32 s37, s1, 0
	s_add_u32 s38, s0, s51
	s_addc_u32 s39, s1, 0
	s_add_u32 s40, s0, s52
	s_addc_u32 s41, s1, 0
	s_add_u32 s42, s0, s53
	s_addc_u32 s43, s1, 0
	s_add_u32 s44, s0, s54
	s_addc_u32 s45, s1, 0
	s_add_u32 s46, s0, s55
	s_addc_u32 s47, s1, 0
	global_load_dwordx4 v[96:99], v240, s[32:33]
	global_load_dwordx4 v[100:103], v240, s[34:35]
	global_load_dwordx4 v[104:107], v240, s[36:37]
	global_load_dwordx4 v[108:111], v240, s[38:39]
	global_load_dwordx4 v[112:115], v240, s[40:41]
	global_load_dwordx4 v[116:119], v240, s[42:43]
	global_load_dwordx4 v[120:123], v240, s[44:45]
	global_load_dwordx4 v[124:127], v240, s[46:47]
	s_waitcnt vmcnt(24)
	v_cvt_pk_f32_fp8_e32 v[224:225], v160
	v_cvt_pk_f32_fp8_sdwa v[226:227], v160 src0_sel:WORD_1
	v_cvt_pk_f32_fp8_e32 v[228:229], v161
	v_cvt_pk_f32_fp8_sdwa v[230:231], v161 src0_sel:WORD_1
	v_cvt_pk_f32_fp8_e32 v[232:233], v162
	v_cvt_pk_f32_fp8_sdwa v[234:235], v162 src0_sel:WORD_1
	v_cvt_pk_f32_fp8_e32 v[236:237], v163
	v_cvt_pk_f32_fp8_sdwa v[238:239], v163 src0_sel:WORD_1
	v_pk_fma_f32 v[0:1], v[224:225], s[16:17], v[0:1] op_sel_hi:[1,0,1]
	v_pk_fma_f32 v[2:3], v[226:227], s[16:17], v[2:3] op_sel_hi:[1,0,1]
	v_pk_fma_f32 v[4:5], v[228:229], s[16:17], v[4:5] op_sel_hi:[1,0,1]
	v_pk_fma_f32 v[6:7], v[230:231], s[16:17], v[6:7] op_sel_hi:[1,0,1]
	v_pk_fma_f32 v[8:9], v[232:233], s[16:17], v[8:9] op_sel_hi:[1,0,1]
	v_pk_fma_f32 v[10:11], v[234:235], s[16:17], v[10:11] op_sel_hi:[1,0,1]
	v_pk_fma_f32 v[12:13], v[236:237], s[16:17], v[12:13] op_sel_hi:[1,0,1]
	v_pk_fma_f32 v[14:15], v[238:239], s[16:17], v[14:15] op_sel_hi:[1,0,1]
	v_cvt_pk_f32_fp8_e32 v[224:225], v164
	v_cvt_pk_f32_fp8_sdwa v[226:227], v164 src0_sel:WORD_1
	v_cvt_pk_f32_fp8_e32 v[228:229], v165
	v_cvt_pk_f32_fp8_sdwa v[230:231], v165 src0_sel:WORD_1
	v_cvt_pk_f32_fp8_e32 v[232:233], v166
	v_cvt_pk_f32_fp8_sdwa v[234:235], v166 src0_sel:WORD_1
	v_cvt_pk_f32_fp8_e32 v[236:237], v167
	v_cvt_pk_f32_fp8_sdwa v[238:239], v167 src0_sel:WORD_1
	v_pk_fma_f32 v[0:1], v[224:225], s[18:19], v[0:1] op_sel_hi:[1,0,1]
	v_pk_fma_f32 v[2:3], v[226:227], s[18:19], v[2:3] op_sel_hi:[1,0,1]
	v_pk_fma_f32 v[4:5], v[228:229], s[18:19], v[4:5] op_sel_hi:[1,0,1]
	v_pk_fma_f32 v[6:7], v[230:231], s[18:19], v[6:7] op_sel_hi:[1,0,1]
	v_pk_fma_f32 v[8:9], v[232:233], s[18:19], v[8:9] op_sel_hi:[1,0,1]
	v_pk_fma_f32 v[10:11], v[234:235], s[18:19], v[10:11] op_sel_hi:[1,0,1]
	v_pk_fma_f32 v[12:13], v[236:237], s[18:19], v[12:13] op_sel_hi:[1,0,1]
	v_pk_fma_f32 v[14:15], v[238:239], s[18:19], v[14:15] op_sel_hi:[1,0,1]
	v_cvt_pk_f32_fp8_e32 v[224:225], v168
	v_cvt_pk_f32_fp8_sdwa v[226:227], v168 src0_sel:WORD_1
	v_cvt_pk_f32_fp8_e32 v[228:229], v169
	v_cvt_pk_f32_fp8_sdwa v[230:231], v169 src0_sel:WORD_1
	v_cvt_pk_f32_fp8_e32 v[232:233], v170
	v_cvt_pk_f32_fp8_sdwa v[234:235], v170 src0_sel:WORD_1
	v_cvt_pk_f32_fp8_e32 v[236:237], v171
	v_cvt_pk_f32_fp8_sdwa v[238:239], v171 src0_sel:WORD_1
; DI void peer_item_v(const Params& p, int item) {
;     ...
;     float* orow = p.out + tok * 1024 + lane * 4;
;     float4 y[4];
;     float ss = 0.f;
; #pragma unroll
;     for (int i = 0; i < 4; ++i) {
;       y[i] = *(const float4*)(orow + 256 * i);
	v_pk_fma_f32 v[0:1], v[224:225], s[20:21], v[0:1] op_sel_hi:[1,0,1]
	v_pk_fma_f32 v[2:3], v[226:227], s[20:21], v[2:3] op_sel_hi:[1,0,1]
	v_pk_fma_f32 v[4:5], v[228:229], s[20:21], v[4:5] op_sel_hi:[1,0,1]
	v_pk_fma_f32 v[6:7], v[230:231], s[20:21], v[6:7] op_sel_hi:[1,0,1]
	v_pk_fma_f32 v[8:9], v[232:233], s[20:21], v[8:9] op_sel_hi:[1,0,1]
	v_pk_fma_f32 v[10:11], v[234:235], s[20:21], v[10:11] op_sel_hi:[1,0,1]
	v_pk_fma_f32 v[12:13], v[236:237], s[20:21], v[12:13] op_sel_hi:[1,0,1]
	v_pk_fma_f32 v[14:15], v[238:239], s[20:21], v[14:15] op_sel_hi:[1,0,1]
	v_cvt_pk_f32_fp8_e32 v[224:225], v172
	v_cvt_pk_f32_fp8_sdwa v[226:227], v172 src0_sel:WORD_1
	v_cvt_pk_f32_fp8_e32 v[228:229], v173
	v_cvt_pk_f32_fp8_sdwa v[230:231], v173 src0_sel:WORD_1
	v_cvt_pk_f32_fp8_e32 v[232:233], v174
	v_cvt_pk_f32_fp8_sdwa v[234:235], v174 src0_sel:WORD_1
	v_cvt_pk_f32_fp8_e32 v[236:237], v175
	v_cvt_pk_f32_fp8_sdwa v[238:239], v175 src0_sel:WORD_1
	v_pk_fma_f32 v[0:1], v[224:225], s[22:23], v[0:1] op_sel_hi:[1,0,1]
	v_pk_fma_f32 v[2:3], v[226:227], s[22:23], v[2:3] op_sel_hi:[1,0,1]
	v_pk_fma_f32 v[4:5], v[228:229], s[22:23], v[4:5] op_sel_hi:[1,0,1]
	v_pk_fma_f32 v[6:7], v[230:231], s[22:23], v[6:7] op_sel_hi:[1,0,1]
	v_pk_fma_f32 v[8:9], v[232:233], s[22:23], v[8:9] op_sel_hi:[1,0,1]
	v_pk_fma_f32 v[10:11], v[234:235], s[22:23], v[10:11] op_sel_hi:[1,0,1]
	v_pk_fma_f32 v[12:13], v[236:237], s[22:23], v[12:13] op_sel_hi:[1,0,1]
	v_pk_fma_f32 v[14:15], v[238:239], s[22:23], v[14:15] op_sel_hi:[1,0,1]
	v_cvt_pk_f32_fp8_e32 v[224:225], v176
	v_cvt_pk_f32_fp8_sdwa v[226:227], v176 src0_sel:WORD_1
	v_cvt_pk_f32_fp8_e32 v[228:229], v177
	v_cvt_pk_f32_fp8_sdwa v[230:231], v177 src0_sel:WORD_1
	v_cvt_pk_f32_fp8_e32 v[232:233], v178
	v_cvt_pk_f32_fp8_sdwa v[234:235], v178 src0_sel:WORD_1
	v_cvt_pk_f32_fp8_e32 v[236:237], v179
	v_cvt_pk_f32_fp8_sdwa v[238:239], v179 src0_sel:WORD_1
	v_pk_fma_f32 v[0:1], v[224:225], s[24:25], v[0:1] op_sel_hi:[1,0,1]
	v_pk_fma_f32 v[2:3], v[226:227], s[24:25], v[2:3] op_sel_hi:[1,0,1]
	v_pk_fma_f32 v[4:5], v[228:229], s[24:25], v[4:5] op_sel_hi:[1,0,1]
	v_pk_fma_f32 v[6:7], v[230:231], s[24:25], v[6:7] op_sel_hi:[1,0,1]
	v_pk_fma_f32 v[8:9], v[232:233], s[24:25], v[8:9] op_sel_hi:[1,0,1]
	v_pk_fma_f32 v[10:11], v[234:235], s[24:25], v[10:11] op_sel_hi:[1,0,1]
	v_pk_fma_f32 v[12:13], v[236:237], s[24:25], v[12:13] op_sel_hi:[1,0,1]
	v_pk_fma_f32 v[14:15], v[238:239], s[24:25], v[14:15] op_sel_hi:[1,0,1]
	v_cvt_pk_f32_fp8_e32 v[224:225], v180
	v_cvt_pk_f32_fp8_sdwa v[226:227], v180 src0_sel:WORD_1
	v_cvt_pk_f32_fp8_e32 v[228:229], v181
	v_cvt_pk_f32_fp8_sdwa v[230:231], v181 src0_sel:WORD_1
	v_cvt_pk_f32_fp8_e32 v[232:233], v182
	v_cvt_pk_f32_fp8_sdwa v[234:235], v182 src0_sel:WORD_1
	v_cvt_pk_f32_fp8_e32 v[236:237], v183
	v_cvt_pk_f32_fp8_sdwa v[238:239], v183 src0_sel:WORD_1
	v_pk_fma_f32 v[0:1], v[224:225], s[26:27], v[0:1] op_sel_hi:[1,0,1]
	v_pk_fma_f32 v[2:3], v[226:227], s[26:27], v[2:3] op_sel_hi:[1,0,1]
	v_pk_fma_f32 v[4:5], v[228:229], s[26:27], v[4:5] op_sel_hi:[1,0,1]
	v_pk_fma_f32 v[6:7], v[230:231], s[26:27], v[6:7] op_sel_hi:[1,0,1]
	v_pk_fma_f32 v[8:9], v[232:233], s[26:27], v[8:9] op_sel_hi:[1,0,1]
	v_pk_fma_f32 v[10:11], v[234:235], s[26:27], v[10:11] op_sel_hi:[1,0,1]
	v_pk_fma_f32 v[12:13], v[236:237], s[26:27], v[12:13] op_sel_hi:[1,0,1]
	v_pk_fma_f32 v[14:15], v[238:239], s[26:27], v[14:15] op_sel_hi:[1,0,1]
	v_cvt_pk_f32_fp8_e32 v[224:225], v184
	v_cvt_pk_f32_fp8_sdwa v[226:227], v184 src0_sel:WORD_1
	v_cvt_pk_f32_fp8_e32 v[228:229], v185
	v_cvt_pk_f32_fp8_sdwa v[230:231], v185 src0_sel:WORD_1
	v_cvt_pk_f32_fp8_e32 v[232:233], v186
	v_cvt_pk_f32_fp8_sdwa v[234:235], v186 src0_sel:WORD_1
	v_cvt_pk_f32_fp8_e32 v[236:237], v187
	v_cvt_pk_f32_fp8_sdwa v[238:239], v187 src0_sel:WORD_1
	v_pk_fma_f32 v[0:1], v[224:225], s[28:29], v[0:1] op_sel_hi:[1,0,1]
	v_pk_fma_f32 v[2:3], v[226:227], s[28:29], v[2:3] op_sel_hi:[1,0,1]
	v_pk_fma_f32 v[4:5], v[228:229], s[28:29], v[4:5] op_sel_hi:[1,0,1]
	v_pk_fma_f32 v[6:7], v[230:231], s[28:29], v[6:7] op_sel_hi:[1,0,1]
	v_pk_fma_f32 v[8:9], v[232:233], s[28:29], v[8:9] op_sel_hi:[1,0,1]
	v_pk_fma_f32 v[10:11], v[234:235], s[28:29], v[10:11] op_sel_hi:[1,0,1]
	v_pk_fma_f32 v[12:13], v[236:237], s[28:29], v[12:13] op_sel_hi:[1,0,1]
	v_pk_fma_f32 v[14:15], v[238:239], s[28:29], v[14:15] op_sel_hi:[1,0,1]
	v_cvt_pk_f32_fp8_e32 v[224:225], v188
	v_cvt_pk_f32_fp8_sdwa v[226:227], v188 src0_sel:WORD_1
	v_cvt_pk_f32_fp8_e32 v[228:229], v189
	v_cvt_pk_f32_fp8_sdwa v[230:231], v189 src0_sel:WORD_1
	v_cvt_pk_f32_fp8_e32 v[232:233], v190
	v_cvt_pk_f32_fp8_sdwa v[234:235], v190 src0_sel:WORD_1
	v_cvt_pk_f32_fp8_e32 v[236:237], v191
	v_cvt_pk_f32_fp8_sdwa v[238:239], v191 src0_sel:WORD_1
	v_pk_fma_f32 v[0:1], v[224:225], s[30:31], v[0:1] op_sel_hi:[1,0,1]
	v_pk_fma_f32 v[2:3], v[226:227], s[30:31], v[2:3] op_sel_hi:[1,0,1]
	v_pk_fma_f32 v[4:5], v[228:229], s[30:31], v[4:5] op_sel_hi:[1,0,1]
	v_pk_fma_f32 v[6:7], v[230:231], s[30:31], v[6:7] op_sel_hi:[1,0,1]
	v_pk_fma_f32 v[8:9], v[232:233], s[30:31], v[8:9] op_sel_hi:[1,0,1]
	v_pk_fma_f32 v[10:11], v[234:235], s[30:31], v[10:11] op_sel_hi:[1,0,1]
	v_pk_fma_f32 v[12:13], v[236:237], s[30:31], v[12:13] op_sel_hi:[1,0,1]
	v_pk_fma_f32 v[14:15], v[238:239], s[30:31], v[14:15] op_sel_hi:[1,0,1]
	v_readlane_b32 s16, v135, s72
	v_readlane_b32 s18, v135, s73
	v_readlane_b32 s20, v135, s74
	v_readlane_b32 s22, v135, s75
	v_readlane_b32 s24, v135, s76
	v_readlane_b32 s26, v135, s77
	v_readlane_b32 s28, v135, s78
	v_readlane_b32 s30, v135, s79
	s_cmp_eq_u32 s12, 7
	s_cbranch_scc1 .Lvd_last5_Lvq_kA
	v_readlane_b32 s48, v128, s80
	v_readlane_b32 s49, v128, s81
	v_readlane_b32 s50, v128, s82
	v_readlane_b32 s51, v128, s83
	v_readlane_b32 s52, v128, s84
	v_readlane_b32 s53, v128, s85
	v_readlane_b32 s54, v128, s86
	v_readlane_b32 s55, v128, s87
	s_add_u32 s32, s0, s48
	s_addc_u32 s33, s1, 0
	s_add_u32 s34, s0, s49
	s_addc_u32 s35, s1, 0
	s_add_u32 s36, s0, s50
	s_addc_u32 s37, s1, 0
	s_add_u32 s38, s0, s51
	s_addc_u32 s39, s1, 0
	s_add_u32 s40, s0, s52
	s_addc_u32 s41, s1, 0
	s_add_u32 s42, s0, s53
	s_addc_u32 s43, s1, 0
	s_add_u32 s44, s0, s54
	s_addc_u32 s45, s1, 0
	s_add_u32 s46, s0, s55
	s_addc_u32 s47, s1, 0
	global_load_dwordx4 v[160:163], v240, s[32:33]
	global_load_dwordx4 v[164:167], v240, s[34:35]
	global_load_dwordx4 v[168:171], v240, s[36:37]
	global_load_dwordx4 v[172:175], v240, s[38:39]
	global_load_dwordx4 v[176:179], v240, s[40:41]
	global_load_dwordx4 v[180:183], v240, s[42:43]
	global_load_dwordx4 v[184:187], v240, s[44:45]
	global_load_dwordx4 v[188:191], v240, s[46:47]
	s_waitcnt vmcnt(24)
	s_branch .Lvd_cons5_Lvq_kA
; DI void peer_item_v(const Params& p, int item) {
;     ...
;     float* orow = p.out + tok * 1024 + lane * 4;
;     float4 y[4];
;     float ss = 0.f;
; #pragma unroll
;     for (int i = 0; i < 4; ++i) {
;       y[i] = *(const float4*)(orow + 256 * i);
.Lvd_last5_Lvq_kA:
	global_load_dwordx4 v[160:163], v240, s[88:89]
	global_load_dwordx4 v[164:167], v240, s[88:89] offset:1024
	global_load_dwordx4 v[168:171], v240, s[88:89] offset:2048
	global_load_dwordx4 v[172:175], v240, s[88:89] offset:3072
	global_load_dwordx4 v[176:179], v240, s[90:91]
	global_load_dwordx4 v[180:183], v240, s[90:91] offset:1024
	global_load_dwordx4 v[184:187], v240, s[90:91] offset:2048
	global_load_dwordx4 v[188:191], v240, s[90:91] offset:3072
	s_waitcnt vmcnt(24)
.Lvd_cons5_Lvq_kA:
	v_cvt_pk_f32_fp8_e32 v[224:225], v192
	v_cvt_pk_f32_fp8_sdwa v[226:227], v192 src0_sel:WORD_1
	v_cvt_pk_f32_fp8_e32 v[228:229], v193
	v_cvt_pk_f32_fp8_sdwa v[230:231], v193 src0_sel:WORD_1
	v_cvt_pk_f32_fp8_e32 v[232:233], v194
	v_cvt_pk_f32_fp8_sdwa v[234:235], v194 src0_sel:WORD_1
	v_cvt_pk_f32_fp8_e32 v[236:237], v195
	v_cvt_pk_f32_fp8_sdwa v[238:239], v195 src0_sel:WORD_1
	v_pk_fma_f32 v[16:17], v[224:225], s[16:17], v[16:17] op_sel_hi:[1,0,1]
	v_pk_fma_f32 v[18:19], v[226:227], s[16:17], v[18:19] op_sel_hi:[1,0,1]
	v_pk_fma_f32 v[20:21], v[228:229], s[16:17], v[20:21] op_sel_hi:[1,0,1]
	v_pk_fma_f32 v[22:23], v[230:231], s[16:17], v[22:23] op_sel_hi:[1,0,1]
	v_pk_fma_f32 v[24:25], v[232:233], s[16:17], v[24:25] op_sel_hi:[1,0,1]
	v_pk_fma_f32 v[26:27], v[234:235], s[16:17], v[26:27] op_sel_hi:[1,0,1]
	v_pk_fma_f32 v[28:29], v[236:237], s[16:17], v[28:29] op_sel_hi:[1,0,1]
	v_pk_fma_f32 v[30:31], v[238:239], s[16:17], v[30:31] op_sel_hi:[1,0,1]
	v_cvt_pk_f32_fp8_e32 v[224:225], v196
	v_cvt_pk_f32_fp8_sdwa v[226:227], v196 src0_sel:WORD_1
	v_cvt_pk_f32_fp8_e32 v[228:229], v197
	v_cvt_pk_f32_fp8_sdwa v[230:231], v197 src0_sel:WORD_1
	v_cvt_pk_f32_fp8_e32 v[232:233], v198
	v_cvt_pk_f32_fp8_sdwa v[234:235], v198 src0_sel:WORD_1
	v_cvt_pk_f32_fp8_e32 v[236:237], v199
	v_cvt_pk_f32_fp8_sdwa v[238:239], v199 src0_sel:WORD_1
	v_pk_fma_f32 v[16:17], v[224:225], s[18:19], v[16:17] op_sel_hi:[1,0,1]
	v_pk_fma_f32 v[18:19], v[226:227], s[18:19], v[18:19] op_sel_hi:[1,0,1]
	v_pk_fma_f32 v[20:21], v[228:229], s[18:19], v[20:21] op_sel_hi:[1,0,1]
	v_pk_fma_f32 v[22:23], v[230:231], s[18:19], v[22:23] op_sel_hi:[1,0,1]
	v_pk_fma_f32 v[24:25], v[232:233], s[18:19], v[24:25] op_sel_hi:[1,0,1]
	v_pk_fma_f32 v[26:27], v[234:235], s[18:19], v[26:27] op_sel_hi:[1,0,1]
	v_pk_fma_f32 v[28:29], v[236:237], s[18:19], v[28:29] op_sel_hi:[1,0,1]
	v_pk_fma_f32 v[30:31], v[238:239], s[18:19], v[30:31] op_sel_hi:[1,0,1]
	v_cvt_pk_f32_fp8_e32 v[224:225], v200
	v_cvt_pk_f32_fp8_sdwa v[226:227], v200 src0_sel:WORD_1
	v_cvt_pk_f32_fp8_e32 v[228:229], v201
	v_cvt_pk_f32_fp8_sdwa v[230:231], v201 src0_sel:WORD_1
	v_cvt_pk_f32_fp8_e32 v[232:233], v202
	v_cvt_pk_f32_fp8_sdwa v[234:235], v202 src0_sel:WORD_1
	v_cvt_pk_f32_fp8_e32 v[236:237], v203
	v_cvt_pk_f32_fp8_sdwa v[238:239], v203 src0_sel:WORD_1
	v_pk_fma_f32 v[16:17], v[224:225], s[20:21], v[16:17] op_sel_hi:[1,0,1]
	v_pk_fma_f32 v[18:19], v[226:227], s[20:21], v[18:19] op_sel_hi:[1,0,1]
	v_pk_fma_f32 v[20:21], v[228:229], s[20:21], v[20:21] op_sel_hi:[1,0,1]
	v_pk_fma_f32 v[22:23], v[230:231], s[20:21], v[22:23] op_sel_hi:[1,0,1]
	v_pk_fma_f32 v[24:25], v[232:233], s[20:21], v[24:25] op_sel_hi:[1,0,1]
	v_pk_fma_f32 v[26:27], v[234:235], s[20:21], v[26:27] op_sel_hi:[1,0,1]
	v_pk_fma_f32 v[28:29], v[236:237], s[20:21], v[28:29] op_sel_hi:[1,0,1]
	v_pk_fma_f32 v[30:31], v[238:239], s[20:21], v[30:31] op_sel_hi:[1,0,1]
	v_cvt_pk_f32_fp8_e32 v[224:225], v204
	v_cvt_pk_f32_fp8_sdwa v[226:227], v204 src0_sel:WORD_1
	v_cvt_pk_f32_fp8_e32 v[228:229], v205
	v_cvt_pk_f32_fp8_sdwa v[230:231], v205 src0_sel:WORD_1
	v_cvt_pk_f32_fp8_e32 v[232:233], v206
	v_cvt_pk_f32_fp8_sdwa v[234:235], v206 src0_sel:WORD_1
	v_cvt_pk_f32_fp8_e32 v[236:237], v207
	v_cvt_pk_f32_fp8_sdwa v[238:239], v207 src0_sel:WORD_1
	v_pk_fma_f32 v[16:17], v[224:225], s[22:23], v[16:17] op_sel_hi:[1,0,1]
	v_pk_fma_f32 v[18:19], v[226:227], s[22:23], v[18:19] op_sel_hi:[1,0,1]
	v_pk_fma_f32 v[20:21], v[228:229], s[22:23], v[20:21] op_sel_hi:[1,0,1]
	v_pk_fma_f32 v[22:23], v[230:231], s[22:23], v[22:23] op_sel_hi:[1,0,1]
	v_pk_fma_f32 v[24:25], v[232:233], s[22:23], v[24:25] op_sel_hi:[1,0,1]
	v_pk_fma_f32 v[26:27], v[234:235], s[22:23], v[26:27] op_sel_hi:[1,0,1]
	v_pk_fma_f32 v[28:29], v[236:237], s[22:23], v[28:29] op_sel_hi:[1,0,1]
	v_pk_fma_f32 v[30:31], v[238:239], s[22:23], v[30:31] op_sel_hi:[1,0,1]
	v_cvt_pk_f32_fp8_e32 v[224:225], v208
	v_cvt_pk_f32_fp8_sdwa v[226:227], v208 src0_sel:WORD_1
	v_cvt_pk_f32_fp8_e32 v[228:229], v209
	v_cvt_pk_f32_fp8_sdwa v[230:231], v209 src0_sel:WORD_1
	v_cvt_pk_f32_fp8_e32 v[232:233], v210
	v_cvt_pk_f32_fp8_sdwa v[234:235], v210 src0_sel:WORD_1
	v_cvt_pk_f32_fp8_e32 v[236:237], v211
	v_cvt_pk_f32_fp8_sdwa v[238:239], v211 src0_sel:WORD_1
	v_pk_fma_f32 v[16:17], v[224:225], s[24:25], v[16:17] op_sel_hi:[1,0,1]
	v_pk_fma_f32 v[18:19], v[226:227], s[24:25], v[18:19] op_sel_hi:[1,0,1]
	v_pk_fma_f32 v[20:21], v[228:229], s[24:25], v[20:21] op_sel_hi:[1,0,1]
	v_pk_fma_f32 v[22:23], v[230:231], s[24:25], v[22:23] op_sel_hi:[1,0,1]
	v_pk_fma_f32 v[24:25], v[232:233], s[24:25], v[24:25] op_sel_hi:[1,0,1]
	v_pk_fma_f32 v[26:27], v[234:235], s[24:25], v[26:27] op_sel_hi:[1,0,1]
	v_pk_fma_f32 v[28:29], v[236:237], s[24:25], v[28:29] op_sel_hi:[1,0,1]
	v_pk_fma_f32 v[30:31], v[238:239], s[24:25], v[30:31] op_sel_hi:[1,0,1]
	v_cvt_pk_f32_fp8_e32 v[224:225], v212
	v_cvt_pk_f32_fp8_sdwa v[226:227], v212 src0_sel:WORD_1
	v_cvt_pk_f32_fp8_e32 v[228:229], v213
	v_cvt_pk_f32_fp8_sdwa v[230:231], v213 src0_sel:WORD_1
	v_cvt_pk_f32_fp8_e32 v[232:233], v214
	v_cvt_pk_f32_fp8_sdwa v[234:235], v214 src0_sel:WORD_1
	v_cvt_pk_f32_fp8_e32 v[236:237], v215
; DI void peer_item_v(const Params& p, int item) {
;     ...
;     float* orow = p.out + tok * 1024 + lane * 4;
;     float4 y[4];
;     float ss = 0.f;
; #pragma unroll
;     for (int i = 0; i < 4; ++i) {
;       y[i] = *(const float4*)(orow + 256 * i);
	v_cvt_pk_f32_fp8_sdwa v[238:239], v215 src0_sel:WORD_1
	v_pk_fma_f32 v[16:17], v[224:225], s[26:27], v[16:17] op_sel_hi:[1,0,1]
	v_pk_fma_f32 v[18:19], v[226:227], s[26:27], v[18:19] op_sel_hi:[1,0,1]
	v_pk_fma_f32 v[20:21], v[228:229], s[26:27], v[20:21] op_sel_hi:[1,0,1]
	v_pk_fma_f32 v[22:23], v[230:231], s[26:27], v[22:23] op_sel_hi:[1,0,1]
	v_pk_fma_f32 v[24:25], v[232:233], s[26:27], v[24:25] op_sel_hi:[1,0,1]
	v_pk_fma_f32 v[26:27], v[234:235], s[26:27], v[26:27] op_sel_hi:[1,0,1]
	v_pk_fma_f32 v[28:29], v[236:237], s[26:27], v[28:29] op_sel_hi:[1,0,1]
	v_pk_fma_f32 v[30:31], v[238:239], s[26:27], v[30:31] op_sel_hi:[1,0,1]
	v_cvt_pk_f32_fp8_e32 v[224:225], v216
	v_cvt_pk_f32_fp8_sdwa v[226:227], v216 src0_sel:WORD_1
	v_cvt_pk_f32_fp8_e32 v[228:229], v217
	v_cvt_pk_f32_fp8_sdwa v[230:231], v217 src0_sel:WORD_1
	v_cvt_pk_f32_fp8_e32 v[232:233], v218
	v_cvt_pk_f32_fp8_sdwa v[234:235], v218 src0_sel:WORD_1
	v_cvt_pk_f32_fp8_e32 v[236:237], v219
	v_cvt_pk_f32_fp8_sdwa v[238:239], v219 src0_sel:WORD_1
	v_pk_fma_f32 v[16:17], v[224:225], s[28:29], v[16:17] op_sel_hi:[1,0,1]
	v_pk_fma_f32 v[18:19], v[226:227], s[28:29], v[18:19] op_sel_hi:[1,0,1]
	v_pk_fma_f32 v[20:21], v[228:229], s[28:29], v[20:21] op_sel_hi:[1,0,1]
	v_pk_fma_f32 v[22:23], v[230:231], s[28:29], v[22:23] op_sel_hi:[1,0,1]
	v_pk_fma_f32 v[24:25], v[232:233], s[28:29], v[24:25] op_sel_hi:[1,0,1]
	v_pk_fma_f32 v[26:27], v[234:235], s[28:29], v[26:27] op_sel_hi:[1,0,1]
	v_pk_fma_f32 v[28:29], v[236:237], s[28:29], v[28:29] op_sel_hi:[1,0,1]
	v_pk_fma_f32 v[30:31], v[238:239], s[28:29], v[30:31] op_sel_hi:[1,0,1]
	v_cvt_pk_f32_fp8_e32 v[224:225], v220
	v_cvt_pk_f32_fp8_sdwa v[226:227], v220 src0_sel:WORD_1
	v_cvt_pk_f32_fp8_e32 v[228:229], v221
	v_cvt_pk_f32_fp8_sdwa v[230:231], v221 src0_sel:WORD_1
	v_cvt_pk_f32_fp8_e32 v[232:233], v222
	v_cvt_pk_f32_fp8_sdwa v[234:235], v222 src0_sel:WORD_1
	v_cvt_pk_f32_fp8_e32 v[236:237], v223
	v_cvt_pk_f32_fp8_sdwa v[238:239], v223 src0_sel:WORD_1
	v_pk_fma_f32 v[16:17], v[224:225], s[30:31], v[16:17] op_sel_hi:[1,0,1]
	v_pk_fma_f32 v[18:19], v[226:227], s[30:31], v[18:19] op_sel_hi:[1,0,1]
	v_pk_fma_f32 v[20:21], v[228:229], s[30:31], v[20:21] op_sel_hi:[1,0,1]
	v_pk_fma_f32 v[22:23], v[230:231], s[30:31], v[22:23] op_sel_hi:[1,0,1]
	v_pk_fma_f32 v[24:25], v[232:233], s[30:31], v[24:25] op_sel_hi:[1,0,1]
	v_pk_fma_f32 v[26:27], v[234:235], s[30:31], v[26:27] op_sel_hi:[1,0,1]
	v_pk_fma_f32 v[28:29], v[236:237], s[30:31], v[28:29] op_sel_hi:[1,0,1]
	v_pk_fma_f32 v[30:31], v[238:239], s[30:31], v[30:31] op_sel_hi:[1,0,1]
	v_readlane_b32 s16, v139, s72
	v_readlane_b32 s18, v139, s73
	v_readlane_b32 s20, v139, s74
	v_readlane_b32 s22, v139, s75
	v_readlane_b32 s24, v139, s76
	v_readlane_b32 s26, v139, s77
	v_readlane_b32 s28, v139, s78
	v_readlane_b32 s30, v139, s79
	s_cmp_eq_u32 s12, 7
	s_cbranch_scc1 .Lvd_last6_Lvq_kA
	v_readlane_b32 s48, v132, s80
	v_readlane_b32 s49, v132, s81
	v_readlane_b32 s50, v132, s82
	v_readlane_b32 s51, v132, s83
	v_readlane_b32 s52, v132, s84
	v_readlane_b32 s53, v132, s85
	v_readlane_b32 s54, v132, s86
	v_readlane_b32 s55, v132, s87
	s_add_u32 s32, s0, s48
	s_addc_u32 s33, s1, 0
	s_add_u32 s34, s0, s49
	s_addc_u32 s35, s1, 0
	s_add_u32 s36, s0, s50
	s_addc_u32 s37, s1, 0
	s_add_u32 s38, s0, s51
	s_addc_u32 s39, s1, 0
	s_add_u32 s40, s0, s52
	s_addc_u32 s41, s1, 0
	s_add_u32 s42, s0, s53
	s_addc_u32 s43, s1, 0
	s_add_u32 s44, s0, s54
	s_addc_u32 s45, s1, 0
	s_add_u32 s46, s0, s55
	s_addc_u32 s47, s1, 0
	global_load_dwordx4 v[192:195], v240, s[32:33]
	global_load_dwordx4 v[196:199], v240, s[34:35]
	global_load_dwordx4 v[200:203], v240, s[36:37]
	global_load_dwordx4 v[204:207], v240, s[38:39]
	global_load_dwordx4 v[208:211], v240, s[40:41]
	global_load_dwordx4 v[212:215], v240, s[42:43]
	global_load_dwordx4 v[216:219], v240, s[44:45]
	global_load_dwordx4 v[220:223], v240, s[46:47]
	s_waitcnt vmcnt(24)
	s_branch .Lvd_cons6_Lvq_kA
.Lvd_last6_Lvq_kA:
	global_load_dwordx4 v[192:195], v240, s[92:93]
	global_load_dwordx4 v[196:199], v240, s[92:93] offset:1024
	global_load_dwordx4 v[200:203], v240, s[92:93] offset:2048
	global_load_dwordx4 v[204:207], v240, s[92:93] offset:3072
	global_load_dwordx4 v[208:211], v240, s[94:95]
	global_load_dwordx4 v[212:215], v240, s[94:95] offset:1024
	global_load_dwordx4 v[216:219], v240, s[94:95] offset:2048
	global_load_dwordx4 v[220:223], v240, s[94:95] offset:3072
	s_waitcnt vmcnt(24)
; DI void peer_item_v(const Params& p, int item) {
;     ...
;     V_ISSUE(vqa, 0)
; #pragma unroll 1
;     for (int g = 0; g < 16; g += 2) {
;       V_ISSUE(vqb, g + 1)
;       V_CONSUME(vqa, g)
;       if (g + 2 < 16) V_ISSUE(vqa, g + 2)
;       V_CONSUME(vqb, g + 1)
;     }
.Lvd_cons6_Lvq_kA:
	v_cvt_pk_f32_fp8_e32 v[224:225], v64
	v_cvt_pk_f32_fp8_sdwa v[226:227], v64 src0_sel:WORD_1
	v_cvt_pk_f32_fp8_e32 v[228:229], v65
	v_cvt_pk_f32_fp8_sdwa v[230:231], v65 src0_sel:WORD_1
	v_cvt_pk_f32_fp8_e32 v[232:233], v66
	v_cvt_pk_f32_fp8_sdwa v[234:235], v66 src0_sel:WORD_1
	v_cvt_pk_f32_fp8_e32 v[236:237], v67
	v_cvt_pk_f32_fp8_sdwa v[238:239], v67 src0_sel:WORD_1
	v_pk_fma_f32 v[32:33], v[224:225], s[16:17], v[32:33] op_sel_hi:[1,0,1]
	v_pk_fma_f32 v[34:35], v[226:227], s[16:17], v[34:35] op_sel_hi:[1,0,1]
	v_pk_fma_f32 v[36:37], v[228:229], s[16:17], v[36:37] op_sel_hi:[1,0,1]
	v_pk_fma_f32 v[38:39], v[230:231], s[16:17], v[38:39] op_sel_hi:[1,0,1]
	v_pk_fma_f32 v[40:41], v[232:233], s[16:17], v[40:41] op_sel_hi:[1,0,1]
	v_pk_fma_f32 v[42:43], v[234:235], s[16:17], v[42:43] op_sel_hi:[1,0,1]
	v_pk_fma_f32 v[44:45], v[236:237], s[16:17], v[44:45] op_sel_hi:[1,0,1]
	v_pk_fma_f32 v[46:47], v[238:239], s[16:17], v[46:47] op_sel_hi:[1,0,1]
	v_cvt_pk_f32_fp8_e32 v[224:225], v68
	v_cvt_pk_f32_fp8_sdwa v[226:227], v68 src0_sel:WORD_1
	v_cvt_pk_f32_fp8_e32 v[228:229], v69
	v_cvt_pk_f32_fp8_sdwa v[230:231], v69 src0_sel:WORD_1
	v_cvt_pk_f32_fp8_e32 v[232:233], v70
	v_cvt_pk_f32_fp8_sdwa v[234:235], v70 src0_sel:WORD_1
	v_cvt_pk_f32_fp8_e32 v[236:237], v71
	v_cvt_pk_f32_fp8_sdwa v[238:239], v71 src0_sel:WORD_1
	v_pk_fma_f32 v[32:33], v[224:225], s[18:19], v[32:33] op_sel_hi:[1,0,1]
	v_pk_fma_f32 v[34:35], v[226:227], s[18:19], v[34:35] op_sel_hi:[1,0,1]
	v_pk_fma_f32 v[36:37], v[228:229], s[18:19], v[36:37] op_sel_hi:[1,0,1]
	v_pk_fma_f32 v[38:39], v[230:231], s[18:19], v[38:39] op_sel_hi:[1,0,1]
	v_pk_fma_f32 v[40:41], v[232:233], s[18:19], v[40:41] op_sel_hi:[1,0,1]
	v_pk_fma_f32 v[42:43], v[234:235], s[18:19], v[42:43] op_sel_hi:[1,0,1]
	v_pk_fma_f32 v[44:45], v[236:237], s[18:19], v[44:45] op_sel_hi:[1,0,1]
	v_pk_fma_f32 v[46:47], v[238:239], s[18:19], v[46:47] op_sel_hi:[1,0,1]
	v_cvt_pk_f32_fp8_e32 v[224:225], v72
	v_cvt_pk_f32_fp8_sdwa v[226:227], v72 src0_sel:WORD_1
	v_cvt_pk_f32_fp8_e32 v[228:229], v73
	v_cvt_pk_f32_fp8_sdwa v[230:231], v73 src0_sel:WORD_1
	v_cvt_pk_f32_fp8_e32 v[232:233], v74
	v_cvt_pk_f32_fp8_sdwa v[234:235], v74 src0_sel:WORD_1
	v_cvt_pk_f32_fp8_e32 v[236:237], v75
	v_cvt_pk_f32_fp8_sdwa v[238:239], v75 src0_sel:WORD_1
	v_pk_fma_f32 v[32:33], v[224:225], s[20:21], v[32:33] op_sel_hi:[1,0,1]
	v_pk_fma_f32 v[34:35], v[226:227], s[20:21], v[34:35] op_sel_hi:[1,0,1]
	v_pk_fma_f32 v[36:37], v[228:229], s[20:21], v[36:37] op_sel_hi:[1,0,1]
	v_pk_fma_f32 v[38:39], v[230:231], s[20:21], v[38:39] op_sel_hi:[1,0,1]
	v_pk_fma_f32 v[40:41], v[232:233], s[20:21], v[40:41] op_sel_hi:[1,0,1]
	v_pk_fma_f32 v[42:43], v[234:235], s[20:21], v[42:43] op_sel_hi:[1,0,1]
	v_pk_fma_f32 v[44:45], v[236:237], s[20:21], v[44:45] op_sel_hi:[1,0,1]
	v_pk_fma_f32 v[46:47], v[238:239], s[20:21], v[46:47] op_sel_hi:[1,0,1]
	v_cvt_pk_f32_fp8_e32 v[224:225], v76
	v_cvt_pk_f32_fp8_sdwa v[226:227], v76 src0_sel:WORD_1
	v_cvt_pk_f32_fp8_e32 v[228:229], v77
	v_cvt_pk_f32_fp8_sdwa v[230:231], v77 src0_sel:WORD_1
	v_cvt_pk_f32_fp8_e32 v[232:233], v78
	v_cvt_pk_f32_fp8_sdwa v[234:235], v78 src0_sel:WORD_1
	v_cvt_pk_f32_fp8_e32 v[236:237], v79
	v_cvt_pk_f32_fp8_sdwa v[238:239], v79 src0_sel:WORD_1
	v_pk_fma_f32 v[32:33], v[224:225], s[22:23], v[32:33] op_sel_hi:[1,0,1]
	v_pk_fma_f32 v[34:35], v[226:227], s[22:23], v[34:35] op_sel_hi:[1,0,1]
	v_pk_fma_f32 v[36:37], v[228:229], s[22:23], v[36:37] op_sel_hi:[1,0,1]
	v_pk_fma_f32 v[38:39], v[230:231], s[22:23], v[38:39] op_sel_hi:[1,0,1]
	v_pk_fma_f32 v[40:41], v[232:233], s[22:23], v[40:41] op_sel_hi:[1,0,1]
	v_pk_fma_f32 v[42:43], v[234:235], s[22:23], v[42:43] op_sel_hi:[1,0,1]
	v_pk_fma_f32 v[44:45], v[236:237], s[22:23], v[44:45] op_sel_hi:[1,0,1]
	v_pk_fma_f32 v[46:47], v[238:239], s[22:23], v[46:47] op_sel_hi:[1,0,1]
	v_cvt_pk_f32_fp8_e32 v[224:225], v80
	v_cvt_pk_f32_fp8_sdwa v[226:227], v80 src0_sel:WORD_1
	v_cvt_pk_f32_fp8_e32 v[228:229], v81
	v_cvt_pk_f32_fp8_sdwa v[230:231], v81 src0_sel:WORD_1
	v_cvt_pk_f32_fp8_e32 v[232:233], v82
	v_cvt_pk_f32_fp8_sdwa v[234:235], v82 src0_sel:WORD_1
	v_cvt_pk_f32_fp8_e32 v[236:237], v83
	v_cvt_pk_f32_fp8_sdwa v[238:239], v83 src0_sel:WORD_1
	v_pk_fma_f32 v[32:33], v[224:225], s[24:25], v[32:33] op_sel_hi:[1,0,1]
	v_pk_fma_f32 v[34:35], v[226:227], s[24:25], v[34:35] op_sel_hi:[1,0,1]
	v_pk_fma_f32 v[36:37], v[228:229], s[24:25], v[36:37] op_sel_hi:[1,0,1]
	v_pk_fma_f32 v[38:39], v[230:231], s[24:25], v[38:39] op_sel_hi:[1,0,1]
; DI void peer_item_v(const Params& p, int item) {
;     ...
;     V_ISSUE(vqa, 0)
; #pragma unroll 1
;     for (int g = 0; g < 16; g += 2) {
;       V_ISSUE(vqb, g + 1)
;       V_CONSUME(vqa, g)
;       if (g + 2 < 16) V_ISSUE(vqa, g + 2)
;       V_CONSUME(vqb, g + 1)
;     }
	v_pk_fma_f32 v[40:41], v[232:233], s[24:25], v[40:41] op_sel_hi:[1,0,1]
	v_pk_fma_f32 v[42:43], v[234:235], s[24:25], v[42:43] op_sel_hi:[1,0,1]
	v_pk_fma_f32 v[44:45], v[236:237], s[24:25], v[44:45] op_sel_hi:[1,0,1]
	v_pk_fma_f32 v[46:47], v[238:239], s[24:25], v[46:47] op_sel_hi:[1,0,1]
	v_cvt_pk_f32_fp8_e32 v[224:225], v84
	v_cvt_pk_f32_fp8_sdwa v[226:227], v84 src0_sel:WORD_1
	v_cvt_pk_f32_fp8_e32 v[228:229], v85
	v_cvt_pk_f32_fp8_sdwa v[230:231], v85 src0_sel:WORD_1
	v_cvt_pk_f32_fp8_e32 v[232:233], v86
	v_cvt_pk_f32_fp8_sdwa v[234:235], v86 src0_sel:WORD_1
	v_cvt_pk_f32_fp8_e32 v[236:237], v87
	v_cvt_pk_f32_fp8_sdwa v[238:239], v87 src0_sel:WORD_1
	v_pk_fma_f32 v[32:33], v[224:225], s[26:27], v[32:33] op_sel_hi:[1,0,1]
	v_pk_fma_f32 v[34:35], v[226:227], s[26:27], v[34:35] op_sel_hi:[1,0,1]
	v_pk_fma_f32 v[36:37], v[228:229], s[26:27], v[36:37] op_sel_hi:[1,0,1]
	v_pk_fma_f32 v[38:39], v[230:231], s[26:27], v[38:39] op_sel_hi:[1,0,1]
	v_pk_fma_f32 v[40:41], v[232:233], s[26:27], v[40:41] op_sel_hi:[1,0,1]
	v_pk_fma_f32 v[42:43], v[234:235], s[26:27], v[42:43] op_sel_hi:[1,0,1]
	v_pk_fma_f32 v[44:45], v[236:237], s[26:27], v[44:45] op_sel_hi:[1,0,1]
	v_pk_fma_f32 v[46:47], v[238:239], s[26:27], v[46:47] op_sel_hi:[1,0,1]
	v_cvt_pk_f32_fp8_e32 v[224:225], v88
	v_cvt_pk_f32_fp8_sdwa v[226:227], v88 src0_sel:WORD_1
	v_cvt_pk_f32_fp8_e32 v[228:229], v89
	v_cvt_pk_f32_fp8_sdwa v[230:231], v89 src0_sel:WORD_1
	v_cvt_pk_f32_fp8_e32 v[232:233], v90
	v_cvt_pk_f32_fp8_sdwa v[234:235], v90 src0_sel:WORD_1
	v_cvt_pk_f32_fp8_e32 v[236:237], v91
	v_cvt_pk_f32_fp8_sdwa v[238:239], v91 src0_sel:WORD_1
	v_pk_fma_f32 v[32:33], v[224:225], s[28:29], v[32:33] op_sel_hi:[1,0,1]
	v_pk_fma_f32 v[34:35], v[226:227], s[28:29], v[34:35] op_sel_hi:[1,0,1]
	v_pk_fma_f32 v[36:37], v[228:229], s[28:29], v[36:37] op_sel_hi:[1,0,1]
	v_pk_fma_f32 v[38:39], v[230:231], s[28:29], v[38:39] op_sel_hi:[1,0,1]
	v_pk_fma_f32 v[40:41], v[232:233], s[28:29], v[40:41] op_sel_hi:[1,0,1]
	v_pk_fma_f32 v[42:43], v[234:235], s[28:29], v[42:43] op_sel_hi:[1,0,1]
	v_pk_fma_f32 v[44:45], v[236:237], s[28:29], v[44:45] op_sel_hi:[1,0,1]
	v_pk_fma_f32 v[46:47], v[238:239], s[28:29], v[46:47] op_sel_hi:[1,0,1]
	v_cvt_pk_f32_fp8_e32 v[224:225], v92
	v_cvt_pk_f32_fp8_sdwa v[226:227], v92 src0_sel:WORD_1
	v_cvt_pk_f32_fp8_e32 v[228:229], v93
	v_cvt_pk_f32_fp8_sdwa v[230:231], v93 src0_sel:WORD_1
	v_cvt_pk_f32_fp8_e32 v[232:233], v94
	v_cvt_pk_f32_fp8_sdwa v[234:235], v94 src0_sel:WORD_1
	v_cvt_pk_f32_fp8_e32 v[236:237], v95
	v_cvt_pk_f32_fp8_sdwa v[238:239], v95 src0_sel:WORD_1
	v_pk_fma_f32 v[32:33], v[224:225], s[30:31], v[32:33] op_sel_hi:[1,0,1]
	v_pk_fma_f32 v[34:35], v[226:227], s[30:31], v[34:35] op_sel_hi:[1,0,1]
	v_pk_fma_f32 v[36:37], v[228:229], s[30:31], v[36:37] op_sel_hi:[1,0,1]
	v_pk_fma_f32 v[38:39], v[230:231], s[30:31], v[38:39] op_sel_hi:[1,0,1]
	v_pk_fma_f32 v[40:41], v[232:233], s[30:31], v[40:41] op_sel_hi:[1,0,1]
	v_pk_fma_f32 v[42:43], v[234:235], s[30:31], v[42:43] op_sel_hi:[1,0,1]
	v_pk_fma_f32 v[44:45], v[236:237], s[30:31], v[44:45] op_sel_hi:[1,0,1]
	v_pk_fma_f32 v[46:47], v[238:239], s[30:31], v[46:47] op_sel_hi:[1,0,1]
	v_readlane_b32 s16, v143, s72
	v_readlane_b32 s18, v143, s73
	v_readlane_b32 s20, v143, s74
	v_readlane_b32 s22, v143, s75
	v_readlane_b32 s24, v143, s76
	v_readlane_b32 s26, v143, s77
	v_readlane_b32 s28, v143, s78
	v_readlane_b32 s30, v143, s79
	s_cmp_eq_u32 s12, 7
	s_cbranch_scc1 .Lvd_last7_Lvq_kA
	v_readlane_b32 s48, v136, s80
	v_readlane_b32 s49, v136, s81
	v_readlane_b32 s50, v136, s82
	v_readlane_b32 s51, v136, s83
	v_readlane_b32 s52, v136, s84
	v_readlane_b32 s53, v136, s85
	v_readlane_b32 s54, v136, s86
	v_readlane_b32 s55, v136, s87
	s_add_u32 s32, s0, s48
	s_addc_u32 s33, s1, 0
	s_add_u32 s34, s0, s49
	s_addc_u32 s35, s1, 0
	s_add_u32 s36, s0, s50
	s_addc_u32 s37, s1, 0
	s_add_u32 s38, s0, s51
	s_addc_u32 s39, s1, 0
	s_add_u32 s40, s0, s52
	s_addc_u32 s41, s1, 0
	s_add_u32 s42, s0, s53
	s_addc_u32 s43, s1, 0
	s_add_u32 s44, s0, s54
	s_addc_u32 s45, s1, 0
	s_add_u32 s46, s0, s55
	s_addc_u32 s47, s1, 0
	global_load_dwordx4 v[64:67], v240, s[32:33]
	global_load_dwordx4 v[68:71], v240, s[34:35]
	global_load_dwordx4 v[72:75], v240, s[36:37]
	global_load_dwordx4 v[76:79], v240, s[38:39]
	global_load_dwordx4 v[80:83], v240, s[40:41]
	global_load_dwordx4 v[84:87], v240, s[42:43]
	global_load_dwordx4 v[88:91], v240, s[44:45]
	global_load_dwordx4 v[92:95], v240, s[46:47]
	s_waitcnt vmcnt(24)
	s_branch .Lvd_cons7_Lvq_kA

; DI void peer_item_v(const Params& p, int item) {
;     ...
;     V_ISSUE(vqa, 0)
; #pragma unroll 1
;     for (int g = 0; g < 16; g += 2) {
;       V_ISSUE(vqb, g + 1)
;       V_CONSUME(vqa, g)
;       if (g + 2 < 16) V_ISSUE(vqa, g + 2)
;       V_CONSUME(vqb, g + 1)
;     }
.Lvd_cons7_Lvq_kA:
	v_cvt_pk_f32_fp8_e32 v[224:225], v96
	v_cvt_pk_f32_fp8_sdwa v[226:227], v96 src0_sel:WORD_1
	v_cvt_pk_f32_fp8_e32 v[228:229], v97
	v_cvt_pk_f32_fp8_sdwa v[230:231], v97 src0_sel:WORD_1
	v_cvt_pk_f32_fp8_e32 v[232:233], v98
	v_cvt_pk_f32_fp8_sdwa v[234:235], v98 src0_sel:WORD_1
	v_cvt_pk_f32_fp8_e32 v[236:237], v99
	v_cvt_pk_f32_fp8_sdwa v[238:239], v99 src0_sel:WORD_1
	v_pk_fma_f32 v[48:49], v[224:225], s[16:17], v[48:49] op_sel_hi:[1,0,1]
	v_pk_fma_f32 v[50:51], v[226:227], s[16:17], v[50:51] op_sel_hi:[1,0,1]
	v_pk_fma_f32 v[52:53], v[228:229], s[16:17], v[52:53] op_sel_hi:[1,0,1]
	v_pk_fma_f32 v[54:55], v[230:231], s[16:17], v[54:55] op_sel_hi:[1,0,1]
	v_pk_fma_f32 v[56:57], v[232:233], s[16:17], v[56:57] op_sel_hi:[1,0,1]
	v_pk_fma_f32 v[58:59], v[234:235], s[16:17], v[58:59] op_sel_hi:[1,0,1]
	v_pk_fma_f32 v[60:61], v[236:237], s[16:17], v[60:61] op_sel_hi:[1,0,1]
	v_pk_fma_f32 v[62:63], v[238:239], s[16:17], v[62:63] op_sel_hi:[1,0,1]
	v_cvt_pk_f32_fp8_e32 v[224:225], v100
	v_cvt_pk_f32_fp8_sdwa v[226:227], v100 src0_sel:WORD_1
	v_cvt_pk_f32_fp8_e32 v[228:229], v101
	v_cvt_pk_f32_fp8_sdwa v[230:231], v101 src0_sel:WORD_1
	v_cvt_pk_f32_fp8_e32 v[232:233], v102
	v_cvt_pk_f32_fp8_sdwa v[234:235], v102 src0_sel:WORD_1
	v_cvt_pk_f32_fp8_e32 v[236:237], v103
	v_cvt_pk_f32_fp8_sdwa v[238:239], v103 src0_sel:WORD_1
	v_pk_fma_f32 v[48:49], v[224:225], s[18:19], v[48:49] op_sel_hi:[1,0,1]
	v_pk_fma_f32 v[50:51], v[226:227], s[18:19], v[50:51] op_sel_hi:[1,0,1]
	v_pk_fma_f32 v[52:53], v[228:229], s[18:19], v[52:53] op_sel_hi:[1,0,1]
	v_pk_fma_f32 v[54:55], v[230:231], s[18:19], v[54:55] op_sel_hi:[1,0,1]
	v_pk_fma_f32 v[56:57], v[232:233], s[18:19], v[56:57] op_sel_hi:[1,0,1]
	v_pk_fma_f32 v[58:59], v[234:235], s[18:19], v[58:59] op_sel_hi:[1,0,1]
	v_pk_fma_f32 v[60:61], v[236:237], s[18:19], v[60:61] op_sel_hi:[1,0,1]
	v_pk_fma_f32 v[62:63], v[238:239], s[18:19], v[62:63] op_sel_hi:[1,0,1]
	v_cvt_pk_f32_fp8_e32 v[224:225], v104
	v_cvt_pk_f32_fp8_sdwa v[226:227], v104 src0_sel:WORD_1
	v_cvt_pk_f32_fp8_e32 v[228:229], v105
	v_cvt_pk_f32_fp8_sdwa v[230:231], v105 src0_sel:WORD_1
	v_cvt_pk_f32_fp8_e32 v[232:233], v106
	v_cvt_pk_f32_fp8_sdwa v[234:235], v106 src0_sel:WORD_1
	v_cvt_pk_f32_fp8_e32 v[236:237], v107
	v_cvt_pk_f32_fp8_sdwa v[238:239], v107 src0_sel:WORD_1
	v_pk_fma_f32 v[48:49], v[224:225], s[20:21], v[48:49] op_sel_hi:[1,0,1]
	v_pk_fma_f32 v[50:51], v[226:227], s[20:21], v[50:51] op_sel_hi:[1,0,1]
	v_pk_fma_f32 v[52:53], v[228:229], s[20:21], v[52:53] op_sel_hi:[1,0,1]
	v_pk_fma_f32 v[54:55], v[230:231], s[20:21], v[54:55] op_sel_hi:[1,0,1]
	v_pk_fma_f32 v[56:57], v[232:233], s[20:21], v[56:57] op_sel_hi:[1,0,1]
	v_pk_fma_f32 v[58:59], v[234:235], s[20:21], v[58:59] op_sel_hi:[1,0,1]
	v_pk_fma_f32 v[60:61], v[236:237], s[20:21], v[60:61] op_sel_hi:[1,0,1]
	v_pk_fma_f32 v[62:63], v[238:239], s[20:21], v[62:63] op_sel_hi:[1,0,1]
	v_cvt_pk_f32_fp8_e32 v[224:225], v108
	v_cvt_pk_f32_fp8_sdwa v[226:227], v108 src0_sel:WORD_1
	v_cvt_pk_f32_fp8_e32 v[228:229], v109
	v_cvt_pk_f32_fp8_sdwa v[230:231], v109 src0_sel:WORD_1
	v_cvt_pk_f32_fp8_e32 v[232:233], v110
	v_cvt_pk_f32_fp8_sdwa v[234:235], v110 src0_sel:WORD_1
	v_cvt_pk_f32_fp8_e32 v[236:237], v111
	v_cvt_pk_f32_fp8_sdwa v[238:239], v111 src0_sel:WORD_1
	v_pk_fma_f32 v[48:49], v[224:225], s[22:23], v[48:49] op_sel_hi:[1,0,1]
	v_pk_fma_f32 v[50:51], v[226:227], s[22:23], v[50:51] op_sel_hi:[1,0,1]
	v_pk_fma_f32 v[52:53], v[228:229], s[22:23], v[52:53] op_sel_hi:[1,0,1]
	v_pk_fma_f32 v[54:55], v[230:231], s[22:23], v[54:55] op_sel_hi:[1,0,1]
	v_pk_fma_f32 v[56:57], v[232:233], s[22:23], v[56:57] op_sel_hi:[1,0,1]
	v_pk_fma_f32 v[58:59], v[234:235], s[22:23], v[58:59] op_sel_hi:[1,0,1]
	v_pk_fma_f32 v[60:61], v[236:237], s[22:23], v[60:61] op_sel_hi:[1,0,1]
	v_pk_fma_f32 v[62:63], v[238:239], s[22:23], v[62:63] op_sel_hi:[1,0,1]
	v_cvt_pk_f32_fp8_e32 v[224:225], v112
	v_cvt_pk_f32_fp8_sdwa v[226:227], v112 src0_sel:WORD_1
	v_cvt_pk_f32_fp8_e32 v[228:229], v113
	v_cvt_pk_f32_fp8_sdwa v[230:231], v113 src0_sel:WORD_1
	v_cvt_pk_f32_fp8_e32 v[232:233], v114
	v_cvt_pk_f32_fp8_sdwa v[234:235], v114 src0_sel:WORD_1
	v_cvt_pk_f32_fp8_e32 v[236:237], v115
	v_cvt_pk_f32_fp8_sdwa v[238:239], v115 src0_sel:WORD_1
	v_pk_fma_f32 v[48:49], v[224:225], s[24:25], v[48:49] op_sel_hi:[1,0,1]
	v_pk_fma_f32 v[50:51], v[226:227], s[24:25], v[50:51] op_sel_hi:[1,0,1]
	v_pk_fma_f32 v[52:53], v[228:229], s[24:25], v[52:53] op_sel_hi:[1,0,1]
	v_pk_fma_f32 v[54:55], v[230:231], s[24:25], v[54:55] op_sel_hi:[1,0,1]
	v_pk_fma_f32 v[56:57], v[232:233], s[24:25], v[56:57] op_sel_hi:[1,0,1]
	v_pk_fma_f32 v[58:59], v[234:235], s[24:25], v[58:59] op_sel_hi:[1,0,1]
	v_pk_fma_f32 v[60:61], v[236:237], s[24:25], v[60:61] op_sel_hi:[1,0,1]
	v_pk_fma_f32 v[62:63], v[238:239], s[24:25], v[62:63] op_sel_hi:[1,0,1]
	v_cvt_pk_f32_fp8_e32 v[224:225], v116
	v_cvt_pk_f32_fp8_sdwa v[226:227], v116 src0_sel:WORD_1
	v_cvt_pk_f32_fp8_e32 v[228:229], v117
	v_cvt_pk_f32_fp8_sdwa v[230:231], v117 src0_sel:WORD_1
	v_cvt_pk_f32_fp8_e32 v[232:233], v118
	v_cvt_pk_f32_fp8_sdwa v[234:235], v118 src0_sel:WORD_1
	v_cvt_pk_f32_fp8_e32 v[236:237], v119
	v_cvt_pk_f32_fp8_sdwa v[238:239], v119 src0_sel:WORD_1
	v_pk_fma_f32 v[48:49], v[224:225], s[26:27], v[48:49] op_sel_hi:[1,0,1]
	v_pk_fma_f32 v[50:51], v[226:227], s[26:27], v[50:51] op_sel_hi:[1,0,1]
	v_pk_fma_f32 v[52:53], v[228:229], s[26:27], v[52:53] op_sel_hi:[1,0,1]
	v_pk_fma_f32 v[54:55], v[230:231], s[26:27], v[54:55] op_sel_hi:[1,0,1]
	v_pk_fma_f32 v[56:57], v[232:233], s[26:27], v[56:57] op_sel_hi:[1,0,1]
	v_pk_fma_f32 v[58:59], v[234:235], s[26:27], v[58:59] op_sel_hi:[1,0,1]
; DI void peer_item_v(const Params& p, int item) {
;     ...
;     V_ISSUE(vqa, 0)
; #pragma unroll 1
;     for (int g = 0; g < 16; g += 2) {
;       V_ISSUE(vqb, g + 1)
;       V_CONSUME(vqa, g)
;       if (g + 2 < 16) V_ISSUE(vqa, g + 2)
;       V_CONSUME(vqb, g + 1)
;     }
;     ...
;     float* orow = p.out + tok * 1024 + lane * 4;
;     float4 y[4];
;     float ss = 0.f;
; #pragma unroll
;     for (int i = 0; i < 4; ++i) {
;       y[i] = *(const float4*)(orow + 256 * i);
;       y[i].x += out[4 * i]; y[i].y += out[4 * i + 1]; y[i].z += out[4 * i + 2]; y[i].w += out[4 * i + 3];
;       ss += y[i].x * y[i].x + y[i].y * y[i].y + y[i].z * y[i].z + y[i].w * y[i].w;
;     }
;     ss = wave_sum(ss);
;     const float r = rsqrtf(ss * (1.f / 1024.f) + 1e-6f);
	v_pk_fma_f32 v[60:61], v[236:237], s[26:27], v[60:61] op_sel_hi:[1,0,1]
	v_pk_fma_f32 v[62:63], v[238:239], s[26:27], v[62:63] op_sel_hi:[1,0,1]
	v_cvt_pk_f32_fp8_e32 v[224:225], v120
	v_cvt_pk_f32_fp8_sdwa v[226:227], v120 src0_sel:WORD_1
	v_cvt_pk_f32_fp8_e32 v[228:229], v121
	v_cvt_pk_f32_fp8_sdwa v[230:231], v121 src0_sel:WORD_1
	v_cvt_pk_f32_fp8_e32 v[232:233], v122
	v_cvt_pk_f32_fp8_sdwa v[234:235], v122 src0_sel:WORD_1
	v_cvt_pk_f32_fp8_e32 v[236:237], v123
	v_cvt_pk_f32_fp8_sdwa v[238:239], v123 src0_sel:WORD_1
	v_pk_fma_f32 v[48:49], v[224:225], s[28:29], v[48:49] op_sel_hi:[1,0,1]
	v_pk_fma_f32 v[50:51], v[226:227], s[28:29], v[50:51] op_sel_hi:[1,0,1]
	v_pk_fma_f32 v[52:53], v[228:229], s[28:29], v[52:53] op_sel_hi:[1,0,1]
	v_pk_fma_f32 v[54:55], v[230:231], s[28:29], v[54:55] op_sel_hi:[1,0,1]
	v_pk_fma_f32 v[56:57], v[232:233], s[28:29], v[56:57] op_sel_hi:[1,0,1]
	v_pk_fma_f32 v[58:59], v[234:235], s[28:29], v[58:59] op_sel_hi:[1,0,1]
	v_pk_fma_f32 v[60:61], v[236:237], s[28:29], v[60:61] op_sel_hi:[1,0,1]
	v_pk_fma_f32 v[62:63], v[238:239], s[28:29], v[62:63] op_sel_hi:[1,0,1]
	v_cvt_pk_f32_fp8_e32 v[224:225], v124
	v_cvt_pk_f32_fp8_sdwa v[226:227], v124 src0_sel:WORD_1
	v_cvt_pk_f32_fp8_e32 v[228:229], v125
	v_cvt_pk_f32_fp8_sdwa v[230:231], v125 src0_sel:WORD_1
	v_cvt_pk_f32_fp8_e32 v[232:233], v126
	v_cvt_pk_f32_fp8_sdwa v[234:235], v126 src0_sel:WORD_1
	v_cvt_pk_f32_fp8_e32 v[236:237], v127
	v_cvt_pk_f32_fp8_sdwa v[238:239], v127 src0_sel:WORD_1
	v_pk_fma_f32 v[48:49], v[224:225], s[30:31], v[48:49] op_sel_hi:[1,0,1]
	v_pk_fma_f32 v[50:51], v[226:227], s[30:31], v[50:51] op_sel_hi:[1,0,1]
	v_pk_fma_f32 v[52:53], v[228:229], s[30:31], v[52:53] op_sel_hi:[1,0,1]
	v_pk_fma_f32 v[54:55], v[230:231], s[30:31], v[54:55] op_sel_hi:[1,0,1]
	v_pk_fma_f32 v[56:57], v[232:233], s[30:31], v[56:57] op_sel_hi:[1,0,1]
	v_pk_fma_f32 v[58:59], v[234:235], s[30:31], v[58:59] op_sel_hi:[1,0,1]
	v_pk_fma_f32 v[60:61], v[236:237], s[30:31], v[60:61] op_sel_hi:[1,0,1]
	v_pk_fma_f32 v[62:63], v[238:239], s[30:31], v[62:63] op_sel_hi:[1,0,1]
	s_mov_b32 s72, s80
	s_mov_b32 s73, s81
	s_mov_b32 s74, s82
	s_mov_b32 s75, s83
	s_mov_b32 s76, s84
	s_mov_b32 s77, s85
	s_mov_b32 s78, s86
	s_mov_b32 s79, s87
	s_add_u32 s80, s80, 8
	s_add_u32 s81, s81, 8
	s_add_u32 s82, s82, 8
	s_add_u32 s83, s83, 8
	s_add_u32 s84, s84, 8
	s_add_u32 s85, s85, 8
	s_add_u32 s86, s86, 8
	s_add_u32 s87, s87, 8
	s_and_b32 s80, s80, 63
	s_and_b32 s81, s81, 63
	s_and_b32 s82, s82, 63
	s_and_b32 s83, s83, 63
	s_and_b32 s84, s84, 63
	s_and_b32 s85, s85, 63
	s_and_b32 s86, s86, 63
	s_and_b32 s87, s87, 63
	s_add_u32 s12, s12, 1
	s_cmp_lt_u32 s12, 8
	s_cbranch_scc1 .Lvq_kA
	s_waitcnt vmcnt(0)
	global_load_dwordx4 v[128:131], v240, s[8:9]
	global_load_dwordx4 v[132:135], v240, s[8:9] offset:1024
	global_load_dwordx4 v[136:139], v240, s[8:9] offset:2048
	global_load_dwordx4 v[140:143], v240, s[8:9] offset:3072
	s_add_u32 s32, s62, 0
	s_addc_u32 s33, s63, 0
	s_add_u32 s34, s62, 4096
	s_addc_u32 s35, s63, 0
	s_add_u32 s36, s62, 8192
	s_addc_u32 s37, s63, 0
	s_add_u32 s38, s62, 12288
	s_addc_u32 s39, s63, 0
	s_waitcnt vmcnt(0)
	v_pk_add_f32 v[160:161], v[160:161], v[0:1]
	v_pk_add_f32 v[162:163], v[162:163], v[2:3]
	v_pk_add_f32 v[164:165], v[164:165], v[4:5]
	v_pk_add_f32 v[166:167], v[166:167], v[6:7]
	v_pk_add_f32 v[168:169], v[168:169], v[8:9]
	v_pk_add_f32 v[170:171], v[170:171], v[10:11]
	v_pk_add_f32 v[172:173], v[172:173], v[12:13]
	v_pk_add_f32 v[174:175], v[174:175], v[14:15]
	v_pk_mul_f32 v[224:225], v[160:161], v[160:161]
	v_pk_mul_f32 v[226:227], v[162:163], v[162:163]
	v_pk_fma_f32 v[224:225], v[164:165], v[164:165], v[224:225]
	v_pk_fma_f32 v[226:227], v[166:167], v[166:167], v[226:227]
	v_pk_fma_f32 v[224:225], v[168:169], v[168:169], v[224:225]
	v_pk_fma_f32 v[226:227], v[170:171], v[170:171], v[226:227]
	v_pk_fma_f32 v[224:225], v[172:173], v[172:173], v[224:225]
	v_pk_fma_f32 v[226:227], v[174:175], v[174:175], v[226:227]
	v_pk_add_f32 v[224:225], v[224:225], v[226:227]
	s_nop 0
	v_add_f32_e32 v224, v224, v225
	ds_bpermute_b32 v225, v242, v224
	s_waitcnt lgkmcnt(0)
	v_add_f32_e32 v224, v224, v225
	ds_bpermute_b32 v225, v243, v224
	s_waitcnt lgkmcnt(0)
	v_add_f32_e32 v224, v224, v225
	ds_bpermute_b32 v225, v244, v224
	s_waitcnt lgkmcnt(0)
	v_add_f32_e32 v224, v224, v225
	ds_bpermute_b32 v225, v245, v224
	s_waitcnt lgkmcnt(0)
	v_add_f32_e32 v224, v224, v225
	ds_bpermute_b32 v225, v246, v224
	s_waitcnt lgkmcnt(0)
	v_add_f32_e32 v224, v224, v225
	ds_bpermute_b32 v225, v247, v224
	s_waitcnt lgkmcnt(0)
	v_add_f32_e32 v224, v224, v225
	v_fmamk_f32 v224, v224, 0x3a800000, v248
	v_rsq_f32_e32 v224, v224
	s_nop 1
	v_pk_mul_f32 v[226:227], v[128:129], v[224:225] op_sel_hi:[1,0]
	v_pk_mul_f32 v[160:161], v[160:161], v[226:227]
	v_pk_mul_f32 v[228:229], v[130:131], v[224:225] op_sel_hi:[1,0]
	v_pk_mul_f32 v[162:163], v[162:163], v[228:229]
	v_pk_mul_f32 v[230:231], v[132:133], v[224:225] op_sel_hi:[1,0]
	v_pk_mul_f32 v[164:165], v[164:165], v[230:231]
	v_pk_mul_f32 v[232:233], v[134:135], v[224:225] op_sel_hi:[1,0]
	v_pk_mul_f32 v[166:167], v[166:167], v[232:233]
	v_pk_mul_f32 v[226:227], v[136:137], v[224:225] op_sel_hi:[1,0]
	v_pk_mul_f32 v[168:169], v[168:169], v[226:227]
	v_pk_mul_f32 v[228:229], v[138:139], v[224:225] op_sel_hi:[1,0]
	v_pk_mul_f32 v[170:171], v[170:171], v[228:229]
	v_pk_mul_f32 v[230:231], v[140:141], v[224:225] op_sel_hi:[1,0]
	v_pk_mul_f32 v[172:173], v[172:173], v[230:231]
	v_pk_mul_f32 v[232:233], v[142:143], v[224:225] op_sel_hi:[1,0]
	v_pk_mul_f32 v[174:175], v[174:175], v[232:233]
	v_pk_add_f32 v[176:177], v[176:177], v[16:17]
	v_pk_add_f32 v[178:179], v[178:179], v[18:19]
	v_pk_add_f32 v[180:181], v[180:181], v[20:21]
	v_pk_add_f32 v[182:183], v[182:183], v[22:23]
	v_pk_add_f32 v[184:185], v[184:185], v[24:25]
	v_pk_add_f32 v[186:187], v[186:187], v[26:27]
	v_pk_add_f32 v[188:189], v[188:189], v[28:29]
	v_pk_add_f32 v[190:191], v[190:191], v[30:31]
	v_pk_mul_f32 v[224:225], v[176:177], v[176:177]
	v_pk_mul_f32 v[226:227], v[178:179], v[178:179]
	v_pk_fma_f32 v[224:225], v[180:181], v[180:181], v[224:225]
	v_pk_fma_f32 v[226:227], v[182:183], v[182:183], v[226:227]
	v_pk_fma_f32 v[224:225], v[184:185], v[184:185], v[224:225]
	v_pk_fma_f32 v[226:227], v[186:187], v[186:187], v[226:227]
	v_pk_fma_f32 v[224:225], v[188:189], v[188:189], v[224:225]
	v_pk_fma_f32 v[226:227], v[190:191], v[190:191], v[226:227]
	v_pk_add_f32 v[224:225], v[224:225], v[226:227]
	s_nop 0
	v_add_f32_e32 v224, v224, v225
	ds_bpermute_b32 v225, v242, v224
	s_waitcnt lgkmcnt(0)
; DI void peer_item_v(const Params& p, int item) {
;     ...
;     float ss = 0.f;
; #pragma unroll
;     for (int i = 0; i < 4; ++i) {
;       y[i] = *(const float4*)(orow + 256 * i);
;       y[i].x += out[4 * i]; y[i].y += out[4 * i + 1]; y[i].z += out[4 * i + 2]; y[i].w += out[4 * i + 3];
;       ss += y[i].x * y[i].x + y[i].y * y[i].y + y[i].z * y[i].z + y[i].w * y[i].w;
;     }
;     ss = wave_sum(ss);
;     const float r = rsqrtf(ss * (1.f / 1024.f) + 1e-6f);
; #pragma unroll
;     for (int i = 0; i < 4; ++i) {
;       float4 g = *(const float4*)(p.g_final + 256 * i + lane * 4);
;       y[i].x *= r * g.x; y[i].y *= r * g.y; y[i].z *= r * g.z; y[i].w *= r * g.w;
;       *(float4*)(orow + 256 * i) = y[i];
	v_add_f32_e32 v224, v224, v225
	ds_bpermute_b32 v225, v243, v224
	s_waitcnt lgkmcnt(0)
	v_add_f32_e32 v224, v224, v225
	ds_bpermute_b32 v225, v244, v224
	s_waitcnt lgkmcnt(0)
	v_add_f32_e32 v224, v224, v225
	ds_bpermute_b32 v225, v245, v224
	s_waitcnt lgkmcnt(0)
	v_add_f32_e32 v224, v224, v225
	ds_bpermute_b32 v225, v246, v224
	s_waitcnt lgkmcnt(0)
	v_add_f32_e32 v224, v224, v225
	ds_bpermute_b32 v225, v247, v224
	s_waitcnt lgkmcnt(0)
	v_add_f32_e32 v224, v224, v225
	v_fmamk_f32 v224, v224, 0x3a800000, v248
	v_rsq_f32_e32 v224, v224
	s_nop 1
	v_pk_mul_f32 v[226:227], v[128:129], v[224:225] op_sel_hi:[1,0]
	v_pk_mul_f32 v[176:177], v[176:177], v[226:227]
	v_pk_mul_f32 v[228:229], v[130:131], v[224:225] op_sel_hi:[1,0]
	v_pk_mul_f32 v[178:179], v[178:179], v[228:229]
	v_pk_mul_f32 v[230:231], v[132:133], v[224:225] op_sel_hi:[1,0]
	v_pk_mul_f32 v[180:181], v[180:181], v[230:231]
	v_pk_mul_f32 v[232:233], v[134:135], v[224:225] op_sel_hi:[1,0]
	v_pk_mul_f32 v[182:183], v[182:183], v[232:233]
	v_pk_mul_f32 v[226:227], v[136:137], v[224:225] op_sel_hi:[1,0]
	v_pk_mul_f32 v[184:185], v[184:185], v[226:227]
	v_pk_mul_f32 v[228:229], v[138:139], v[224:225] op_sel_hi:[1,0]
	v_pk_mul_f32 v[186:187], v[186:187], v[228:229]
	v_pk_mul_f32 v[230:231], v[140:141], v[224:225] op_sel_hi:[1,0]
	v_pk_mul_f32 v[188:189], v[188:189], v[230:231]
	v_pk_mul_f32 v[232:233], v[142:143], v[224:225] op_sel_hi:[1,0]
	v_pk_mul_f32 v[190:191], v[190:191], v[232:233]
	v_pk_add_f32 v[192:193], v[192:193], v[32:33]
	v_pk_add_f32 v[194:195], v[194:195], v[34:35]
	v_pk_add_f32 v[196:197], v[196:197], v[36:37]
	v_pk_add_f32 v[198:199], v[198:199], v[38:39]
	v_pk_add_f32 v[200:201], v[200:201], v[40:41]
	v_pk_add_f32 v[202:203], v[202:203], v[42:43]
	v_pk_add_f32 v[204:205], v[204:205], v[44:45]
	v_pk_add_f32 v[206:207], v[206:207], v[46:47]
	v_pk_mul_f32 v[224:225], v[192:193], v[192:193]
	v_pk_mul_f32 v[226:227], v[194:195], v[194:195]
	v_pk_fma_f32 v[224:225], v[196:197], v[196:197], v[224:225]
	v_pk_fma_f32 v[226:227], v[198:199], v[198:199], v[226:227]
	v_pk_fma_f32 v[224:225], v[200:201], v[200:201], v[224:225]
	v_pk_fma_f32 v[226:227], v[202:203], v[202:203], v[226:227]
	v_pk_fma_f32 v[224:225], v[204:205], v[204:205], v[224:225]
	v_pk_fma_f32 v[226:227], v[206:207], v[206:207], v[226:227]
	v_pk_add_f32 v[224:225], v[224:225], v[226:227]
	s_nop 0
	v_add_f32_e32 v224, v224, v225
	ds_bpermute_b32 v225, v242, v224
	s_waitcnt lgkmcnt(0)
	v_add_f32_e32 v224, v224, v225
	ds_bpermute_b32 v225, v243, v224
	s_waitcnt lgkmcnt(0)
	v_add_f32_e32 v224, v224, v225
	ds_bpermute_b32 v225, v244, v224
	s_waitcnt lgkmcnt(0)
	v_add_f32_e32 v224, v224, v225
	ds_bpermute_b32 v225, v245, v224
	s_waitcnt lgkmcnt(0)
	v_add_f32_e32 v224, v224, v225
	ds_bpermute_b32 v225, v246, v224
	s_waitcnt lgkmcnt(0)
	v_add_f32_e32 v224, v224, v225
	ds_bpermute_b32 v225, v247, v224
	s_waitcnt lgkmcnt(0)
	v_add_f32_e32 v224, v224, v225
	v_fmamk_f32 v224, v224, 0x3a800000, v248
	v_rsq_f32_e32 v224, v224
	s_nop 1
	v_pk_mul_f32 v[226:227], v[128:129], v[224:225] op_sel_hi:[1,0]
	v_pk_mul_f32 v[192:193], v[192:193], v[226:227]
	v_pk_mul_f32 v[228:229], v[130:131], v[224:225] op_sel_hi:[1,0]
	v_pk_mul_f32 v[194:195], v[194:195], v[228:229]
	v_pk_mul_f32 v[230:231], v[132:133], v[224:225] op_sel_hi:[1,0]
	v_pk_mul_f32 v[196:197], v[196:197], v[230:231]
	v_pk_mul_f32 v[232:233], v[134:135], v[224:225] op_sel_hi:[1,0]
	v_pk_mul_f32 v[198:199], v[198:199], v[232:233]
	v_pk_mul_f32 v[226:227], v[136:137], v[224:225] op_sel_hi:[1,0]
	v_pk_mul_f32 v[200:201], v[200:201], v[226:227]
	v_pk_mul_f32 v[228:229], v[138:139], v[224:225] op_sel_hi:[1,0]
	v_pk_mul_f32 v[202:203], v[202:203], v[228:229]
	v_pk_mul_f32 v[230:231], v[140:141], v[224:225] op_sel_hi:[1,0]
	v_pk_mul_f32 v[204:205], v[204:205], v[230:231]
	v_pk_mul_f32 v[232:233], v[142:143], v[224:225] op_sel_hi:[1,0]
	v_pk_mul_f32 v[206:207], v[206:207], v[232:233]
	v_pk_add_f32 v[208:209], v[208:209], v[48:49]
	v_pk_add_f32 v[210:211], v[210:211], v[50:51]
	v_pk_add_f32 v[212:213], v[212:213], v[52:53]
	v_pk_add_f32 v[214:215], v[214:215], v[54:55]
	v_pk_add_f32 v[216:217], v[216:217], v[56:57]
	v_pk_add_f32 v[218:219], v[218:219], v[58:59]
	v_pk_add_f32 v[220:221], v[220:221], v[60:61]
	v_pk_add_f32 v[222:223], v[222:223], v[62:63]
	v_pk_mul_f32 v[224:225], v[208:209], v[208:209]
	v_pk_mul_f32 v[226:227], v[210:211], v[210:211]
	v_pk_fma_f32 v[224:225], v[212:213], v[212:213], v[224:225]
	v_pk_fma_f32 v[226:227], v[214:215], v[214:215], v[226:227]
	v_pk_fma_f32 v[224:225], v[216:217], v[216:217], v[224:225]
	v_pk_fma_f32 v[226:227], v[218:219], v[218:219], v[226:227]
	v_pk_fma_f32 v[224:225], v[220:221], v[220:221], v[224:225]
	v_pk_fma_f32 v[226:227], v[222:223], v[222:223], v[226:227]
	v_pk_add_f32 v[224:225], v[224:225], v[226:227]
	s_nop 0
	v_add_f32_e32 v224, v224, v225
	ds_bpermute_b32 v225, v242, v224
	s_waitcnt lgkmcnt(0)
	v_add_f32_e32 v224, v224, v225
	ds_bpermute_b32 v225, v243, v224
	s_waitcnt lgkmcnt(0)
	v_add_f32_e32 v224, v224, v225
	ds_bpermute_b32 v225, v244, v224
	s_waitcnt lgkmcnt(0)
	v_add_f32_e32 v224, v224, v225
	ds_bpermute_b32 v225, v245, v224
	s_waitcnt lgkmcnt(0)
	v_add_f32_e32 v224, v224, v225
	ds_bpermute_b32 v225, v246, v224
	s_waitcnt lgkmcnt(0)
	v_add_f32_e32 v224, v224, v225
	ds_bpermute_b32 v225, v247, v224
	s_waitcnt lgkmcnt(0)
; DI void peer_item_v(const Params& p, int item) {
;     ...
;     float out[16];
; #pragma unroll
;     for (int i = 0; i < 16; ++i) out[i] = 0.f;
;     u32x4 vqa[8], vqb[8];
;     ...
;     const float r = rsqrtf(ss * (1.f / 1024.f) + 1e-6f);
; #pragma unroll
;     for (int i = 0; i < 4; ++i) {
;       float4 g = *(const float4*)(p.g_final + 256 * i + lane * 4);
;       y[i].x *= r * g.x; y[i].y *= r * g.y; y[i].z *= r * g.z; y[i].w *= r * g.w;
;       *(float4*)(orow + 256 * i) = y[i];
;     }
	v_add_f32_e32 v224, v224, v225
	v_fmamk_f32 v224, v224, 0x3a800000, v248
	v_rsq_f32_e32 v224, v224
	s_nop 1
	v_pk_mul_f32 v[226:227], v[128:129], v[224:225] op_sel_hi:[1,0]
	v_pk_mul_f32 v[208:209], v[208:209], v[226:227]
	v_pk_mul_f32 v[228:229], v[130:131], v[224:225] op_sel_hi:[1,0]
	v_pk_mul_f32 v[210:211], v[210:211], v[228:229]
	v_pk_mul_f32 v[230:231], v[132:133], v[224:225] op_sel_hi:[1,0]
	v_pk_mul_f32 v[212:213], v[212:213], v[230:231]
	v_pk_mul_f32 v[232:233], v[134:135], v[224:225] op_sel_hi:[1,0]
	v_pk_mul_f32 v[214:215], v[214:215], v[232:233]
	v_pk_mul_f32 v[226:227], v[136:137], v[224:225] op_sel_hi:[1,0]
	v_pk_mul_f32 v[216:217], v[216:217], v[226:227]
	v_pk_mul_f32 v[228:229], v[138:139], v[224:225] op_sel_hi:[1,0]
	v_pk_mul_f32 v[218:219], v[218:219], v[228:229]
	v_pk_mul_f32 v[230:231], v[140:141], v[224:225] op_sel_hi:[1,0]
	v_pk_mul_f32 v[220:221], v[220:221], v[230:231]
	v_pk_mul_f32 v[232:233], v[142:143], v[224:225] op_sel_hi:[1,0]
	v_pk_mul_f32 v[222:223], v[222:223], v[232:233]
	global_store_dwordx4 v240, v[160:163], s[32:33]
	global_store_dwordx4 v240, v[164:167], s[32:33] offset:1024
	global_store_dwordx4 v240, v[168:171], s[32:33] offset:2048
	global_store_dwordx4 v240, v[172:175], s[32:33] offset:3072
	global_store_dwordx4 v240, v[176:179], s[34:35]
	global_store_dwordx4 v240, v[180:183], s[34:35] offset:1024
	global_store_dwordx4 v240, v[184:187], s[34:35] offset:2048
	global_store_dwordx4 v240, v[188:191], s[34:35] offset:3072
	global_store_dwordx4 v240, v[192:195], s[36:37]
	global_store_dwordx4 v240, v[196:199], s[36:37] offset:1024
	global_store_dwordx4 v240, v[200:203], s[36:37] offset:2048
	global_store_dwordx4 v240, v[204:207], s[36:37] offset:3072
	global_store_dwordx4 v240, v[208:211], s[38:39]
	global_store_dwordx4 v240, v[212:215], s[38:39] offset:1024
	global_store_dwordx4 v240, v[216:219], s[38:39] offset:2048
	global_store_dwordx4 v240, v[220:223], s[38:39] offset:3072
	s_nop 1
	v_mov_b32_e32 v64, 0
	v_mov_b32_e32 v65, 0
	v_mov_b32_e32 v66, 0
	v_mov_b32_e32 v67, 0
	v_mov_b32_e32 v68, 0
	v_mov_b32_e32 v69, 0
	v_mov_b32_e32 v70, 0
	v_mov_b32_e32 v71, 0
	v_mov_b32_e32 v72, 0
	v_mov_b32_e32 v73, 0
	v_mov_b32_e32 v74, 0
	v_mov_b32_e32 v75, 0
	v_mov_b32_e32 v76, 0
	v_mov_b32_e32 v77, 0
	v_mov_b32_e32 v78, 0
	v_mov_b32_e32 v79, 0
	v_mov_b32_e32 v80, 0
	v_mov_b32_e32 v81, 0
	v_mov_b32_e32 v82, 0
	v_mov_b32_e32 v83, 0
	v_mov_b32_e32 v84, 0
	v_mov_b32_e32 v85, 0
	v_mov_b32_e32 v86, 0
	v_mov_b32_e32 v87, 0
	v_mov_b32_e32 v88, 0
	v_mov_b32_e32 v89, 0
	v_mov_b32_e32 v90, 0
	v_mov_b32_e32 v91, 0
	v_mov_b32_e32 v92, 0
	v_mov_b32_e32 v93, 0
	v_mov_b32_e32 v94, 0
	v_mov_b32_e32 v95, 0
	v_mov_b32_e32 v96, 0
	v_mov_b32_e32 v97, 0
	v_mov_b32_e32 v98, 0
	v_mov_b32_e32 v99, 0
	v_mov_b32_e32 v100, 0
	v_mov_b32_e32 v101, 0
	v_mov_b32_e32 v102, 0
	v_mov_b32_e32 v103, 0
	v_mov_b32_e32 v104, 0
	v_mov_b32_e32 v105, 0
	v_mov_b32_e32 v106, 0
	v_mov_b32_e32 v107, 0
	v_mov_b32_e32 v108, 0
	v_mov_b32_e32 v109, 0
	v_mov_b32_e32 v110, 0
	v_mov_b32_e32 v111, 0
	v_mov_b32_e32 v112, 0
	v_mov_b32_e32 v113, 0
	v_mov_b32_e32 v114, 0
	v_mov_b32_e32 v115, 0
	v_mov_b32_e32 v116, 0
	v_mov_b32_e32 v117, 0
	v_mov_b32_e32 v118, 0
	v_mov_b32_e32 v119, 0
	v_mov_b32_e32 v120, 0
	v_mov_b32_e32 v121, 0
	v_mov_b32_e32 v122, 0
	v_mov_b32_e32 v123, 0
	v_mov_b32_e32 v124, 0
	v_mov_b32_e32 v125, 0
	v_mov_b32_e32 v126, 0
	v_mov_b32_e32 v127, 0
	s_add_u32 s88, s62, 16384
	s_addc_u32 s89, s63, 0
	s_add_u32 s90, s62, 20480
	s_addc_u32 s91, s63, 0
	s_add_u32 s92, s62, 24576
	s_addc_u32 s93, s63, 0
	s_add_u32 s94, s62, 28672
	s_addc_u32 s95, s63, 0
	s_mov_b32 s72, 0
	s_mov_b32 s73, 1
	s_mov_b32 s74, 2
	s_mov_b32 s75, 3
	s_mov_b32 s76, 4
	s_mov_b32 s77, 5
	s_mov_b32 s78, 6
	s_mov_b32 s79, 7
	s_mov_b32 s80, 8
	s_mov_b32 s81, 9
	s_mov_b32 s82, 10
	s_mov_b32 s83, 11
	s_mov_b32 s84, 12
	s_mov_b32 s85, 13
	s_mov_b32 s86, 14
	s_mov_b32 s87, 15
	s_nop 0
	v_readlane_b32 s48, v144, s72
	v_readlane_b32 s49, v144, s73
	v_readlane_b32 s50, v144, s74
	v_readlane_b32 s51, v144, s75
	v_readlane_b32 s52, v144, s76
	v_readlane_b32 s53, v144, s77
	v_readlane_b32 s54, v144, s78
	v_readlane_b32 s55, v144, s79
	s_add_u32 s32, s0, s48
	s_addc_u32 s33, s1, 0
	s_add_u32 s34, s0, s49
	s_addc_u32 s35, s1, 0
	s_add_u32 s36, s0, s50
	s_addc_u32 s37, s1, 0
	s_add_u32 s38, s0, s51
	s_addc_u32 s39, s1, 0
	s_add_u32 s40, s0, s52
	s_addc_u32 s41, s1, 0
	s_add_u32 s42, s0, s53
	s_addc_u32 s43, s1, 0
	s_add_u32 s44, s0, s54
	s_addc_u32 s45, s1, 0
	s_add_u32 s46, s0, s55
	s_addc_u32 s47, s1, 0
	global_load_dwordx4 v[160:163], v240, s[32:33]
	global_load_dwordx4 v[164:167], v240, s[34:35]
	global_load_dwordx4 v[168:171], v240, s[36:37]
	global_load_dwordx4 v[172:175], v240, s[38:39]
	global_load_dwordx4 v[176:179], v240, s[40:41]
	global_load_dwordx4 v[180:183], v240, s[42:43]
	global_load_dwordx4 v[184:187], v240, s[44:45]
	global_load_dwordx4 v[188:191], v240, s[46:47]
	v_readlane_b32 s48, v148, s72
	v_readlane_b32 s49, v148, s73
	v_readlane_b32 s50, v148, s74
	v_readlane_b32 s51, v148, s75
	v_readlane_b32 s52, v148, s76
	v_readlane_b32 s53, v148, s77
	v_readlane_b32 s54, v148, s78
	v_readlane_b32 s55, v148, s79
	s_add_u32 s32, s0, s48
	s_addc_u32 s33, s1, 0
	s_add_u32 s34, s0, s49
	s_addc_u32 s35, s1, 0
	s_add_u32 s36, s0, s50
	s_addc_u32 s37, s1, 0
	s_add_u32 s38, s0, s51
	s_addc_u32 s39, s1, 0
	s_add_u32 s40, s0, s52
	s_addc_u32 s41, s1, 0
	s_add_u32 s42, s0, s53
	s_addc_u32 s43, s1, 0
	s_add_u32 s44, s0, s54
	s_addc_u32 s45, s1, 0
	s_add_u32 s46, s0, s55
	s_addc_u32 s47, s1, 0
	global_load_dwordx4 v[192:195], v240, s[32:33]
	global_load_dwordx4 v[196:199], v240, s[34:35]
	global_load_dwordx4 v[200:203], v240, s[36:37]
	global_load_dwordx4 v[204:207], v240, s[38:39]
	global_load_dwordx4 v[208:211], v240, s[40:41]
	global_load_dwordx4 v[212:215], v240, s[42:43]
	global_load_dwordx4 v[216:219], v240, s[44:45]
	global_load_dwordx4 v[220:223], v240, s[46:47]
	v_readlane_b32 s48, v152, s72
	v_readlane_b32 s49, v152, s73
	v_readlane_b32 s50, v152, s74
	v_readlane_b32 s51, v152, s75
	v_readlane_b32 s52, v152, s76
	v_readlane_b32 s53, v152, s77
	v_readlane_b32 s54, v152, s78
	v_readlane_b32 s55, v152, s79
	s_add_u32 s32, s0, s48
	s_addc_u32 s33, s1, 0
	s_add_u32 s34, s0, s49
	s_addc_u32 s35, s1, 0
	s_add_u32 s36, s0, s50
	s_addc_u32 s37, s1, 0
	s_add_u32 s38, s0, s51
	s_addc_u32 s39, s1, 0
	s_add_u32 s40, s0, s52
	s_addc_u32 s41, s1, 0
	s_add_u32 s42, s0, s53
	s_addc_u32 s43, s1, 0
	s_add_u32 s44, s0, s54
	s_addc_u32 s45, s1, 0
	s_add_u32 s46, s0, s55
	s_addc_u32 s47, s1, 0
	global_load_dwordx4 v[0:3], v240, s[32:33]
	global_load_dwordx4 v[4:7], v240, s[34:35]
	global_load_dwordx4 v[8:11], v240, s[36:37]
	global_load_dwordx4 v[12:15], v240, s[38:39]
	global_load_dwordx4 v[16:19], v240, s[40:41]
	global_load_dwordx4 v[20:23], v240, s[42:43]
	global_load_dwordx4 v[24:27], v240, s[44:45]
	global_load_dwordx4 v[28:31], v240, s[46:47]
	s_mov_b32 s12, 0
; DI void peer_item_v(const Params& p, int item) {
;     ...
;     V_ISSUE(vqa, 0)
; #pragma unroll 1
;     for (int g = 0; g < 16; g += 2) {
;       V_ISSUE(vqb, g + 1)
;       V_CONSUME(vqa, g)
;       if (g + 2 < 16) V_ISSUE(vqa, g + 2)
;       V_CONSUME(vqb, g + 1)
;     }
.Lvq_kB:
	v_readlane_b32 s16, v146, s72
	v_readlane_b32 s18, v146, s73
	v_readlane_b32 s20, v146, s74
	v_readlane_b32 s22, v146, s75
	v_readlane_b32 s24, v146, s76
	v_readlane_b32 s26, v146, s77
	v_readlane_b32 s28, v146, s78
	v_readlane_b32 s30, v146, s79
	v_readlane_b32 s48, v156, s72
	v_readlane_b32 s49, v156, s73
	v_readlane_b32 s50, v156, s74
	v_readlane_b32 s51, v156, s75
	v_readlane_b32 s52, v156, s76
	v_readlane_b32 s53, v156, s77
	v_readlane_b32 s54, v156, s78
	v_readlane_b32 s55, v156, s79
	s_add_u32 s32, s0, s48
	s_addc_u32 s33, s1, 0
	s_add_u32 s34, s0, s49
	s_addc_u32 s35, s1, 0
	s_add_u32 s36, s0, s50
	s_addc_u32 s37, s1, 0
	s_add_u32 s38, s0, s51
	s_addc_u32 s39, s1, 0
	s_add_u32 s40, s0, s52
	s_addc_u32 s41, s1, 0
	s_add_u32 s42, s0, s53
	s_addc_u32 s43, s1, 0
	s_add_u32 s44, s0, s54
	s_addc_u32 s45, s1, 0
	s_add_u32 s46, s0, s55
	s_addc_u32 s47, s1, 0
	global_load_dwordx4 v[32:35], v240, s[32:33]
	global_load_dwordx4 v[36:39], v240, s[34:35]
	global_load_dwordx4 v[40:43], v240, s[36:37]
	global_load_dwordx4 v[44:47], v240, s[38:39]
	global_load_dwordx4 v[48:51], v240, s[40:41]
	global_load_dwordx4 v[52:55], v240, s[42:43]
	global_load_dwordx4 v[56:59], v240, s[44:45]
	global_load_dwordx4 v[60:63], v240, s[46:47]
	s_waitcnt vmcnt(24)
	v_cvt_pk_f32_fp8_e32 v[224:225], v160
	v_cvt_pk_f32_fp8_sdwa v[226:227], v160 src0_sel:WORD_1
	v_cvt_pk_f32_fp8_e32 v[228:229], v161
	v_cvt_pk_f32_fp8_sdwa v[230:231], v161 src0_sel:WORD_1
	v_cvt_pk_f32_fp8_e32 v[232:233], v162
	v_cvt_pk_f32_fp8_sdwa v[234:235], v162 src0_sel:WORD_1
	v_cvt_pk_f32_fp8_e32 v[236:237], v163
	v_cvt_pk_f32_fp8_sdwa v[238:239], v163 src0_sel:WORD_1
	v_pk_fma_f32 v[64:65], v[224:225], s[16:17], v[64:65] op_sel_hi:[1,0,1]
	v_pk_fma_f32 v[66:67], v[226:227], s[16:17], v[66:67] op_sel_hi:[1,0,1]
	v_pk_fma_f32 v[68:69], v[228:229], s[16:17], v[68:69] op_sel_hi:[1,0,1]
	v_pk_fma_f32 v[70:71], v[230:231], s[16:17], v[70:71] op_sel_hi:[1,0,1]
	v_pk_fma_f32 v[72:73], v[232:233], s[16:17], v[72:73] op_sel_hi:[1,0,1]
	v_pk_fma_f32 v[74:75], v[234:235], s[16:17], v[74:75] op_sel_hi:[1,0,1]
	v_pk_fma_f32 v[76:77], v[236:237], s[16:17], v[76:77] op_sel_hi:[1,0,1]
	v_pk_fma_f32 v[78:79], v[238:239], s[16:17], v[78:79] op_sel_hi:[1,0,1]
	v_cvt_pk_f32_fp8_e32 v[224:225], v164
	v_cvt_pk_f32_fp8_sdwa v[226:227], v164 src0_sel:WORD_1
	v_cvt_pk_f32_fp8_e32 v[228:229], v165
	v_cvt_pk_f32_fp8_sdwa v[230:231], v165 src0_sel:WORD_1
	v_cvt_pk_f32_fp8_e32 v[232:233], v166
	v_cvt_pk_f32_fp8_sdwa v[234:235], v166 src0_sel:WORD_1
	v_cvt_pk_f32_fp8_e32 v[236:237], v167
	v_cvt_pk_f32_fp8_sdwa v[238:239], v167 src0_sel:WORD_1
	v_pk_fma_f32 v[64:65], v[224:225], s[18:19], v[64:65] op_sel_hi:[1,0,1]
	v_pk_fma_f32 v[66:67], v[226:227], s[18:19], v[66:67] op_sel_hi:[1,0,1]
	v_pk_fma_f32 v[68:69], v[228:229], s[18:19], v[68:69] op_sel_hi:[1,0,1]
	v_pk_fma_f32 v[70:71], v[230:231], s[18:19], v[70:71] op_sel_hi:[1,0,1]
	v_pk_fma_f32 v[72:73], v[232:233], s[18:19], v[72:73] op_sel_hi:[1,0,1]
	v_pk_fma_f32 v[74:75], v[234:235], s[18:19], v[74:75] op_sel_hi:[1,0,1]
	v_pk_fma_f32 v[76:77], v[236:237], s[18:19], v[76:77] op_sel_hi:[1,0,1]
	v_pk_fma_f32 v[78:79], v[238:239], s[18:19], v[78:79] op_sel_hi:[1,0,1]
	v_cvt_pk_f32_fp8_e32 v[224:225], v168
	v_cvt_pk_f32_fp8_sdwa v[226:227], v168 src0_sel:WORD_1
	v_cvt_pk_f32_fp8_e32 v[228:229], v169
	v_cvt_pk_f32_fp8_sdwa v[230:231], v169 src0_sel:WORD_1
	v_cvt_pk_f32_fp8_e32 v[232:233], v170
	v_cvt_pk_f32_fp8_sdwa v[234:235], v170 src0_sel:WORD_1
	v_cvt_pk_f32_fp8_e32 v[236:237], v171
	v_cvt_pk_f32_fp8_sdwa v[238:239], v171 src0_sel:WORD_1
	v_pk_fma_f32 v[64:65], v[224:225], s[20:21], v[64:65] op_sel_hi:[1,0,1]
	v_pk_fma_f32 v[66:67], v[226:227], s[20:21], v[66:67] op_sel_hi:[1,0,1]
	v_pk_fma_f32 v[68:69], v[228:229], s[20:21], v[68:69] op_sel_hi:[1,0,1]
	v_pk_fma_f32 v[70:71], v[230:231], s[20:21], v[70:71] op_sel_hi:[1,0,1]
	v_pk_fma_f32 v[72:73], v[232:233], s[20:21], v[72:73] op_sel_hi:[1,0,1]
	v_pk_fma_f32 v[74:75], v[234:235], s[20:21], v[74:75] op_sel_hi:[1,0,1]
	v_pk_fma_f32 v[76:77], v[236:237], s[20:21], v[76:77] op_sel_hi:[1,0,1]
	v_pk_fma_f32 v[78:79], v[238:239], s[20:21], v[78:79] op_sel_hi:[1,0,1]
	v_cvt_pk_f32_fp8_e32 v[224:225], v172
	v_cvt_pk_f32_fp8_sdwa v[226:227], v172 src0_sel:WORD_1
	v_cvt_pk_f32_fp8_e32 v[228:229], v173
	v_cvt_pk_f32_fp8_sdwa v[230:231], v173 src0_sel:WORD_1
	v_cvt_pk_f32_fp8_e32 v[232:233], v174
	v_cvt_pk_f32_fp8_sdwa v[234:235], v174 src0_sel:WORD_1
	v_cvt_pk_f32_fp8_e32 v[236:237], v175
	v_cvt_pk_f32_fp8_sdwa v[238:239], v175 src0_sel:WORD_1
	v_pk_fma_f32 v[64:65], v[224:225], s[22:23], v[64:65] op_sel_hi:[1,0,1]
	v_pk_fma_f32 v[66:67], v[226:227], s[22:23], v[66:67] op_sel_hi:[1,0,1]
	v_pk_fma_f32 v[68:69], v[228:229], s[22:23], v[68:69] op_sel_hi:[1,0,1]
	v_pk_fma_f32 v[70:71], v[230:231], s[22:23], v[70:71] op_sel_hi:[1,0,1]
	v_pk_fma_f32 v[72:73], v[232:233], s[22:23], v[72:73] op_sel_hi:[1,0,1]
	v_pk_fma_f32 v[74:75], v[234:235], s[22:23], v[74:75] op_sel_hi:[1,0,1]
	v_pk_fma_f32 v[76:77], v[236:237], s[22:23], v[76:77] op_sel_hi:[1,0,1]
	v_pk_fma_f32 v[78:79], v[238:239], s[22:23], v[78:79] op_sel_hi:[1,0,1]
	v_cvt_pk_f32_fp8_e32 v[224:225], v176
	v_cvt_pk_f32_fp8_sdwa v[226:227], v176 src0_sel:WORD_1
	v_cvt_pk_f32_fp8_e32 v[228:229], v177
	v_cvt_pk_f32_fp8_sdwa v[230:231], v177 src0_sel:WORD_1
	v_cvt_pk_f32_fp8_e32 v[232:233], v178
	v_cvt_pk_f32_fp8_sdwa v[234:235], v178 src0_sel:WORD_1
	v_cvt_pk_f32_fp8_e32 v[236:237], v179
	v_cvt_pk_f32_fp8_sdwa v[238:239], v179 src0_sel:WORD_1
	v_pk_fma_f32 v[64:65], v[224:225], s[24:25], v[64:65] op_sel_hi:[1,0,1]
	v_pk_fma_f32 v[66:67], v[226:227], s[24:25], v[66:67] op_sel_hi:[1,0,1]
; DI void peer_item_v(const Params& p, int item) {
;     ...
;     V_ISSUE(vqa, 0)
; #pragma unroll 1
;     for (int g = 0; g < 16; g += 2) {
;       V_ISSUE(vqb, g + 1)
;       V_CONSUME(vqa, g)
;       if (g + 2 < 16) V_ISSUE(vqa, g + 2)
;       V_CONSUME(vqb, g + 1)
;     }
	v_pk_fma_f32 v[68:69], v[228:229], s[24:25], v[68:69] op_sel_hi:[1,0,1]
	v_pk_fma_f32 v[70:71], v[230:231], s[24:25], v[70:71] op_sel_hi:[1,0,1]
	v_pk_fma_f32 v[72:73], v[232:233], s[24:25], v[72:73] op_sel_hi:[1,0,1]
	v_pk_fma_f32 v[74:75], v[234:235], s[24:25], v[74:75] op_sel_hi:[1,0,1]
	v_pk_fma_f32 v[76:77], v[236:237], s[24:25], v[76:77] op_sel_hi:[1,0,1]
	v_pk_fma_f32 v[78:79], v[238:239], s[24:25], v[78:79] op_sel_hi:[1,0,1]
	v_cvt_pk_f32_fp8_e32 v[224:225], v180
	v_cvt_pk_f32_fp8_sdwa v[226:227], v180 src0_sel:WORD_1
	v_cvt_pk_f32_fp8_e32 v[228:229], v181
	v_cvt_pk_f32_fp8_sdwa v[230:231], v181 src0_sel:WORD_1
	v_cvt_pk_f32_fp8_e32 v[232:233], v182
	v_cvt_pk_f32_fp8_sdwa v[234:235], v182 src0_sel:WORD_1
	v_cvt_pk_f32_fp8_e32 v[236:237], v183
	v_cvt_pk_f32_fp8_sdwa v[238:239], v183 src0_sel:WORD_1
	v_pk_fma_f32 v[64:65], v[224:225], s[26:27], v[64:65] op_sel_hi:[1,0,1]
	v_pk_fma_f32 v[66:67], v[226:227], s[26:27], v[66:67] op_sel_hi:[1,0,1]
	v_pk_fma_f32 v[68:69], v[228:229], s[26:27], v[68:69] op_sel_hi:[1,0,1]
	v_pk_fma_f32 v[70:71], v[230:231], s[26:27], v[70:71] op_sel_hi:[1,0,1]
	v_pk_fma_f32 v[72:73], v[232:233], s[26:27], v[72:73] op_sel_hi:[1,0,1]
	v_pk_fma_f32 v[74:75], v[234:235], s[26:27], v[74:75] op_sel_hi:[1,0,1]
	v_pk_fma_f32 v[76:77], v[236:237], s[26:27], v[76:77] op_sel_hi:[1,0,1]
	v_pk_fma_f32 v[78:79], v[238:239], s[26:27], v[78:79] op_sel_hi:[1,0,1]
	v_cvt_pk_f32_fp8_e32 v[224:225], v184
	v_cvt_pk_f32_fp8_sdwa v[226:227], v184 src0_sel:WORD_1
	v_cvt_pk_f32_fp8_e32 v[228:229], v185
	v_cvt_pk_f32_fp8_sdwa v[230:231], v185 src0_sel:WORD_1
	v_cvt_pk_f32_fp8_e32 v[232:233], v186
	v_cvt_pk_f32_fp8_sdwa v[234:235], v186 src0_sel:WORD_1
	v_cvt_pk_f32_fp8_e32 v[236:237], v187
	v_cvt_pk_f32_fp8_sdwa v[238:239], v187 src0_sel:WORD_1
	v_pk_fma_f32 v[64:65], v[224:225], s[28:29], v[64:65] op_sel_hi:[1,0,1]
	v_pk_fma_f32 v[66:67], v[226:227], s[28:29], v[66:67] op_sel_hi:[1,0,1]
	v_pk_fma_f32 v[68:69], v[228:229], s[28:29], v[68:69] op_sel_hi:[1,0,1]
	v_pk_fma_f32 v[70:71], v[230:231], s[28:29], v[70:71] op_sel_hi:[1,0,1]
	v_pk_fma_f32 v[72:73], v[232:233], s[28:29], v[72:73] op_sel_hi:[1,0,1]
	v_pk_fma_f32 v[74:75], v[234:235], s[28:29], v[74:75] op_sel_hi:[1,0,1]
	v_pk_fma_f32 v[76:77], v[236:237], s[28:29], v[76:77] op_sel_hi:[1,0,1]
	v_pk_fma_f32 v[78:79], v[238:239], s[28:29], v[78:79] op_sel_hi:[1,0,1]
	v_cvt_pk_f32_fp8_e32 v[224:225], v188
	v_cvt_pk_f32_fp8_sdwa v[226:227], v188 src0_sel:WORD_1
	v_cvt_pk_f32_fp8_e32 v[228:229], v189
	v_cvt_pk_f32_fp8_sdwa v[230:231], v189 src0_sel:WORD_1
	v_cvt_pk_f32_fp8_e32 v[232:233], v190
	v_cvt_pk_f32_fp8_sdwa v[234:235], v190 src0_sel:WORD_1
	v_cvt_pk_f32_fp8_e32 v[236:237], v191
	v_cvt_pk_f32_fp8_sdwa v[238:239], v191 src0_sel:WORD_1
	v_pk_fma_f32 v[64:65], v[224:225], s[30:31], v[64:65] op_sel_hi:[1,0,1]
	v_pk_fma_f32 v[66:67], v[226:227], s[30:31], v[66:67] op_sel_hi:[1,0,1]
	v_pk_fma_f32 v[68:69], v[228:229], s[30:31], v[68:69] op_sel_hi:[1,0,1]
	v_pk_fma_f32 v[70:71], v[230:231], s[30:31], v[70:71] op_sel_hi:[1,0,1]
	v_pk_fma_f32 v[72:73], v[232:233], s[30:31], v[72:73] op_sel_hi:[1,0,1]
	v_pk_fma_f32 v[74:75], v[234:235], s[30:31], v[74:75] op_sel_hi:[1,0,1]
	v_pk_fma_f32 v[76:77], v[236:237], s[30:31], v[76:77] op_sel_hi:[1,0,1]
	v_pk_fma_f32 v[78:79], v[238:239], s[30:31], v[78:79] op_sel_hi:[1,0,1]
	v_readlane_b32 s16, v150, s72
	v_readlane_b32 s18, v150, s73
	v_readlane_b32 s20, v150, s74
	v_readlane_b32 s22, v150, s75
	v_readlane_b32 s24, v150, s76
	v_readlane_b32 s26, v150, s77
	v_readlane_b32 s28, v150, s78
	v_readlane_b32 s30, v150, s79
	v_readlane_b32 s48, v145, s72
	v_readlane_b32 s49, v145, s73
	v_readlane_b32 s50, v145, s74
	v_readlane_b32 s51, v145, s75
	v_readlane_b32 s52, v145, s76
	v_readlane_b32 s53, v145, s77
	v_readlane_b32 s54, v145, s78
	v_readlane_b32 s55, v145, s79
	s_add_u32 s32, s0, s48
	s_addc_u32 s33, s1, 0
	s_add_u32 s34, s0, s49
	s_addc_u32 s35, s1, 0
	s_add_u32 s36, s0, s50
	s_addc_u32 s37, s1, 0
	s_add_u32 s38, s0, s51
	s_addc_u32 s39, s1, 0
	s_add_u32 s40, s0, s52
	s_addc_u32 s41, s1, 0
	s_add_u32 s42, s0, s53
	s_addc_u32 s43, s1, 0
	s_add_u32 s44, s0, s54
	s_addc_u32 s45, s1, 0
	s_add_u32 s46, s0, s55
	s_addc_u32 s47, s1, 0
	global_load_dwordx4 v[160:163], v240, s[32:33]
	global_load_dwordx4 v[164:167], v240, s[34:35]
	global_load_dwordx4 v[168:171], v240, s[36:37]
	global_load_dwordx4 v[172:175], v240, s[38:39]
	global_load_dwordx4 v[176:179], v240, s[40:41]
	global_load_dwordx4 v[180:183], v240, s[42:43]
	global_load_dwordx4 v[184:187], v240, s[44:45]
	global_load_dwordx4 v[188:191], v240, s[46:47]
	s_waitcnt vmcnt(24)
; DI void peer_item_v(const Params& p, int item) {
;     ...
;     V_ISSUE(vqa, 0)
; #pragma unroll 1
;     for (int g = 0; g < 16; g += 2) {
;       V_ISSUE(vqb, g + 1)
;       V_CONSUME(vqa, g)
;       if (g + 2 < 16) V_ISSUE(vqa, g + 2)
;       V_CONSUME(vqb, g + 1)
;     }
	v_cvt_pk_f32_fp8_e32 v[224:225], v192
	v_cvt_pk_f32_fp8_sdwa v[226:227], v192 src0_sel:WORD_1
	v_cvt_pk_f32_fp8_e32 v[228:229], v193
	v_cvt_pk_f32_fp8_sdwa v[230:231], v193 src0_sel:WORD_1
	v_cvt_pk_f32_fp8_e32 v[232:233], v194
	v_cvt_pk_f32_fp8_sdwa v[234:235], v194 src0_sel:WORD_1
	v_cvt_pk_f32_fp8_e32 v[236:237], v195
	v_cvt_pk_f32_fp8_sdwa v[238:239], v195 src0_sel:WORD_1
	v_pk_fma_f32 v[80:81], v[224:225], s[16:17], v[80:81] op_sel_hi:[1,0,1]
	v_pk_fma_f32 v[82:83], v[226:227], s[16:17], v[82:83] op_sel_hi:[1,0,1]
	v_pk_fma_f32 v[84:85], v[228:229], s[16:17], v[84:85] op_sel_hi:[1,0,1]
	v_pk_fma_f32 v[86:87], v[230:231], s[16:17], v[86:87] op_sel_hi:[1,0,1]
	v_pk_fma_f32 v[88:89], v[232:233], s[16:17], v[88:89] op_sel_hi:[1,0,1]
	v_pk_fma_f32 v[90:91], v[234:235], s[16:17], v[90:91] op_sel_hi:[1,0,1]
	v_pk_fma_f32 v[92:93], v[236:237], s[16:17], v[92:93] op_sel_hi:[1,0,1]
	v_pk_fma_f32 v[94:95], v[238:239], s[16:17], v[94:95] op_sel_hi:[1,0,1]
	v_cvt_pk_f32_fp8_e32 v[224:225], v196
	v_cvt_pk_f32_fp8_sdwa v[226:227], v196 src0_sel:WORD_1
	v_cvt_pk_f32_fp8_e32 v[228:229], v197
	v_cvt_pk_f32_fp8_sdwa v[230:231], v197 src0_sel:WORD_1
	v_cvt_pk_f32_fp8_e32 v[232:233], v198
	v_cvt_pk_f32_fp8_sdwa v[234:235], v198 src0_sel:WORD_1
	v_cvt_pk_f32_fp8_e32 v[236:237], v199
	v_cvt_pk_f32_fp8_sdwa v[238:239], v199 src0_sel:WORD_1
	v_pk_fma_f32 v[80:81], v[224:225], s[18:19], v[80:81] op_sel_hi:[1,0,1]
	v_pk_fma_f32 v[82:83], v[226:227], s[18:19], v[82:83] op_sel_hi:[1,0,1]
	v_pk_fma_f32 v[84:85], v[228:229], s[18:19], v[84:85] op_sel_hi:[1,0,1]
	v_pk_fma_f32 v[86:87], v[230:231], s[18:19], v[86:87] op_sel_hi:[1,0,1]
	v_pk_fma_f32 v[88:89], v[232:233], s[18:19], v[88:89] op_sel_hi:[1,0,1]
	v_pk_fma_f32 v[90:91], v[234:235], s[18:19], v[90:91] op_sel_hi:[1,0,1]
	v_pk_fma_f32 v[92:93], v[236:237], s[18:19], v[92:93] op_sel_hi:[1,0,1]
	v_pk_fma_f32 v[94:95], v[238:239], s[18:19], v[94:95] op_sel_hi:[1,0,1]
	v_cvt_pk_f32_fp8_e32 v[224:225], v200
	v_cvt_pk_f32_fp8_sdwa v[226:227], v200 src0_sel:WORD_1
	v_cvt_pk_f32_fp8_e32 v[228:229], v201
	v_cvt_pk_f32_fp8_sdwa v[230:231], v201 src0_sel:WORD_1
	v_cvt_pk_f32_fp8_e32 v[232:233], v202
	v_cvt_pk_f32_fp8_sdwa v[234:235], v202 src0_sel:WORD_1
	v_cvt_pk_f32_fp8_e32 v[236:237], v203
	v_cvt_pk_f32_fp8_sdwa v[238:239], v203 src0_sel:WORD_1
	v_pk_fma_f32 v[80:81], v[224:225], s[20:21], v[80:81] op_sel_hi:[1,0,1]
	v_pk_fma_f32 v[82:83], v[226:227], s[20:21], v[82:83] op_sel_hi:[1,0,1]
	v_pk_fma_f32 v[84:85], v[228:229], s[20:21], v[84:85] op_sel_hi:[1,0,1]
	v_pk_fma_f32 v[86:87], v[230:231], s[20:21], v[86:87] op_sel_hi:[1,0,1]
	v_pk_fma_f32 v[88:89], v[232:233], s[20:21], v[88:89] op_sel_hi:[1,0,1]
	v_pk_fma_f32 v[90:91], v[234:235], s[20:21], v[90:91] op_sel_hi:[1,0,1]
	v_pk_fma_f32 v[92:93], v[236:237], s[20:21], v[92:93] op_sel_hi:[1,0,1]
	v_pk_fma_f32 v[94:95], v[238:239], s[20:21], v[94:95] op_sel_hi:[1,0,1]
	v_cvt_pk_f32_fp8_e32 v[224:225], v204
	v_cvt_pk_f32_fp8_sdwa v[226:227], v204 src0_sel:WORD_1
	v_cvt_pk_f32_fp8_e32 v[228:229], v205
	v_cvt_pk_f32_fp8_sdwa v[230:231], v205 src0_sel:WORD_1
	v_cvt_pk_f32_fp8_e32 v[232:233], v206
	v_cvt_pk_f32_fp8_sdwa v[234:235], v206 src0_sel:WORD_1
	v_cvt_pk_f32_fp8_e32 v[236:237], v207
	v_cvt_pk_f32_fp8_sdwa v[238:239], v207 src0_sel:WORD_1
	v_pk_fma_f32 v[80:81], v[224:225], s[22:23], v[80:81] op_sel_hi:[1,0,1]
	v_pk_fma_f32 v[82:83], v[226:227], s[22:23], v[82:83] op_sel_hi:[1,0,1]
	v_pk_fma_f32 v[84:85], v[228:229], s[22:23], v[84:85] op_sel_hi:[1,0,1]
	v_pk_fma_f32 v[86:87], v[230:231], s[22:23], v[86:87] op_sel_hi:[1,0,1]
	v_pk_fma_f32 v[88:89], v[232:233], s[22:23], v[88:89] op_sel_hi:[1,0,1]
	v_pk_fma_f32 v[90:91], v[234:235], s[22:23], v[90:91] op_sel_hi:[1,0,1]
	v_pk_fma_f32 v[92:93], v[236:237], s[22:23], v[92:93] op_sel_hi:[1,0,1]
	v_pk_fma_f32 v[94:95], v[238:239], s[22:23], v[94:95] op_sel_hi:[1,0,1]
	v_cvt_pk_f32_fp8_e32 v[224:225], v208
	v_cvt_pk_f32_fp8_sdwa v[226:227], v208 src0_sel:WORD_1
	v_cvt_pk_f32_fp8_e32 v[228:229], v209
	v_cvt_pk_f32_fp8_sdwa v[230:231], v209 src0_sel:WORD_1
	v_cvt_pk_f32_fp8_e32 v[232:233], v210
	v_cvt_pk_f32_fp8_sdwa v[234:235], v210 src0_sel:WORD_1
	v_cvt_pk_f32_fp8_e32 v[236:237], v211
	v_cvt_pk_f32_fp8_sdwa v[238:239], v211 src0_sel:WORD_1
	v_pk_fma_f32 v[80:81], v[224:225], s[24:25], v[80:81] op_sel_hi:[1,0,1]
	v_pk_fma_f32 v[82:83], v[226:227], s[24:25], v[82:83] op_sel_hi:[1,0,1]
	v_pk_fma_f32 v[84:85], v[228:229], s[24:25], v[84:85] op_sel_hi:[1,0,1]
	v_pk_fma_f32 v[86:87], v[230:231], s[24:25], v[86:87] op_sel_hi:[1,0,1]
	v_pk_fma_f32 v[88:89], v[232:233], s[24:25], v[88:89] op_sel_hi:[1,0,1]
	v_pk_fma_f32 v[90:91], v[234:235], s[24:25], v[90:91] op_sel_hi:[1,0,1]
	v_pk_fma_f32 v[92:93], v[236:237], s[24:25], v[92:93] op_sel_hi:[1,0,1]
	v_pk_fma_f32 v[94:95], v[238:239], s[24:25], v[94:95] op_sel_hi:[1,0,1]
	v_cvt_pk_f32_fp8_e32 v[224:225], v212
	v_cvt_pk_f32_fp8_sdwa v[226:227], v212 src0_sel:WORD_1
	v_cvt_pk_f32_fp8_e32 v[228:229], v213
	v_cvt_pk_f32_fp8_sdwa v[230:231], v213 src0_sel:WORD_1
	v_cvt_pk_f32_fp8_e32 v[232:233], v214
	v_cvt_pk_f32_fp8_sdwa v[234:235], v214 src0_sel:WORD_1
	v_cvt_pk_f32_fp8_e32 v[236:237], v215
	v_cvt_pk_f32_fp8_sdwa v[238:239], v215 src0_sel:WORD_1
	v_pk_fma_f32 v[80:81], v[224:225], s[26:27], v[80:81] op_sel_hi:[1,0,1]
	v_pk_fma_f32 v[82:83], v[226:227], s[26:27], v[82:83] op_sel_hi:[1,0,1]
	v_pk_fma_f32 v[84:85], v[228:229], s[26:27], v[84:85] op_sel_hi:[1,0,1]
	v_pk_fma_f32 v[86:87], v[230:231], s[26:27], v[86:87] op_sel_hi:[1,0,1]
	v_pk_fma_f32 v[88:89], v[232:233], s[26:27], v[88:89] op_sel_hi:[1,0,1]
	v_pk_fma_f32 v[90:91], v[234:235], s[26:27], v[90:91] op_sel_hi:[1,0,1]
; DI void peer_item_v(const Params& p, int item) {
;     ...
;     V_ISSUE(vqa, 0)
; #pragma unroll 1
;     for (int g = 0; g < 16; g += 2) {
;       V_ISSUE(vqb, g + 1)
;       V_CONSUME(vqa, g)
;       if (g + 2 < 16) V_ISSUE(vqa, g + 2)
;       V_CONSUME(vqb, g + 1)
;     }
	v_pk_fma_f32 v[92:93], v[236:237], s[26:27], v[92:93] op_sel_hi:[1,0,1]
	v_pk_fma_f32 v[94:95], v[238:239], s[26:27], v[94:95] op_sel_hi:[1,0,1]
	v_cvt_pk_f32_fp8_e32 v[224:225], v216
	v_cvt_pk_f32_fp8_sdwa v[226:227], v216 src0_sel:WORD_1
	v_cvt_pk_f32_fp8_e32 v[228:229], v217
	v_cvt_pk_f32_fp8_sdwa v[230:231], v217 src0_sel:WORD_1
	v_cvt_pk_f32_fp8_e32 v[232:233], v218
	v_cvt_pk_f32_fp8_sdwa v[234:235], v218 src0_sel:WORD_1
	v_cvt_pk_f32_fp8_e32 v[236:237], v219
	v_cvt_pk_f32_fp8_sdwa v[238:239], v219 src0_sel:WORD_1
	v_pk_fma_f32 v[80:81], v[224:225], s[28:29], v[80:81] op_sel_hi:[1,0,1]
	v_pk_fma_f32 v[82:83], v[226:227], s[28:29], v[82:83] op_sel_hi:[1,0,1]
	v_pk_fma_f32 v[84:85], v[228:229], s[28:29], v[84:85] op_sel_hi:[1,0,1]
	v_pk_fma_f32 v[86:87], v[230:231], s[28:29], v[86:87] op_sel_hi:[1,0,1]
	v_pk_fma_f32 v[88:89], v[232:233], s[28:29], v[88:89] op_sel_hi:[1,0,1]
	v_pk_fma_f32 v[90:91], v[234:235], s[28:29], v[90:91] op_sel_hi:[1,0,1]
	v_pk_fma_f32 v[92:93], v[236:237], s[28:29], v[92:93] op_sel_hi:[1,0,1]
	v_pk_fma_f32 v[94:95], v[238:239], s[28:29], v[94:95] op_sel_hi:[1,0,1]
	v_cvt_pk_f32_fp8_e32 v[224:225], v220
	v_cvt_pk_f32_fp8_sdwa v[226:227], v220 src0_sel:WORD_1
	v_cvt_pk_f32_fp8_e32 v[228:229], v221
	v_cvt_pk_f32_fp8_sdwa v[230:231], v221 src0_sel:WORD_1
	v_cvt_pk_f32_fp8_e32 v[232:233], v222
	v_cvt_pk_f32_fp8_sdwa v[234:235], v222 src0_sel:WORD_1
	v_cvt_pk_f32_fp8_e32 v[236:237], v223
	v_cvt_pk_f32_fp8_sdwa v[238:239], v223 src0_sel:WORD_1
	v_pk_fma_f32 v[80:81], v[224:225], s[30:31], v[80:81] op_sel_hi:[1,0,1]
	v_pk_fma_f32 v[82:83], v[226:227], s[30:31], v[82:83] op_sel_hi:[1,0,1]
	v_pk_fma_f32 v[84:85], v[228:229], s[30:31], v[84:85] op_sel_hi:[1,0,1]
	v_pk_fma_f32 v[86:87], v[230:231], s[30:31], v[86:87] op_sel_hi:[1,0,1]
	v_pk_fma_f32 v[88:89], v[232:233], s[30:31], v[88:89] op_sel_hi:[1,0,1]
	v_pk_fma_f32 v[90:91], v[234:235], s[30:31], v[90:91] op_sel_hi:[1,0,1]
	v_pk_fma_f32 v[92:93], v[236:237], s[30:31], v[92:93] op_sel_hi:[1,0,1]
	v_pk_fma_f32 v[94:95], v[238:239], s[30:31], v[94:95] op_sel_hi:[1,0,1]
	v_readlane_b32 s16, v154, s72
	v_readlane_b32 s18, v154, s73
	v_readlane_b32 s20, v154, s74
	v_readlane_b32 s22, v154, s75
	v_readlane_b32 s24, v154, s76
	v_readlane_b32 s26, v154, s77
	v_readlane_b32 s28, v154, s78
	v_readlane_b32 s30, v154, s79
	v_readlane_b32 s48, v149, s72
	v_readlane_b32 s49, v149, s73
	v_readlane_b32 s50, v149, s74
	v_readlane_b32 s51, v149, s75
	v_readlane_b32 s52, v149, s76
	v_readlane_b32 s53, v149, s77
	v_readlane_b32 s54, v149, s78
	v_readlane_b32 s55, v149, s79
	s_add_u32 s32, s0, s48
	s_addc_u32 s33, s1, 0
	s_add_u32 s34, s0, s49
	s_addc_u32 s35, s1, 0
	s_add_u32 s36, s0, s50
	s_addc_u32 s37, s1, 0
	s_add_u32 s38, s0, s51
	s_addc_u32 s39, s1, 0
	s_add_u32 s40, s0, s52
	s_addc_u32 s41, s1, 0
	s_add_u32 s42, s0, s53
	s_addc_u32 s43, s1, 0
	s_add_u32 s44, s0, s54
	s_addc_u32 s45, s1, 0
	s_add_u32 s46, s0, s55
	s_addc_u32 s47, s1, 0
	global_load_dwordx4 v[192:195], v240, s[32:33]
	global_load_dwordx4 v[196:199], v240, s[34:35]
	global_load_dwordx4 v[200:203], v240, s[36:37]
	global_load_dwordx4 v[204:207], v240, s[38:39]
	global_load_dwordx4 v[208:211], v240, s[40:41]
	global_load_dwordx4 v[212:215], v240, s[42:43]
	global_load_dwordx4 v[216:219], v240, s[44:45]
	global_load_dwordx4 v[220:223], v240, s[46:47]
	s_waitcnt vmcnt(24)
	v_cvt_pk_f32_fp8_e32 v[224:225], v0
	v_cvt_pk_f32_fp8_sdwa v[226:227], v0 src0_sel:WORD_1
	v_cvt_pk_f32_fp8_e32 v[228:229], v1
	v_cvt_pk_f32_fp8_sdwa v[230:231], v1 src0_sel:WORD_1
	v_cvt_pk_f32_fp8_e32 v[232:233], v2
	v_cvt_pk_f32_fp8_sdwa v[234:235], v2 src0_sel:WORD_1
	v_cvt_pk_f32_fp8_e32 v[236:237], v3
	v_cvt_pk_f32_fp8_sdwa v[238:239], v3 src0_sel:WORD_1
	v_pk_fma_f32 v[96:97], v[224:225], s[16:17], v[96:97] op_sel_hi:[1,0,1]
	v_pk_fma_f32 v[98:99], v[226:227], s[16:17], v[98:99] op_sel_hi:[1,0,1]
	v_pk_fma_f32 v[100:101], v[228:229], s[16:17], v[100:101] op_sel_hi:[1,0,1]
	v_pk_fma_f32 v[102:103], v[230:231], s[16:17], v[102:103] op_sel_hi:[1,0,1]
	v_pk_fma_f32 v[104:105], v[232:233], s[16:17], v[104:105] op_sel_hi:[1,0,1]
	v_pk_fma_f32 v[106:107], v[234:235], s[16:17], v[106:107] op_sel_hi:[1,0,1]
	v_pk_fma_f32 v[108:109], v[236:237], s[16:17], v[108:109] op_sel_hi:[1,0,1]
	v_pk_fma_f32 v[110:111], v[238:239], s[16:17], v[110:111] op_sel_hi:[1,0,1]
	v_cvt_pk_f32_fp8_e32 v[224:225], v4
	v_cvt_pk_f32_fp8_sdwa v[226:227], v4 src0_sel:WORD_1
	v_cvt_pk_f32_fp8_e32 v[228:229], v5
	v_cvt_pk_f32_fp8_sdwa v[230:231], v5 src0_sel:WORD_1
	v_cvt_pk_f32_fp8_e32 v[232:233], v6
	v_cvt_pk_f32_fp8_sdwa v[234:235], v6 src0_sel:WORD_1
	v_cvt_pk_f32_fp8_e32 v[236:237], v7
	v_cvt_pk_f32_fp8_sdwa v[238:239], v7 src0_sel:WORD_1
	v_pk_fma_f32 v[96:97], v[224:225], s[18:19], v[96:97] op_sel_hi:[1,0,1]
	v_pk_fma_f32 v[98:99], v[226:227], s[18:19], v[98:99] op_sel_hi:[1,0,1]
	v_pk_fma_f32 v[100:101], v[228:229], s[18:19], v[100:101] op_sel_hi:[1,0,1]
	v_pk_fma_f32 v[102:103], v[230:231], s[18:19], v[102:103] op_sel_hi:[1,0,1]
	v_pk_fma_f32 v[104:105], v[232:233], s[18:19], v[104:105] op_sel_hi:[1,0,1]
	v_pk_fma_f32 v[106:107], v[234:235], s[18:19], v[106:107] op_sel_hi:[1,0,1]
	v_pk_fma_f32 v[108:109], v[236:237], s[18:19], v[108:109] op_sel_hi:[1,0,1]
	v_pk_fma_f32 v[110:111], v[238:239], s[18:19], v[110:111] op_sel_hi:[1,0,1]
	v_cvt_pk_f32_fp8_e32 v[224:225], v8
	v_cvt_pk_f32_fp8_sdwa v[226:227], v8 src0_sel:WORD_1
	v_cvt_pk_f32_fp8_e32 v[228:229], v9
	v_cvt_pk_f32_fp8_sdwa v[230:231], v9 src0_sel:WORD_1
	v_cvt_pk_f32_fp8_e32 v[232:233], v10
	v_cvt_pk_f32_fp8_sdwa v[234:235], v10 src0_sel:WORD_1
	v_cvt_pk_f32_fp8_e32 v[236:237], v11
	v_cvt_pk_f32_fp8_sdwa v[238:239], v11 src0_sel:WORD_1
; DI void peer_item_v(const Params& p, int item) {
;     ...
;     V_ISSUE(vqa, 0)
; #pragma unroll 1
;     for (int g = 0; g < 16; g += 2) {
;       V_ISSUE(vqb, g + 1)
;       V_CONSUME(vqa, g)
;       if (g + 2 < 16) V_ISSUE(vqa, g + 2)
;       V_CONSUME(vqb, g + 1)
;     }
	v_pk_fma_f32 v[96:97], v[224:225], s[20:21], v[96:97] op_sel_hi:[1,0,1]
	v_pk_fma_f32 v[98:99], v[226:227], s[20:21], v[98:99] op_sel_hi:[1,0,1]
	v_pk_fma_f32 v[100:101], v[228:229], s[20:21], v[100:101] op_sel_hi:[1,0,1]
	v_pk_fma_f32 v[102:103], v[230:231], s[20:21], v[102:103] op_sel_hi:[1,0,1]
	v_pk_fma_f32 v[104:105], v[232:233], s[20:21], v[104:105] op_sel_hi:[1,0,1]
	v_pk_fma_f32 v[106:107], v[234:235], s[20:21], v[106:107] op_sel_hi:[1,0,1]
	v_pk_fma_f32 v[108:109], v[236:237], s[20:21], v[108:109] op_sel_hi:[1,0,1]
	v_pk_fma_f32 v[110:111], v[238:239], s[20:21], v[110:111] op_sel_hi:[1,0,1]
	v_cvt_pk_f32_fp8_e32 v[224:225], v12
	v_cvt_pk_f32_fp8_sdwa v[226:227], v12 src0_sel:WORD_1
	v_cvt_pk_f32_fp8_e32 v[228:229], v13
	v_cvt_pk_f32_fp8_sdwa v[230:231], v13 src0_sel:WORD_1
	v_cvt_pk_f32_fp8_e32 v[232:233], v14
	v_cvt_pk_f32_fp8_sdwa v[234:235], v14 src0_sel:WORD_1
	v_cvt_pk_f32_fp8_e32 v[236:237], v15
	v_cvt_pk_f32_fp8_sdwa v[238:239], v15 src0_sel:WORD_1
	v_pk_fma_f32 v[96:97], v[224:225], s[22:23], v[96:97] op_sel_hi:[1,0,1]
	v_pk_fma_f32 v[98:99], v[226:227], s[22:23], v[98:99] op_sel_hi:[1,0,1]
	v_pk_fma_f32 v[100:101], v[228:229], s[22:23], v[100:101] op_sel_hi:[1,0,1]
	v_pk_fma_f32 v[102:103], v[230:231], s[22:23], v[102:103] op_sel_hi:[1,0,1]
	v_pk_fma_f32 v[104:105], v[232:233], s[22:23], v[104:105] op_sel_hi:[1,0,1]
	v_pk_fma_f32 v[106:107], v[234:235], s[22:23], v[106:107] op_sel_hi:[1,0,1]
	v_pk_fma_f32 v[108:109], v[236:237], s[22:23], v[108:109] op_sel_hi:[1,0,1]
	v_pk_fma_f32 v[110:111], v[238:239], s[22:23], v[110:111] op_sel_hi:[1,0,1]
	v_cvt_pk_f32_fp8_e32 v[224:225], v16
	v_cvt_pk_f32_fp8_sdwa v[226:227], v16 src0_sel:WORD_1
	v_cvt_pk_f32_fp8_e32 v[228:229], v17
	v_cvt_pk_f32_fp8_sdwa v[230:231], v17 src0_sel:WORD_1
	v_cvt_pk_f32_fp8_e32 v[232:233], v18
	v_cvt_pk_f32_fp8_sdwa v[234:235], v18 src0_sel:WORD_1
	v_cvt_pk_f32_fp8_e32 v[236:237], v19
	v_cvt_pk_f32_fp8_sdwa v[238:239], v19 src0_sel:WORD_1
	v_pk_fma_f32 v[96:97], v[224:225], s[24:25], v[96:97] op_sel_hi:[1,0,1]
	v_pk_fma_f32 v[98:99], v[226:227], s[24:25], v[98:99] op_sel_hi:[1,0,1]
	v_pk_fma_f32 v[100:101], v[228:229], s[24:25], v[100:101] op_sel_hi:[1,0,1]
	v_pk_fma_f32 v[102:103], v[230:231], s[24:25], v[102:103] op_sel_hi:[1,0,1]
	v_pk_fma_f32 v[104:105], v[232:233], s[24:25], v[104:105] op_sel_hi:[1,0,1]
	v_pk_fma_f32 v[106:107], v[234:235], s[24:25], v[106:107] op_sel_hi:[1,0,1]
	v_pk_fma_f32 v[108:109], v[236:237], s[24:25], v[108:109] op_sel_hi:[1,0,1]
	v_pk_fma_f32 v[110:111], v[238:239], s[24:25], v[110:111] op_sel_hi:[1,0,1]
	v_cvt_pk_f32_fp8_e32 v[224:225], v20
	v_cvt_pk_f32_fp8_sdwa v[226:227], v20 src0_sel:WORD_1
	v_cvt_pk_f32_fp8_e32 v[228:229], v21
	v_cvt_pk_f32_fp8_sdwa v[230:231], v21 src0_sel:WORD_1
	v_cvt_pk_f32_fp8_e32 v[232:233], v22
	v_cvt_pk_f32_fp8_sdwa v[234:235], v22 src0_sel:WORD_1
	v_cvt_pk_f32_fp8_e32 v[236:237], v23
	v_cvt_pk_f32_fp8_sdwa v[238:239], v23 src0_sel:WORD_1
	v_pk_fma_f32 v[96:97], v[224:225], s[26:27], v[96:97] op_sel_hi:[1,0,1]
	v_pk_fma_f32 v[98:99], v[226:227], s[26:27], v[98:99] op_sel_hi:[1,0,1]
	v_pk_fma_f32 v[100:101], v[228:229], s[26:27], v[100:101] op_sel_hi:[1,0,1]
	v_pk_fma_f32 v[102:103], v[230:231], s[26:27], v[102:103] op_sel_hi:[1,0,1]
	v_pk_fma_f32 v[104:105], v[232:233], s[26:27], v[104:105] op_sel_hi:[1,0,1]
	v_pk_fma_f32 v[106:107], v[234:235], s[26:27], v[106:107] op_sel_hi:[1,0,1]
	v_pk_fma_f32 v[108:109], v[236:237], s[26:27], v[108:109] op_sel_hi:[1,0,1]
	v_pk_fma_f32 v[110:111], v[238:239], s[26:27], v[110:111] op_sel_hi:[1,0,1]
	v_cvt_pk_f32_fp8_e32 v[224:225], v24
	v_cvt_pk_f32_fp8_sdwa v[226:227], v24 src0_sel:WORD_1
	v_cvt_pk_f32_fp8_e32 v[228:229], v25
	v_cvt_pk_f32_fp8_sdwa v[230:231], v25 src0_sel:WORD_1
	v_cvt_pk_f32_fp8_e32 v[232:233], v26
	v_cvt_pk_f32_fp8_sdwa v[234:235], v26 src0_sel:WORD_1
	v_cvt_pk_f32_fp8_e32 v[236:237], v27
	v_cvt_pk_f32_fp8_sdwa v[238:239], v27 src0_sel:WORD_1
	v_pk_fma_f32 v[96:97], v[224:225], s[28:29], v[96:97] op_sel_hi:[1,0,1]
	v_pk_fma_f32 v[98:99], v[226:227], s[28:29], v[98:99] op_sel_hi:[1,0,1]
	v_pk_fma_f32 v[100:101], v[228:229], s[28:29], v[100:101] op_sel_hi:[1,0,1]
	v_pk_fma_f32 v[102:103], v[230:231], s[28:29], v[102:103] op_sel_hi:[1,0,1]
	v_pk_fma_f32 v[104:105], v[232:233], s[28:29], v[104:105] op_sel_hi:[1,0,1]
	v_pk_fma_f32 v[106:107], v[234:235], s[28:29], v[106:107] op_sel_hi:[1,0,1]
	v_pk_fma_f32 v[108:109], v[236:237], s[28:29], v[108:109] op_sel_hi:[1,0,1]
	v_pk_fma_f32 v[110:111], v[238:239], s[28:29], v[110:111] op_sel_hi:[1,0,1]
	v_cvt_pk_f32_fp8_e32 v[224:225], v28
	v_cvt_pk_f32_fp8_sdwa v[226:227], v28 src0_sel:WORD_1
	v_cvt_pk_f32_fp8_e32 v[228:229], v29
	v_cvt_pk_f32_fp8_sdwa v[230:231], v29 src0_sel:WORD_1
	v_cvt_pk_f32_fp8_e32 v[232:233], v30
	v_cvt_pk_f32_fp8_sdwa v[234:235], v30 src0_sel:WORD_1
	v_cvt_pk_f32_fp8_e32 v[236:237], v31
	v_cvt_pk_f32_fp8_sdwa v[238:239], v31 src0_sel:WORD_1
	v_pk_fma_f32 v[96:97], v[224:225], s[30:31], v[96:97] op_sel_hi:[1,0,1]
	v_pk_fma_f32 v[98:99], v[226:227], s[30:31], v[98:99] op_sel_hi:[1,0,1]
	v_pk_fma_f32 v[100:101], v[228:229], s[30:31], v[100:101] op_sel_hi:[1,0,1]
	v_pk_fma_f32 v[102:103], v[230:231], s[30:31], v[102:103] op_sel_hi:[1,0,1]
	v_pk_fma_f32 v[104:105], v[232:233], s[30:31], v[104:105] op_sel_hi:[1,0,1]
	v_pk_fma_f32 v[106:107], v[234:235], s[30:31], v[106:107] op_sel_hi:[1,0,1]
	v_pk_fma_f32 v[108:109], v[236:237], s[30:31], v[108:109] op_sel_hi:[1,0,1]
	v_pk_fma_f32 v[110:111], v[238:239], s[30:31], v[110:111] op_sel_hi:[1,0,1]
	v_readlane_b32 s16, v158, s72
	v_readlane_b32 s18, v158, s73
	v_readlane_b32 s20, v158, s74
	v_readlane_b32 s22, v158, s75
	v_readlane_b32 s24, v158, s76
	v_readlane_b32 s26, v158, s77
	v_readlane_b32 s28, v158, s78
	v_readlane_b32 s30, v158, s79
	v_readlane_b32 s48, v153, s72
	v_readlane_b32 s49, v153, s73
	v_readlane_b32 s50, v153, s74
	v_readlane_b32 s51, v153, s75
	v_readlane_b32 s52, v153, s76
	v_readlane_b32 s53, v153, s77
	v_readlane_b32 s54, v153, s78
	v_readlane_b32 s55, v153, s79
	s_add_u32 s32, s0, s48
	s_addc_u32 s33, s1, 0
	s_add_u32 s34, s0, s49
	s_addc_u32 s35, s1, 0
	s_add_u32 s36, s0, s50
	s_addc_u32 s37, s1, 0
	s_add_u32 s38, s0, s51
	s_addc_u32 s39, s1, 0
	s_add_u32 s40, s0, s52
	s_addc_u32 s41, s1, 0
	s_add_u32 s42, s0, s53
	s_addc_u32 s43, s1, 0
	s_add_u32 s44, s0, s54
	s_addc_u32 s45, s1, 0
	s_add_u32 s46, s0, s55
	s_addc_u32 s47, s1, 0
	global_load_dwordx4 v[0:3], v240, s[32:33]
	global_load_dwordx4 v[4:7], v240, s[34:35]
	global_load_dwordx4 v[8:11], v240, s[36:37]
	global_load_dwordx4 v[12:15], v240, s[38:39]
	global_load_dwordx4 v[16:19], v240, s[40:41]
	global_load_dwordx4 v[20:23], v240, s[42:43]
	global_load_dwordx4 v[24:27], v240, s[44:45]
	global_load_dwordx4 v[28:31], v240, s[46:47]
	s_waitcnt vmcnt(24)
; DI void peer_item_v(const Params& p, int item) {
;     ...
;     V_ISSUE(vqa, 0)
; #pragma unroll 1
;     for (int g = 0; g < 16; g += 2) {
;       V_ISSUE(vqb, g + 1)
;       V_CONSUME(vqa, g)
;       if (g + 2 < 16) V_ISSUE(vqa, g + 2)
;       V_CONSUME(vqb, g + 1)
;     }
	v_cvt_pk_f32_fp8_e32 v[224:225], v32
	v_cvt_pk_f32_fp8_sdwa v[226:227], v32 src0_sel:WORD_1
	v_cvt_pk_f32_fp8_e32 v[228:229], v33
	v_cvt_pk_f32_fp8_sdwa v[230:231], v33 src0_sel:WORD_1
	v_cvt_pk_f32_fp8_e32 v[232:233], v34
	v_cvt_pk_f32_fp8_sdwa v[234:235], v34 src0_sel:WORD_1
	v_cvt_pk_f32_fp8_e32 v[236:237], v35
	v_cvt_pk_f32_fp8_sdwa v[238:239], v35 src0_sel:WORD_1
	v_pk_fma_f32 v[112:113], v[224:225], s[16:17], v[112:113] op_sel_hi:[1,0,1]
	v_pk_fma_f32 v[114:115], v[226:227], s[16:17], v[114:115] op_sel_hi:[1,0,1]
	v_pk_fma_f32 v[116:117], v[228:229], s[16:17], v[116:117] op_sel_hi:[1,0,1]
	v_pk_fma_f32 v[118:119], v[230:231], s[16:17], v[118:119] op_sel_hi:[1,0,1]
	v_pk_fma_f32 v[120:121], v[232:233], s[16:17], v[120:121] op_sel_hi:[1,0,1]
	v_pk_fma_f32 v[122:123], v[234:235], s[16:17], v[122:123] op_sel_hi:[1,0,1]
	v_pk_fma_f32 v[124:125], v[236:237], s[16:17], v[124:125] op_sel_hi:[1,0,1]
	v_pk_fma_f32 v[126:127], v[238:239], s[16:17], v[126:127] op_sel_hi:[1,0,1]
	v_cvt_pk_f32_fp8_e32 v[224:225], v36
	v_cvt_pk_f32_fp8_sdwa v[226:227], v36 src0_sel:WORD_1
	v_cvt_pk_f32_fp8_e32 v[228:229], v37
	v_cvt_pk_f32_fp8_sdwa v[230:231], v37 src0_sel:WORD_1
	v_cvt_pk_f32_fp8_e32 v[232:233], v38
	v_cvt_pk_f32_fp8_sdwa v[234:235], v38 src0_sel:WORD_1
	v_cvt_pk_f32_fp8_e32 v[236:237], v39
	v_cvt_pk_f32_fp8_sdwa v[238:239], v39 src0_sel:WORD_1
	v_pk_fma_f32 v[112:113], v[224:225], s[18:19], v[112:113] op_sel_hi:[1,0,1]
	v_pk_fma_f32 v[114:115], v[226:227], s[18:19], v[114:115] op_sel_hi:[1,0,1]
	v_pk_fma_f32 v[116:117], v[228:229], s[18:19], v[116:117] op_sel_hi:[1,0,1]
	v_pk_fma_f32 v[118:119], v[230:231], s[18:19], v[118:119] op_sel_hi:[1,0,1]
	v_pk_fma_f32 v[120:121], v[232:233], s[18:19], v[120:121] op_sel_hi:[1,0,1]
	v_pk_fma_f32 v[122:123], v[234:235], s[18:19], v[122:123] op_sel_hi:[1,0,1]
	v_pk_fma_f32 v[124:125], v[236:237], s[18:19], v[124:125] op_sel_hi:[1,0,1]
	v_pk_fma_f32 v[126:127], v[238:239], s[18:19], v[126:127] op_sel_hi:[1,0,1]
	v_cvt_pk_f32_fp8_e32 v[224:225], v40
	v_cvt_pk_f32_fp8_sdwa v[226:227], v40 src0_sel:WORD_1
	v_cvt_pk_f32_fp8_e32 v[228:229], v41
	v_cvt_pk_f32_fp8_sdwa v[230:231], v41 src0_sel:WORD_1
	v_cvt_pk_f32_fp8_e32 v[232:233], v42
	v_cvt_pk_f32_fp8_sdwa v[234:235], v42 src0_sel:WORD_1
	v_cvt_pk_f32_fp8_e32 v[236:237], v43
	v_cvt_pk_f32_fp8_sdwa v[238:239], v43 src0_sel:WORD_1
	v_pk_fma_f32 v[112:113], v[224:225], s[20:21], v[112:113] op_sel_hi:[1,0,1]
	v_pk_fma_f32 v[114:115], v[226:227], s[20:21], v[114:115] op_sel_hi:[1,0,1]
	v_pk_fma_f32 v[116:117], v[228:229], s[20:21], v[116:117] op_sel_hi:[1,0,1]
	v_pk_fma_f32 v[118:119], v[230:231], s[20:21], v[118:119] op_sel_hi:[1,0,1]
	v_pk_fma_f32 v[120:121], v[232:233], s[20:21], v[120:121] op_sel_hi:[1,0,1]
	v_pk_fma_f32 v[122:123], v[234:235], s[20:21], v[122:123] op_sel_hi:[1,0,1]
	v_pk_fma_f32 v[124:125], v[236:237], s[20:21], v[124:125] op_sel_hi:[1,0,1]
	v_pk_fma_f32 v[126:127], v[238:239], s[20:21], v[126:127] op_sel_hi:[1,0,1]
	v_cvt_pk_f32_fp8_e32 v[224:225], v44
	v_cvt_pk_f32_fp8_sdwa v[226:227], v44 src0_sel:WORD_1
	v_cvt_pk_f32_fp8_e32 v[228:229], v45
	v_cvt_pk_f32_fp8_sdwa v[230:231], v45 src0_sel:WORD_1
	v_cvt_pk_f32_fp8_e32 v[232:233], v46
	v_cvt_pk_f32_fp8_sdwa v[234:235], v46 src0_sel:WORD_1
	v_cvt_pk_f32_fp8_e32 v[236:237], v47
	v_cvt_pk_f32_fp8_sdwa v[238:239], v47 src0_sel:WORD_1
	v_pk_fma_f32 v[112:113], v[224:225], s[22:23], v[112:113] op_sel_hi:[1,0,1]
	v_pk_fma_f32 v[114:115], v[226:227], s[22:23], v[114:115] op_sel_hi:[1,0,1]
	v_pk_fma_f32 v[116:117], v[228:229], s[22:23], v[116:117] op_sel_hi:[1,0,1]
	v_pk_fma_f32 v[118:119], v[230:231], s[22:23], v[118:119] op_sel_hi:[1,0,1]
	v_pk_fma_f32 v[120:121], v[232:233], s[22:23], v[120:121] op_sel_hi:[1,0,1]
	v_pk_fma_f32 v[122:123], v[234:235], s[22:23], v[122:123] op_sel_hi:[1,0,1]
	v_pk_fma_f32 v[124:125], v[236:237], s[22:23], v[124:125] op_sel_hi:[1,0,1]
	v_pk_fma_f32 v[126:127], v[238:239], s[22:23], v[126:127] op_sel_hi:[1,0,1]
	v_cvt_pk_f32_fp8_e32 v[224:225], v48
	v_cvt_pk_f32_fp8_sdwa v[226:227], v48 src0_sel:WORD_1
	v_cvt_pk_f32_fp8_e32 v[228:229], v49
	v_cvt_pk_f32_fp8_sdwa v[230:231], v49 src0_sel:WORD_1
	v_cvt_pk_f32_fp8_e32 v[232:233], v50
	v_cvt_pk_f32_fp8_sdwa v[234:235], v50 src0_sel:WORD_1
	v_cvt_pk_f32_fp8_e32 v[236:237], v51
	v_cvt_pk_f32_fp8_sdwa v[238:239], v51 src0_sel:WORD_1
	v_pk_fma_f32 v[112:113], v[224:225], s[24:25], v[112:113] op_sel_hi:[1,0,1]
	v_pk_fma_f32 v[114:115], v[226:227], s[24:25], v[114:115] op_sel_hi:[1,0,1]
	v_pk_fma_f32 v[116:117], v[228:229], s[24:25], v[116:117] op_sel_hi:[1,0,1]
	v_pk_fma_f32 v[118:119], v[230:231], s[24:25], v[118:119] op_sel_hi:[1,0,1]
	v_pk_fma_f32 v[120:121], v[232:233], s[24:25], v[120:121] op_sel_hi:[1,0,1]
	v_pk_fma_f32 v[122:123], v[234:235], s[24:25], v[122:123] op_sel_hi:[1,0,1]
	v_pk_fma_f32 v[124:125], v[236:237], s[24:25], v[124:125] op_sel_hi:[1,0,1]
	v_pk_fma_f32 v[126:127], v[238:239], s[24:25], v[126:127] op_sel_hi:[1,0,1]
	v_cvt_pk_f32_fp8_e32 v[224:225], v52
	v_cvt_pk_f32_fp8_sdwa v[226:227], v52 src0_sel:WORD_1
	v_cvt_pk_f32_fp8_e32 v[228:229], v53
	v_cvt_pk_f32_fp8_sdwa v[230:231], v53 src0_sel:WORD_1
	v_cvt_pk_f32_fp8_e32 v[232:233], v54
	v_cvt_pk_f32_fp8_sdwa v[234:235], v54 src0_sel:WORD_1
	v_cvt_pk_f32_fp8_e32 v[236:237], v55
	v_cvt_pk_f32_fp8_sdwa v[238:239], v55 src0_sel:WORD_1
	v_pk_fma_f32 v[112:113], v[224:225], s[26:27], v[112:113] op_sel_hi:[1,0,1]
	v_pk_fma_f32 v[114:115], v[226:227], s[26:27], v[114:115] op_sel_hi:[1,0,1]
	v_pk_fma_f32 v[116:117], v[228:229], s[26:27], v[116:117] op_sel_hi:[1,0,1]
	v_pk_fma_f32 v[118:119], v[230:231], s[26:27], v[118:119] op_sel_hi:[1,0,1]
; DI void peer_item_v(const Params& p, int item) {
;     ...
;     V_ISSUE(vqa, 0)
; #pragma unroll 1
;     for (int g = 0; g < 16; g += 2) {
;       V_ISSUE(vqb, g + 1)
;       V_CONSUME(vqa, g)
;       if (g + 2 < 16) V_ISSUE(vqa, g + 2)
;       V_CONSUME(vqb, g + 1)
;     }
	v_pk_fma_f32 v[120:121], v[232:233], s[26:27], v[120:121] op_sel_hi:[1,0,1]
	v_pk_fma_f32 v[122:123], v[234:235], s[26:27], v[122:123] op_sel_hi:[1,0,1]
	v_pk_fma_f32 v[124:125], v[236:237], s[26:27], v[124:125] op_sel_hi:[1,0,1]
	v_pk_fma_f32 v[126:127], v[238:239], s[26:27], v[126:127] op_sel_hi:[1,0,1]
	v_cvt_pk_f32_fp8_e32 v[224:225], v56
	v_cvt_pk_f32_fp8_sdwa v[226:227], v56 src0_sel:WORD_1
	v_cvt_pk_f32_fp8_e32 v[228:229], v57
	v_cvt_pk_f32_fp8_sdwa v[230:231], v57 src0_sel:WORD_1
	v_cvt_pk_f32_fp8_e32 v[232:233], v58
	v_cvt_pk_f32_fp8_sdwa v[234:235], v58 src0_sel:WORD_1
	v_cvt_pk_f32_fp8_e32 v[236:237], v59
	v_cvt_pk_f32_fp8_sdwa v[238:239], v59 src0_sel:WORD_1
	v_pk_fma_f32 v[112:113], v[224:225], s[28:29], v[112:113] op_sel_hi:[1,0,1]
	v_pk_fma_f32 v[114:115], v[226:227], s[28:29], v[114:115] op_sel_hi:[1,0,1]
	v_pk_fma_f32 v[116:117], v[228:229], s[28:29], v[116:117] op_sel_hi:[1,0,1]
	v_pk_fma_f32 v[118:119], v[230:231], s[28:29], v[118:119] op_sel_hi:[1,0,1]
	v_pk_fma_f32 v[120:121], v[232:233], s[28:29], v[120:121] op_sel_hi:[1,0,1]
	v_pk_fma_f32 v[122:123], v[234:235], s[28:29], v[122:123] op_sel_hi:[1,0,1]
	v_pk_fma_f32 v[124:125], v[236:237], s[28:29], v[124:125] op_sel_hi:[1,0,1]
	v_pk_fma_f32 v[126:127], v[238:239], s[28:29], v[126:127] op_sel_hi:[1,0,1]
	v_cvt_pk_f32_fp8_e32 v[224:225], v60
	v_cvt_pk_f32_fp8_sdwa v[226:227], v60 src0_sel:WORD_1
	v_cvt_pk_f32_fp8_e32 v[228:229], v61
	v_cvt_pk_f32_fp8_sdwa v[230:231], v61 src0_sel:WORD_1
	v_cvt_pk_f32_fp8_e32 v[232:233], v62
	v_cvt_pk_f32_fp8_sdwa v[234:235], v62 src0_sel:WORD_1
	v_cvt_pk_f32_fp8_e32 v[236:237], v63
	v_cvt_pk_f32_fp8_sdwa v[238:239], v63 src0_sel:WORD_1
	v_pk_fma_f32 v[112:113], v[224:225], s[30:31], v[112:113] op_sel_hi:[1,0,1]
	v_pk_fma_f32 v[114:115], v[226:227], s[30:31], v[114:115] op_sel_hi:[1,0,1]
	v_pk_fma_f32 v[116:117], v[228:229], s[30:31], v[116:117] op_sel_hi:[1,0,1]
	v_pk_fma_f32 v[118:119], v[230:231], s[30:31], v[118:119] op_sel_hi:[1,0,1]
	v_pk_fma_f32 v[120:121], v[232:233], s[30:31], v[120:121] op_sel_hi:[1,0,1]
	v_pk_fma_f32 v[122:123], v[234:235], s[30:31], v[122:123] op_sel_hi:[1,0,1]
	v_pk_fma_f32 v[124:125], v[236:237], s[30:31], v[124:125] op_sel_hi:[1,0,1]
	v_pk_fma_f32 v[126:127], v[238:239], s[30:31], v[126:127] op_sel_hi:[1,0,1]
	v_readlane_b32 s16, v147, s72
	v_readlane_b32 s18, v147, s73
	v_readlane_b32 s20, v147, s74
	v_readlane_b32 s22, v147, s75
	v_readlane_b32 s24, v147, s76
	v_readlane_b32 s26, v147, s77
	v_readlane_b32 s28, v147, s78
	v_readlane_b32 s30, v147, s79
	v_readlane_b32 s48, v157, s72
	v_readlane_b32 s49, v157, s73
	v_readlane_b32 s50, v157, s74
	v_readlane_b32 s51, v157, s75
	v_readlane_b32 s52, v157, s76
	v_readlane_b32 s53, v157, s77
	v_readlane_b32 s54, v157, s78
	v_readlane_b32 s55, v157, s79
	s_add_u32 s32, s0, s48
	s_addc_u32 s33, s1, 0
	s_add_u32 s34, s0, s49
	s_addc_u32 s35, s1, 0
	s_add_u32 s36, s0, s50
	s_addc_u32 s37, s1, 0
	s_add_u32 s38, s0, s51
	s_addc_u32 s39, s1, 0
	s_add_u32 s40, s0, s52
	s_addc_u32 s41, s1, 0
	s_add_u32 s42, s0, s53
	s_addc_u32 s43, s1, 0
	s_add_u32 s44, s0, s54
	s_addc_u32 s45, s1, 0
	s_add_u32 s46, s0, s55
	s_addc_u32 s47, s1, 0
	global_load_dwordx4 v[32:35], v240, s[32:33]
	global_load_dwordx4 v[36:39], v240, s[34:35]
	global_load_dwordx4 v[40:43], v240, s[36:37]
	global_load_dwordx4 v[44:47], v240, s[38:39]
	global_load_dwordx4 v[48:51], v240, s[40:41]
	global_load_dwordx4 v[52:55], v240, s[42:43]
	global_load_dwordx4 v[56:59], v240, s[44:45]
	global_load_dwordx4 v[60:63], v240, s[46:47]
	s_waitcnt vmcnt(24)
	v_cvt_pk_f32_fp8_e32 v[224:225], v160
	v_cvt_pk_f32_fp8_sdwa v[226:227], v160 src0_sel:WORD_1
	v_cvt_pk_f32_fp8_e32 v[228:229], v161
	v_cvt_pk_f32_fp8_sdwa v[230:231], v161 src0_sel:WORD_1
	v_cvt_pk_f32_fp8_e32 v[232:233], v162
	v_cvt_pk_f32_fp8_sdwa v[234:235], v162 src0_sel:WORD_1
	v_cvt_pk_f32_fp8_e32 v[236:237], v163
	v_cvt_pk_f32_fp8_sdwa v[238:239], v163 src0_sel:WORD_1
	v_pk_fma_f32 v[64:65], v[224:225], s[16:17], v[64:65] op_sel_hi:[1,0,1]
	v_pk_fma_f32 v[66:67], v[226:227], s[16:17], v[66:67] op_sel_hi:[1,0,1]
	v_pk_fma_f32 v[68:69], v[228:229], s[16:17], v[68:69] op_sel_hi:[1,0,1]
	v_pk_fma_f32 v[70:71], v[230:231], s[16:17], v[70:71] op_sel_hi:[1,0,1]
	v_pk_fma_f32 v[72:73], v[232:233], s[16:17], v[72:73] op_sel_hi:[1,0,1]
	v_pk_fma_f32 v[74:75], v[234:235], s[16:17], v[74:75] op_sel_hi:[1,0,1]
	v_pk_fma_f32 v[76:77], v[236:237], s[16:17], v[76:77] op_sel_hi:[1,0,1]
	v_pk_fma_f32 v[78:79], v[238:239], s[16:17], v[78:79] op_sel_hi:[1,0,1]
	v_cvt_pk_f32_fp8_e32 v[224:225], v164
	v_cvt_pk_f32_fp8_sdwa v[226:227], v164 src0_sel:WORD_1
	v_cvt_pk_f32_fp8_e32 v[228:229], v165
	v_cvt_pk_f32_fp8_sdwa v[230:231], v165 src0_sel:WORD_1
	v_cvt_pk_f32_fp8_e32 v[232:233], v166
	v_cvt_pk_f32_fp8_sdwa v[234:235], v166 src0_sel:WORD_1
	v_cvt_pk_f32_fp8_e32 v[236:237], v167
	v_cvt_pk_f32_fp8_sdwa v[238:239], v167 src0_sel:WORD_1
	v_pk_fma_f32 v[64:65], v[224:225], s[18:19], v[64:65] op_sel_hi:[1,0,1]
	v_pk_fma_f32 v[66:67], v[226:227], s[18:19], v[66:67] op_sel_hi:[1,0,1]
	v_pk_fma_f32 v[68:69], v[228:229], s[18:19], v[68:69] op_sel_hi:[1,0,1]
	v_pk_fma_f32 v[70:71], v[230:231], s[18:19], v[70:71] op_sel_hi:[1,0,1]
	v_pk_fma_f32 v[72:73], v[232:233], s[18:19], v[72:73] op_sel_hi:[1,0,1]
	v_pk_fma_f32 v[74:75], v[234:235], s[18:19], v[74:75] op_sel_hi:[1,0,1]
	v_pk_fma_f32 v[76:77], v[236:237], s[18:19], v[76:77] op_sel_hi:[1,0,1]
	v_pk_fma_f32 v[78:79], v[238:239], s[18:19], v[78:79] op_sel_hi:[1,0,1]
	v_cvt_pk_f32_fp8_e32 v[224:225], v168
	v_cvt_pk_f32_fp8_sdwa v[226:227], v168 src0_sel:WORD_1
	v_cvt_pk_f32_fp8_e32 v[228:229], v169
	v_cvt_pk_f32_fp8_sdwa v[230:231], v169 src0_sel:WORD_1
; DI void peer_item_v(const Params& p, int item) {
;     ...
;     V_ISSUE(vqa, 0)
; #pragma unroll 1
;     for (int g = 0; g < 16; g += 2) {
;       V_ISSUE(vqb, g + 1)
;       V_CONSUME(vqa, g)
;       if (g + 2 < 16) V_ISSUE(vqa, g + 2)
;       V_CONSUME(vqb, g + 1)
;     }
	v_cvt_pk_f32_fp8_e32 v[232:233], v170
	v_cvt_pk_f32_fp8_sdwa v[234:235], v170 src0_sel:WORD_1
	v_cvt_pk_f32_fp8_e32 v[236:237], v171
	v_cvt_pk_f32_fp8_sdwa v[238:239], v171 src0_sel:WORD_1
	v_pk_fma_f32 v[64:65], v[224:225], s[20:21], v[64:65] op_sel_hi:[1,0,1]
	v_pk_fma_f32 v[66:67], v[226:227], s[20:21], v[66:67] op_sel_hi:[1,0,1]
	v_pk_fma_f32 v[68:69], v[228:229], s[20:21], v[68:69] op_sel_hi:[1,0,1]
	v_pk_fma_f32 v[70:71], v[230:231], s[20:21], v[70:71] op_sel_hi:[1,0,1]
	v_pk_fma_f32 v[72:73], v[232:233], s[20:21], v[72:73] op_sel_hi:[1,0,1]
	v_pk_fma_f32 v[74:75], v[234:235], s[20:21], v[74:75] op_sel_hi:[1,0,1]
	v_pk_fma_f32 v[76:77], v[236:237], s[20:21], v[76:77] op_sel_hi:[1,0,1]
	v_pk_fma_f32 v[78:79], v[238:239], s[20:21], v[78:79] op_sel_hi:[1,0,1]
	v_cvt_pk_f32_fp8_e32 v[224:225], v172
	v_cvt_pk_f32_fp8_sdwa v[226:227], v172 src0_sel:WORD_1
	v_cvt_pk_f32_fp8_e32 v[228:229], v173
	v_cvt_pk_f32_fp8_sdwa v[230:231], v173 src0_sel:WORD_1
	v_cvt_pk_f32_fp8_e32 v[232:233], v174
	v_cvt_pk_f32_fp8_sdwa v[234:235], v174 src0_sel:WORD_1
	v_cvt_pk_f32_fp8_e32 v[236:237], v175
	v_cvt_pk_f32_fp8_sdwa v[238:239], v175 src0_sel:WORD_1
	v_pk_fma_f32 v[64:65], v[224:225], s[22:23], v[64:65] op_sel_hi:[1,0,1]
	v_pk_fma_f32 v[66:67], v[226:227], s[22:23], v[66:67] op_sel_hi:[1,0,1]
	v_pk_fma_f32 v[68:69], v[228:229], s[22:23], v[68:69] op_sel_hi:[1,0,1]
	v_pk_fma_f32 v[70:71], v[230:231], s[22:23], v[70:71] op_sel_hi:[1,0,1]
	v_pk_fma_f32 v[72:73], v[232:233], s[22:23], v[72:73] op_sel_hi:[1,0,1]
	v_pk_fma_f32 v[74:75], v[234:235], s[22:23], v[74:75] op_sel_hi:[1,0,1]
	v_pk_fma_f32 v[76:77], v[236:237], s[22:23], v[76:77] op_sel_hi:[1,0,1]
	v_pk_fma_f32 v[78:79], v[238:239], s[22:23], v[78:79] op_sel_hi:[1,0,1]
	v_cvt_pk_f32_fp8_e32 v[224:225], v176
	v_cvt_pk_f32_fp8_sdwa v[226:227], v176 src0_sel:WORD_1
	v_cvt_pk_f32_fp8_e32 v[228:229], v177
	v_cvt_pk_f32_fp8_sdwa v[230:231], v177 src0_sel:WORD_1
	v_cvt_pk_f32_fp8_e32 v[232:233], v178
	v_cvt_pk_f32_fp8_sdwa v[234:235], v178 src0_sel:WORD_1
	v_cvt_pk_f32_fp8_e32 v[236:237], v179
	v_cvt_pk_f32_fp8_sdwa v[238:239], v179 src0_sel:WORD_1
	v_pk_fma_f32 v[64:65], v[224:225], s[24:25], v[64:65] op_sel_hi:[1,0,1]
	v_pk_fma_f32 v[66:67], v[226:227], s[24:25], v[66:67] op_sel_hi:[1,0,1]
	v_pk_fma_f32 v[68:69], v[228:229], s[24:25], v[68:69] op_sel_hi:[1,0,1]
	v_pk_fma_f32 v[70:71], v[230:231], s[24:25], v[70:71] op_sel_hi:[1,0,1]
	v_pk_fma_f32 v[72:73], v[232:233], s[24:25], v[72:73] op_sel_hi:[1,0,1]
	v_pk_fma_f32 v[74:75], v[234:235], s[24:25], v[74:75] op_sel_hi:[1,0,1]
	v_pk_fma_f32 v[76:77], v[236:237], s[24:25], v[76:77] op_sel_hi:[1,0,1]
	v_pk_fma_f32 v[78:79], v[238:239], s[24:25], v[78:79] op_sel_hi:[1,0,1]
	v_cvt_pk_f32_fp8_e32 v[224:225], v180
	v_cvt_pk_f32_fp8_sdwa v[226:227], v180 src0_sel:WORD_1
	v_cvt_pk_f32_fp8_e32 v[228:229], v181
	v_cvt_pk_f32_fp8_sdwa v[230:231], v181 src0_sel:WORD_1
	v_cvt_pk_f32_fp8_e32 v[232:233], v182
	v_cvt_pk_f32_fp8_sdwa v[234:235], v182 src0_sel:WORD_1
	v_cvt_pk_f32_fp8_e32 v[236:237], v183
	v_cvt_pk_f32_fp8_sdwa v[238:239], v183 src0_sel:WORD_1
	v_pk_fma_f32 v[64:65], v[224:225], s[26:27], v[64:65] op_sel_hi:[1,0,1]
	v_pk_fma_f32 v[66:67], v[226:227], s[26:27], v[66:67] op_sel_hi:[1,0,1]
	v_pk_fma_f32 v[68:69], v[228:229], s[26:27], v[68:69] op_sel_hi:[1,0,1]
	v_pk_fma_f32 v[70:71], v[230:231], s[26:27], v[70:71] op_sel_hi:[1,0,1]
	v_pk_fma_f32 v[72:73], v[232:233], s[26:27], v[72:73] op_sel_hi:[1,0,1]
	v_pk_fma_f32 v[74:75], v[234:235], s[26:27], v[74:75] op_sel_hi:[1,0,1]
	v_pk_fma_f32 v[76:77], v[236:237], s[26:27], v[76:77] op_sel_hi:[1,0,1]
	v_pk_fma_f32 v[78:79], v[238:239], s[26:27], v[78:79] op_sel_hi:[1,0,1]
	v_cvt_pk_f32_fp8_e32 v[224:225], v184
	v_cvt_pk_f32_fp8_sdwa v[226:227], v184 src0_sel:WORD_1
	v_cvt_pk_f32_fp8_e32 v[228:229], v185
	v_cvt_pk_f32_fp8_sdwa v[230:231], v185 src0_sel:WORD_1
	v_cvt_pk_f32_fp8_e32 v[232:233], v186
	v_cvt_pk_f32_fp8_sdwa v[234:235], v186 src0_sel:WORD_1
	v_cvt_pk_f32_fp8_e32 v[236:237], v187
	v_cvt_pk_f32_fp8_sdwa v[238:239], v187 src0_sel:WORD_1
	v_pk_fma_f32 v[64:65], v[224:225], s[28:29], v[64:65] op_sel_hi:[1,0,1]
	v_pk_fma_f32 v[66:67], v[226:227], s[28:29], v[66:67] op_sel_hi:[1,0,1]
	v_pk_fma_f32 v[68:69], v[228:229], s[28:29], v[68:69] op_sel_hi:[1,0,1]
	v_pk_fma_f32 v[70:71], v[230:231], s[28:29], v[70:71] op_sel_hi:[1,0,1]
	v_pk_fma_f32 v[72:73], v[232:233], s[28:29], v[72:73] op_sel_hi:[1,0,1]
	v_pk_fma_f32 v[74:75], v[234:235], s[28:29], v[74:75] op_sel_hi:[1,0,1]
	v_pk_fma_f32 v[76:77], v[236:237], s[28:29], v[76:77] op_sel_hi:[1,0,1]
	v_pk_fma_f32 v[78:79], v[238:239], s[28:29], v[78:79] op_sel_hi:[1,0,1]
	v_cvt_pk_f32_fp8_e32 v[224:225], v188
	v_cvt_pk_f32_fp8_sdwa v[226:227], v188 src0_sel:WORD_1
	v_cvt_pk_f32_fp8_e32 v[228:229], v189
	v_cvt_pk_f32_fp8_sdwa v[230:231], v189 src0_sel:WORD_1
	v_cvt_pk_f32_fp8_e32 v[232:233], v190
	v_cvt_pk_f32_fp8_sdwa v[234:235], v190 src0_sel:WORD_1
	v_cvt_pk_f32_fp8_e32 v[236:237], v191
	v_cvt_pk_f32_fp8_sdwa v[238:239], v191 src0_sel:WORD_1
	v_pk_fma_f32 v[64:65], v[224:225], s[30:31], v[64:65] op_sel_hi:[1,0,1]
	v_pk_fma_f32 v[66:67], v[226:227], s[30:31], v[66:67] op_sel_hi:[1,0,1]
	v_pk_fma_f32 v[68:69], v[228:229], s[30:31], v[68:69] op_sel_hi:[1,0,1]
	v_pk_fma_f32 v[70:71], v[230:231], s[30:31], v[70:71] op_sel_hi:[1,0,1]
	v_pk_fma_f32 v[72:73], v[232:233], s[30:31], v[72:73] op_sel_hi:[1,0,1]
	v_pk_fma_f32 v[74:75], v[234:235], s[30:31], v[74:75] op_sel_hi:[1,0,1]
	v_pk_fma_f32 v[76:77], v[236:237], s[30:31], v[76:77] op_sel_hi:[1,0,1]
	v_pk_fma_f32 v[78:79], v[238:239], s[30:31], v[78:79] op_sel_hi:[1,0,1]
	v_readlane_b32 s16, v151, s72
	v_readlane_b32 s18, v151, s73
	v_readlane_b32 s20, v151, s74
	v_readlane_b32 s22, v151, s75
	v_readlane_b32 s24, v151, s76
	v_readlane_b32 s26, v151, s77
	v_readlane_b32 s28, v151, s78
	v_readlane_b32 s30, v151, s79
	s_cmp_eq_u32 s12, 7
	s_cbranch_scc1 .Lvd_last5_Lvq_kB
	v_readlane_b32 s48, v144, s80
	v_readlane_b32 s49, v144, s81
	v_readlane_b32 s50, v144, s82
	v_readlane_b32 s51, v144, s83
	v_readlane_b32 s52, v144, s84
	v_readlane_b32 s53, v144, s85
	v_readlane_b32 s54, v144, s86
	v_readlane_b32 s55, v144, s87
	s_add_u32 s32, s0, s48
	s_addc_u32 s33, s1, 0
	s_add_u32 s34, s0, s49
	s_addc_u32 s35, s1, 0
	s_add_u32 s36, s0, s50
	s_addc_u32 s37, s1, 0
	s_add_u32 s38, s0, s51
	s_addc_u32 s39, s1, 0
	s_add_u32 s40, s0, s52
	s_addc_u32 s41, s1, 0
	s_add_u32 s42, s0, s53
	s_addc_u32 s43, s1, 0
	s_add_u32 s44, s0, s54
	s_addc_u32 s45, s1, 0
	s_add_u32 s46, s0, s55
	s_addc_u32 s47, s1, 0
	global_load_dwordx4 v[160:163], v240, s[32:33]
	global_load_dwordx4 v[164:167], v240, s[34:35]
	global_load_dwordx4 v[168:171], v240, s[36:37]
	global_load_dwordx4 v[172:175], v240, s[38:39]
	global_load_dwordx4 v[176:179], v240, s[40:41]
	global_load_dwordx4 v[180:183], v240, s[42:43]
	global_load_dwordx4 v[184:187], v240, s[44:45]
	global_load_dwordx4 v[188:191], v240, s[46:47]
	s_waitcnt vmcnt(24)
	s_branch .Lvd_cons5_Lvq_kB

; DI void peer_item_v(const Params& p, int item) {
;     ...
;     V_ISSUE(vqa, 0)
; #pragma unroll 1
;     for (int g = 0; g < 16; g += 2) {
;       V_ISSUE(vqb, g + 1)
;       V_CONSUME(vqa, g)
;       if (g + 2 < 16) V_ISSUE(vqa, g + 2)
;       V_CONSUME(vqb, g + 1)
;     }
.Lvd_cons5_Lvq_kB:
	v_cvt_pk_f32_fp8_e32 v[224:225], v192
	v_cvt_pk_f32_fp8_sdwa v[226:227], v192 src0_sel:WORD_1
	v_cvt_pk_f32_fp8_e32 v[228:229], v193
	v_cvt_pk_f32_fp8_sdwa v[230:231], v193 src0_sel:WORD_1
	v_cvt_pk_f32_fp8_e32 v[232:233], v194
	v_cvt_pk_f32_fp8_sdwa v[234:235], v194 src0_sel:WORD_1
	v_cvt_pk_f32_fp8_e32 v[236:237], v195
	v_cvt_pk_f32_fp8_sdwa v[238:239], v195 src0_sel:WORD_1
	v_pk_fma_f32 v[80:81], v[224:225], s[16:17], v[80:81] op_sel_hi:[1,0,1]
	v_pk_fma_f32 v[82:83], v[226:227], s[16:17], v[82:83] op_sel_hi:[1,0,1]
	v_pk_fma_f32 v[84:85], v[228:229], s[16:17], v[84:85] op_sel_hi:[1,0,1]
	v_pk_fma_f32 v[86:87], v[230:231], s[16:17], v[86:87] op_sel_hi:[1,0,1]
	v_pk_fma_f32 v[88:89], v[232:233], s[16:17], v[88:89] op_sel_hi:[1,0,1]
	v_pk_fma_f32 v[90:91], v[234:235], s[16:17], v[90:91] op_sel_hi:[1,0,1]
	v_pk_fma_f32 v[92:93], v[236:237], s[16:17], v[92:93] op_sel_hi:[1,0,1]
	v_pk_fma_f32 v[94:95], v[238:239], s[16:17], v[94:95] op_sel_hi:[1,0,1]
	v_cvt_pk_f32_fp8_e32 v[224:225], v196
	v_cvt_pk_f32_fp8_sdwa v[226:227], v196 src0_sel:WORD_1
	v_cvt_pk_f32_fp8_e32 v[228:229], v197
	v_cvt_pk_f32_fp8_sdwa v[230:231], v197 src0_sel:WORD_1
	v_cvt_pk_f32_fp8_e32 v[232:233], v198
	v_cvt_pk_f32_fp8_sdwa v[234:235], v198 src0_sel:WORD_1
	v_cvt_pk_f32_fp8_e32 v[236:237], v199
	v_cvt_pk_f32_fp8_sdwa v[238:239], v199 src0_sel:WORD_1
	v_pk_fma_f32 v[80:81], v[224:225], s[18:19], v[80:81] op_sel_hi:[1,0,1]
	v_pk_fma_f32 v[82:83], v[226:227], s[18:19], v[82:83] op_sel_hi:[1,0,1]
	v_pk_fma_f32 v[84:85], v[228:229], s[18:19], v[84:85] op_sel_hi:[1,0,1]
	v_pk_fma_f32 v[86:87], v[230:231], s[18:19], v[86:87] op_sel_hi:[1,0,1]
	v_pk_fma_f32 v[88:89], v[232:233], s[18:19], v[88:89] op_sel_hi:[1,0,1]
	v_pk_fma_f32 v[90:91], v[234:235], s[18:19], v[90:91] op_sel_hi:[1,0,1]
	v_pk_fma_f32 v[92:93], v[236:237], s[18:19], v[92:93] op_sel_hi:[1,0,1]
	v_pk_fma_f32 v[94:95], v[238:239], s[18:19], v[94:95] op_sel_hi:[1,0,1]
	v_cvt_pk_f32_fp8_e32 v[224:225], v200
	v_cvt_pk_f32_fp8_sdwa v[226:227], v200 src0_sel:WORD_1
	v_cvt_pk_f32_fp8_e32 v[228:229], v201
	v_cvt_pk_f32_fp8_sdwa v[230:231], v201 src0_sel:WORD_1
	v_cvt_pk_f32_fp8_e32 v[232:233], v202
	v_cvt_pk_f32_fp8_sdwa v[234:235], v202 src0_sel:WORD_1
	v_cvt_pk_f32_fp8_e32 v[236:237], v203
	v_cvt_pk_f32_fp8_sdwa v[238:239], v203 src0_sel:WORD_1
	v_pk_fma_f32 v[80:81], v[224:225], s[20:21], v[80:81] op_sel_hi:[1,0,1]
	v_pk_fma_f32 v[82:83], v[226:227], s[20:21], v[82:83] op_sel_hi:[1,0,1]
	v_pk_fma_f32 v[84:85], v[228:229], s[20:21], v[84:85] op_sel_hi:[1,0,1]
	v_pk_fma_f32 v[86:87], v[230:231], s[20:21], v[86:87] op_sel_hi:[1,0,1]
	v_pk_fma_f32 v[88:89], v[232:233], s[20:21], v[88:89] op_sel_hi:[1,0,1]
	v_pk_fma_f32 v[90:91], v[234:235], s[20:21], v[90:91] op_sel_hi:[1,0,1]
	v_pk_fma_f32 v[92:93], v[236:237], s[20:21], v[92:93] op_sel_hi:[1,0,1]
	v_pk_fma_f32 v[94:95], v[238:239], s[20:21], v[94:95] op_sel_hi:[1,0,1]
	v_cvt_pk_f32_fp8_e32 v[224:225], v204
	v_cvt_pk_f32_fp8_sdwa v[226:227], v204 src0_sel:WORD_1
	v_cvt_pk_f32_fp8_e32 v[228:229], v205
	v_cvt_pk_f32_fp8_sdwa v[230:231], v205 src0_sel:WORD_1
	v_cvt_pk_f32_fp8_e32 v[232:233], v206
	v_cvt_pk_f32_fp8_sdwa v[234:235], v206 src0_sel:WORD_1
	v_cvt_pk_f32_fp8_e32 v[236:237], v207
	v_cvt_pk_f32_fp8_sdwa v[238:239], v207 src0_sel:WORD_1
	v_pk_fma_f32 v[80:81], v[224:225], s[22:23], v[80:81] op_sel_hi:[1,0,1]
	v_pk_fma_f32 v[82:83], v[226:227], s[22:23], v[82:83] op_sel_hi:[1,0,1]
	v_pk_fma_f32 v[84:85], v[228:229], s[22:23], v[84:85] op_sel_hi:[1,0,1]
	v_pk_fma_f32 v[86:87], v[230:231], s[22:23], v[86:87] op_sel_hi:[1,0,1]
	v_pk_fma_f32 v[88:89], v[232:233], s[22:23], v[88:89] op_sel_hi:[1,0,1]
	v_pk_fma_f32 v[90:91], v[234:235], s[22:23], v[90:91] op_sel_hi:[1,0,1]
	v_pk_fma_f32 v[92:93], v[236:237], s[22:23], v[92:93] op_sel_hi:[1,0,1]
	v_pk_fma_f32 v[94:95], v[238:239], s[22:23], v[94:95] op_sel_hi:[1,0,1]
	v_cvt_pk_f32_fp8_e32 v[224:225], v208
	v_cvt_pk_f32_fp8_sdwa v[226:227], v208 src0_sel:WORD_1
	v_cvt_pk_f32_fp8_e32 v[228:229], v209
	v_cvt_pk_f32_fp8_sdwa v[230:231], v209 src0_sel:WORD_1
	v_cvt_pk_f32_fp8_e32 v[232:233], v210
	v_cvt_pk_f32_fp8_sdwa v[234:235], v210 src0_sel:WORD_1
	v_cvt_pk_f32_fp8_e32 v[236:237], v211
	v_cvt_pk_f32_fp8_sdwa v[238:239], v211 src0_sel:WORD_1
	v_pk_fma_f32 v[80:81], v[224:225], s[24:25], v[80:81] op_sel_hi:[1,0,1]
	v_pk_fma_f32 v[82:83], v[226:227], s[24:25], v[82:83] op_sel_hi:[1,0,1]
	v_pk_fma_f32 v[84:85], v[228:229], s[24:25], v[84:85] op_sel_hi:[1,0,1]
	v_pk_fma_f32 v[86:87], v[230:231], s[24:25], v[86:87] op_sel_hi:[1,0,1]
; DI void peer_item_v(const Params& p, int item) {
;     ...
;     V_ISSUE(vqa, 0)
; #pragma unroll 1
;     for (int g = 0; g < 16; g += 2) {
;       V_ISSUE(vqb, g + 1)
;       V_CONSUME(vqa, g)
;       if (g + 2 < 16) V_ISSUE(vqa, g + 2)
;       V_CONSUME(vqb, g + 1)
;     }
	v_pk_fma_f32 v[88:89], v[232:233], s[24:25], v[88:89] op_sel_hi:[1,0,1]
	v_pk_fma_f32 v[90:91], v[234:235], s[24:25], v[90:91] op_sel_hi:[1,0,1]
	v_pk_fma_f32 v[92:93], v[236:237], s[24:25], v[92:93] op_sel_hi:[1,0,1]
	v_pk_fma_f32 v[94:95], v[238:239], s[24:25], v[94:95] op_sel_hi:[1,0,1]
	v_cvt_pk_f32_fp8_e32 v[224:225], v212
	v_cvt_pk_f32_fp8_sdwa v[226:227], v212 src0_sel:WORD_1
	v_cvt_pk_f32_fp8_e32 v[228:229], v213
	v_cvt_pk_f32_fp8_sdwa v[230:231], v213 src0_sel:WORD_1
	v_cvt_pk_f32_fp8_e32 v[232:233], v214
	v_cvt_pk_f32_fp8_sdwa v[234:235], v214 src0_sel:WORD_1
	v_cvt_pk_f32_fp8_e32 v[236:237], v215
	v_cvt_pk_f32_fp8_sdwa v[238:239], v215 src0_sel:WORD_1
	v_pk_fma_f32 v[80:81], v[224:225], s[26:27], v[80:81] op_sel_hi:[1,0,1]
	v_pk_fma_f32 v[82:83], v[226:227], s[26:27], v[82:83] op_sel_hi:[1,0,1]
	v_pk_fma_f32 v[84:85], v[228:229], s[26:27], v[84:85] op_sel_hi:[1,0,1]
	v_pk_fma_f32 v[86:87], v[230:231], s[26:27], v[86:87] op_sel_hi:[1,0,1]
	v_pk_fma_f32 v[88:89], v[232:233], s[26:27], v[88:89] op_sel_hi:[1,0,1]
	v_pk_fma_f32 v[90:91], v[234:235], s[26:27], v[90:91] op_sel_hi:[1,0,1]
	v_pk_fma_f32 v[92:93], v[236:237], s[26:27], v[92:93] op_sel_hi:[1,0,1]
	v_pk_fma_f32 v[94:95], v[238:239], s[26:27], v[94:95] op_sel_hi:[1,0,1]
	v_cvt_pk_f32_fp8_e32 v[224:225], v216
	v_cvt_pk_f32_fp8_sdwa v[226:227], v216 src0_sel:WORD_1
	v_cvt_pk_f32_fp8_e32 v[228:229], v217
	v_cvt_pk_f32_fp8_sdwa v[230:231], v217 src0_sel:WORD_1
	v_cvt_pk_f32_fp8_e32 v[232:233], v218
	v_cvt_pk_f32_fp8_sdwa v[234:235], v218 src0_sel:WORD_1
	v_cvt_pk_f32_fp8_e32 v[236:237], v219
	v_cvt_pk_f32_fp8_sdwa v[238:239], v219 src0_sel:WORD_1
	v_pk_fma_f32 v[80:81], v[224:225], s[28:29], v[80:81] op_sel_hi:[1,0,1]
	v_pk_fma_f32 v[82:83], v[226:227], s[28:29], v[82:83] op_sel_hi:[1,0,1]
	v_pk_fma_f32 v[84:85], v[228:229], s[28:29], v[84:85] op_sel_hi:[1,0,1]
	v_pk_fma_f32 v[86:87], v[230:231], s[28:29], v[86:87] op_sel_hi:[1,0,1]
	v_pk_fma_f32 v[88:89], v[232:233], s[28:29], v[88:89] op_sel_hi:[1,0,1]
	v_pk_fma_f32 v[90:91], v[234:235], s[28:29], v[90:91] op_sel_hi:[1,0,1]
	v_pk_fma_f32 v[92:93], v[236:237], s[28:29], v[92:93] op_sel_hi:[1,0,1]
	v_pk_fma_f32 v[94:95], v[238:239], s[28:29], v[94:95] op_sel_hi:[1,0,1]
	v_cvt_pk_f32_fp8_e32 v[224:225], v220
	v_cvt_pk_f32_fp8_sdwa v[226:227], v220 src0_sel:WORD_1
	v_cvt_pk_f32_fp8_e32 v[228:229], v221
	v_cvt_pk_f32_fp8_sdwa v[230:231], v221 src0_sel:WORD_1
	v_cvt_pk_f32_fp8_e32 v[232:233], v222
	v_cvt_pk_f32_fp8_sdwa v[234:235], v222 src0_sel:WORD_1
	v_cvt_pk_f32_fp8_e32 v[236:237], v223
	v_cvt_pk_f32_fp8_sdwa v[238:239], v223 src0_sel:WORD_1
	v_pk_fma_f32 v[80:81], v[224:225], s[30:31], v[80:81] op_sel_hi:[1,0,1]
	v_pk_fma_f32 v[82:83], v[226:227], s[30:31], v[82:83] op_sel_hi:[1,0,1]
	v_pk_fma_f32 v[84:85], v[228:229], s[30:31], v[84:85] op_sel_hi:[1,0,1]
	v_pk_fma_f32 v[86:87], v[230:231], s[30:31], v[86:87] op_sel_hi:[1,0,1]
	v_pk_fma_f32 v[88:89], v[232:233], s[30:31], v[88:89] op_sel_hi:[1,0,1]
	v_pk_fma_f32 v[90:91], v[234:235], s[30:31], v[90:91] op_sel_hi:[1,0,1]
	v_pk_fma_f32 v[92:93], v[236:237], s[30:31], v[92:93] op_sel_hi:[1,0,1]
	v_pk_fma_f32 v[94:95], v[238:239], s[30:31], v[94:95] op_sel_hi:[1,0,1]
	v_readlane_b32 s16, v155, s72
	v_readlane_b32 s18, v155, s73
	v_readlane_b32 s20, v155, s74
	v_readlane_b32 s22, v155, s75
	v_readlane_b32 s24, v155, s76
	v_readlane_b32 s26, v155, s77
	v_readlane_b32 s28, v155, s78
	v_readlane_b32 s30, v155, s79
	s_cmp_eq_u32 s12, 7
	s_cbranch_scc1 .Lvd_last6_Lvq_kB
	v_readlane_b32 s48, v148, s80
	v_readlane_b32 s49, v148, s81
	v_readlane_b32 s50, v148, s82
	v_readlane_b32 s51, v148, s83
	v_readlane_b32 s52, v148, s84
	v_readlane_b32 s53, v148, s85
	v_readlane_b32 s54, v148, s86
	v_readlane_b32 s55, v148, s87
	s_add_u32 s32, s0, s48
	s_addc_u32 s33, s1, 0
	s_add_u32 s34, s0, s49
	s_addc_u32 s35, s1, 0
	s_add_u32 s36, s0, s50
	s_addc_u32 s37, s1, 0
	s_add_u32 s38, s0, s51
	s_addc_u32 s39, s1, 0
	s_add_u32 s40, s0, s52
	s_addc_u32 s41, s1, 0
	s_add_u32 s42, s0, s53
	s_addc_u32 s43, s1, 0
	s_add_u32 s44, s0, s54
	s_addc_u32 s45, s1, 0
	s_add_u32 s46, s0, s55
	s_addc_u32 s47, s1, 0
	global_load_dwordx4 v[192:195], v240, s[32:33]
	global_load_dwordx4 v[196:199], v240, s[34:35]
	global_load_dwordx4 v[200:203], v240, s[36:37]
	global_load_dwordx4 v[204:207], v240, s[38:39]
	global_load_dwordx4 v[208:211], v240, s[40:41]
	global_load_dwordx4 v[212:215], v240, s[42:43]
	global_load_dwordx4 v[216:219], v240, s[44:45]
	global_load_dwordx4 v[220:223], v240, s[46:47]
	s_waitcnt vmcnt(24)
	s_branch .Lvd_cons6_Lvq_kB

; DI void peer_item_v(const Params& p, int item) {
;     ...
;     V_ISSUE(vqa, 0)
; #pragma unroll 1
;     for (int g = 0; g < 16; g += 2) {
;       V_ISSUE(vqb, g + 1)
;       V_CONSUME(vqa, g)
;       if (g + 2 < 16) V_ISSUE(vqa, g + 2)
;       V_CONSUME(vqb, g + 1)
;     }
.Lvd_cons6_Lvq_kB:
	v_cvt_pk_f32_fp8_e32 v[224:225], v0
	v_cvt_pk_f32_fp8_sdwa v[226:227], v0 src0_sel:WORD_1
	v_cvt_pk_f32_fp8_e32 v[228:229], v1
	v_cvt_pk_f32_fp8_sdwa v[230:231], v1 src0_sel:WORD_1
	v_cvt_pk_f32_fp8_e32 v[232:233], v2
	v_cvt_pk_f32_fp8_sdwa v[234:235], v2 src0_sel:WORD_1
	v_cvt_pk_f32_fp8_e32 v[236:237], v3
	v_cvt_pk_f32_fp8_sdwa v[238:239], v3 src0_sel:WORD_1
	v_pk_fma_f32 v[96:97], v[224:225], s[16:17], v[96:97] op_sel_hi:[1,0,1]
	v_pk_fma_f32 v[98:99], v[226:227], s[16:17], v[98:99] op_sel_hi:[1,0,1]
	v_pk_fma_f32 v[100:101], v[228:229], s[16:17], v[100:101] op_sel_hi:[1,0,1]
	v_pk_fma_f32 v[102:103], v[230:231], s[16:17], v[102:103] op_sel_hi:[1,0,1]
	v_pk_fma_f32 v[104:105], v[232:233], s[16:17], v[104:105] op_sel_hi:[1,0,1]
	v_pk_fma_f32 v[106:107], v[234:235], s[16:17], v[106:107] op_sel_hi:[1,0,1]
	v_pk_fma_f32 v[108:109], v[236:237], s[16:17], v[108:109] op_sel_hi:[1,0,1]
	v_pk_fma_f32 v[110:111], v[238:239], s[16:17], v[110:111] op_sel_hi:[1,0,1]
	v_cvt_pk_f32_fp8_e32 v[224:225], v4
	v_cvt_pk_f32_fp8_sdwa v[226:227], v4 src0_sel:WORD_1
	v_cvt_pk_f32_fp8_e32 v[228:229], v5
	v_cvt_pk_f32_fp8_sdwa v[230:231], v5 src0_sel:WORD_1
	v_cvt_pk_f32_fp8_e32 v[232:233], v6
	v_cvt_pk_f32_fp8_sdwa v[234:235], v6 src0_sel:WORD_1
	v_cvt_pk_f32_fp8_e32 v[236:237], v7
	v_cvt_pk_f32_fp8_sdwa v[238:239], v7 src0_sel:WORD_1
	v_pk_fma_f32 v[96:97], v[224:225], s[18:19], v[96:97] op_sel_hi:[1,0,1]
	v_pk_fma_f32 v[98:99], v[226:227], s[18:19], v[98:99] op_sel_hi:[1,0,1]
	v_pk_fma_f32 v[100:101], v[228:229], s[18:19], v[100:101] op_sel_hi:[1,0,1]
	v_pk_fma_f32 v[102:103], v[230:231], s[18:19], v[102:103] op_sel_hi:[1,0,1]
	v_pk_fma_f32 v[104:105], v[232:233], s[18:19], v[104:105] op_sel_hi:[1,0,1]
	v_pk_fma_f32 v[106:107], v[234:235], s[18:19], v[106:107] op_sel_hi:[1,0,1]
	v_pk_fma_f32 v[108:109], v[236:237], s[18:19], v[108:109] op_sel_hi:[1,0,1]
	v_pk_fma_f32 v[110:111], v[238:239], s[18:19], v[110:111] op_sel_hi:[1,0,1]
	v_cvt_pk_f32_fp8_e32 v[224:225], v8
	v_cvt_pk_f32_fp8_sdwa v[226:227], v8 src0_sel:WORD_1
	v_cvt_pk_f32_fp8_e32 v[228:229], v9
	v_cvt_pk_f32_fp8_sdwa v[230:231], v9 src0_sel:WORD_1
	v_cvt_pk_f32_fp8_e32 v[232:233], v10
	v_cvt_pk_f32_fp8_sdwa v[234:235], v10 src0_sel:WORD_1
	v_cvt_pk_f32_fp8_e32 v[236:237], v11
	v_cvt_pk_f32_fp8_sdwa v[238:239], v11 src0_sel:WORD_1
	v_pk_fma_f32 v[96:97], v[224:225], s[20:21], v[96:97] op_sel_hi:[1,0,1]
	v_pk_fma_f32 v[98:99], v[226:227], s[20:21], v[98:99] op_sel_hi:[1,0,1]
	v_pk_fma_f32 v[100:101], v[228:229], s[20:21], v[100:101] op_sel_hi:[1,0,1]
	v_pk_fma_f32 v[102:103], v[230:231], s[20:21], v[102:103] op_sel_hi:[1,0,1]
	v_pk_fma_f32 v[104:105], v[232:233], s[20:21], v[104:105] op_sel_hi:[1,0,1]
	v_pk_fma_f32 v[106:107], v[234:235], s[20:21], v[106:107] op_sel_hi:[1,0,1]
	v_pk_fma_f32 v[108:109], v[236:237], s[20:21], v[108:109] op_sel_hi:[1,0,1]
	v_pk_fma_f32 v[110:111], v[238:239], s[20:21], v[110:111] op_sel_hi:[1,0,1]
	v_cvt_pk_f32_fp8_e32 v[224:225], v12
	v_cvt_pk_f32_fp8_sdwa v[226:227], v12 src0_sel:WORD_1
	v_cvt_pk_f32_fp8_e32 v[228:229], v13
	v_cvt_pk_f32_fp8_sdwa v[230:231], v13 src0_sel:WORD_1
	v_cvt_pk_f32_fp8_e32 v[232:233], v14
	v_cvt_pk_f32_fp8_sdwa v[234:235], v14 src0_sel:WORD_1
	v_cvt_pk_f32_fp8_e32 v[236:237], v15
	v_cvt_pk_f32_fp8_sdwa v[238:239], v15 src0_sel:WORD_1
	v_pk_fma_f32 v[96:97], v[224:225], s[22:23], v[96:97] op_sel_hi:[1,0,1]
	v_pk_fma_f32 v[98:99], v[226:227], s[22:23], v[98:99] op_sel_hi:[1,0,1]
	v_pk_fma_f32 v[100:101], v[228:229], s[22:23], v[100:101] op_sel_hi:[1,0,1]
	v_pk_fma_f32 v[102:103], v[230:231], s[22:23], v[102:103] op_sel_hi:[1,0,1]
	v_pk_fma_f32 v[104:105], v[232:233], s[22:23], v[104:105] op_sel_hi:[1,0,1]
	v_pk_fma_f32 v[106:107], v[234:235], s[22:23], v[106:107] op_sel_hi:[1,0,1]
	v_pk_fma_f32 v[108:109], v[236:237], s[22:23], v[108:109] op_sel_hi:[1,0,1]
	v_pk_fma_f32 v[110:111], v[238:239], s[22:23], v[110:111] op_sel_hi:[1,0,1]
	v_cvt_pk_f32_fp8_e32 v[224:225], v16
	v_cvt_pk_f32_fp8_sdwa v[226:227], v16 src0_sel:WORD_1
	v_cvt_pk_f32_fp8_e32 v[228:229], v17
	v_cvt_pk_f32_fp8_sdwa v[230:231], v17 src0_sel:WORD_1
	v_cvt_pk_f32_fp8_e32 v[232:233], v18
	v_cvt_pk_f32_fp8_sdwa v[234:235], v18 src0_sel:WORD_1
	v_cvt_pk_f32_fp8_e32 v[236:237], v19
	v_cvt_pk_f32_fp8_sdwa v[238:239], v19 src0_sel:WORD_1
	v_pk_fma_f32 v[96:97], v[224:225], s[24:25], v[96:97] op_sel_hi:[1,0,1]
	v_pk_fma_f32 v[98:99], v[226:227], s[24:25], v[98:99] op_sel_hi:[1,0,1]
	v_pk_fma_f32 v[100:101], v[228:229], s[24:25], v[100:101] op_sel_hi:[1,0,1]
	v_pk_fma_f32 v[102:103], v[230:231], s[24:25], v[102:103] op_sel_hi:[1,0,1]
; DI void peer_item_v(const Params& p, int item) {
;     ...
;     V_ISSUE(vqa, 0)
; #pragma unroll 1
;     for (int g = 0; g < 16; g += 2) {
;       V_ISSUE(vqb, g + 1)
;       V_CONSUME(vqa, g)
;       if (g + 2 < 16) V_ISSUE(vqa, g + 2)
;       V_CONSUME(vqb, g + 1)
;     }
	v_pk_fma_f32 v[104:105], v[232:233], s[24:25], v[104:105] op_sel_hi:[1,0,1]
	v_pk_fma_f32 v[106:107], v[234:235], s[24:25], v[106:107] op_sel_hi:[1,0,1]
	v_pk_fma_f32 v[108:109], v[236:237], s[24:25], v[108:109] op_sel_hi:[1,0,1]
	v_pk_fma_f32 v[110:111], v[238:239], s[24:25], v[110:111] op_sel_hi:[1,0,1]
	v_cvt_pk_f32_fp8_e32 v[224:225], v20
	v_cvt_pk_f32_fp8_sdwa v[226:227], v20 src0_sel:WORD_1
	v_cvt_pk_f32_fp8_e32 v[228:229], v21
	v_cvt_pk_f32_fp8_sdwa v[230:231], v21 src0_sel:WORD_1
	v_cvt_pk_f32_fp8_e32 v[232:233], v22
	v_cvt_pk_f32_fp8_sdwa v[234:235], v22 src0_sel:WORD_1
	v_cvt_pk_f32_fp8_e32 v[236:237], v23
	v_cvt_pk_f32_fp8_sdwa v[238:239], v23 src0_sel:WORD_1
	v_pk_fma_f32 v[96:97], v[224:225], s[26:27], v[96:97] op_sel_hi:[1,0,1]
	v_pk_fma_f32 v[98:99], v[226:227], s[26:27], v[98:99] op_sel_hi:[1,0,1]
	v_pk_fma_f32 v[100:101], v[228:229], s[26:27], v[100:101] op_sel_hi:[1,0,1]
	v_pk_fma_f32 v[102:103], v[230:231], s[26:27], v[102:103] op_sel_hi:[1,0,1]
	v_pk_fma_f32 v[104:105], v[232:233], s[26:27], v[104:105] op_sel_hi:[1,0,1]
	v_pk_fma_f32 v[106:107], v[234:235], s[26:27], v[106:107] op_sel_hi:[1,0,1]
	v_pk_fma_f32 v[108:109], v[236:237], s[26:27], v[108:109] op_sel_hi:[1,0,1]
	v_pk_fma_f32 v[110:111], v[238:239], s[26:27], v[110:111] op_sel_hi:[1,0,1]
	v_cvt_pk_f32_fp8_e32 v[224:225], v24
	v_cvt_pk_f32_fp8_sdwa v[226:227], v24 src0_sel:WORD_1
	v_cvt_pk_f32_fp8_e32 v[228:229], v25
	v_cvt_pk_f32_fp8_sdwa v[230:231], v25 src0_sel:WORD_1
	v_cvt_pk_f32_fp8_e32 v[232:233], v26
	v_cvt_pk_f32_fp8_sdwa v[234:235], v26 src0_sel:WORD_1
	v_cvt_pk_f32_fp8_e32 v[236:237], v27
	v_cvt_pk_f32_fp8_sdwa v[238:239], v27 src0_sel:WORD_1
	v_pk_fma_f32 v[96:97], v[224:225], s[28:29], v[96:97] op_sel_hi:[1,0,1]
	v_pk_fma_f32 v[98:99], v[226:227], s[28:29], v[98:99] op_sel_hi:[1,0,1]
	v_pk_fma_f32 v[100:101], v[228:229], s[28:29], v[100:101] op_sel_hi:[1,0,1]
	v_pk_fma_f32 v[102:103], v[230:231], s[28:29], v[102:103] op_sel_hi:[1,0,1]
	v_pk_fma_f32 v[104:105], v[232:233], s[28:29], v[104:105] op_sel_hi:[1,0,1]
	v_pk_fma_f32 v[106:107], v[234:235], s[28:29], v[106:107] op_sel_hi:[1,0,1]
	v_pk_fma_f32 v[108:109], v[236:237], s[28:29], v[108:109] op_sel_hi:[1,0,1]
	v_pk_fma_f32 v[110:111], v[238:239], s[28:29], v[110:111] op_sel_hi:[1,0,1]
	v_cvt_pk_f32_fp8_e32 v[224:225], v28
	v_cvt_pk_f32_fp8_sdwa v[226:227], v28 src0_sel:WORD_1
	v_cvt_pk_f32_fp8_e32 v[228:229], v29
	v_cvt_pk_f32_fp8_sdwa v[230:231], v29 src0_sel:WORD_1
	v_cvt_pk_f32_fp8_e32 v[232:233], v30
	v_cvt_pk_f32_fp8_sdwa v[234:235], v30 src0_sel:WORD_1
	v_cvt_pk_f32_fp8_e32 v[236:237], v31
	v_cvt_pk_f32_fp8_sdwa v[238:239], v31 src0_sel:WORD_1
	v_pk_fma_f32 v[96:97], v[224:225], s[30:31], v[96:97] op_sel_hi:[1,0,1]
	v_pk_fma_f32 v[98:99], v[226:227], s[30:31], v[98:99] op_sel_hi:[1,0,1]
	v_pk_fma_f32 v[100:101], v[228:229], s[30:31], v[100:101] op_sel_hi:[1,0,1]
	v_pk_fma_f32 v[102:103], v[230:231], s[30:31], v[102:103] op_sel_hi:[1,0,1]
	v_pk_fma_f32 v[104:105], v[232:233], s[30:31], v[104:105] op_sel_hi:[1,0,1]
	v_pk_fma_f32 v[106:107], v[234:235], s[30:31], v[106:107] op_sel_hi:[1,0,1]
	v_pk_fma_f32 v[108:109], v[236:237], s[30:31], v[108:109] op_sel_hi:[1,0,1]
	v_pk_fma_f32 v[110:111], v[238:239], s[30:31], v[110:111] op_sel_hi:[1,0,1]
	v_readlane_b32 s16, v159, s72
	v_readlane_b32 s18, v159, s73
	v_readlane_b32 s20, v159, s74
	v_readlane_b32 s22, v159, s75
	v_readlane_b32 s24, v159, s76
	v_readlane_b32 s26, v159, s77
	v_readlane_b32 s28, v159, s78
	v_readlane_b32 s30, v159, s79
	s_cmp_eq_u32 s12, 7
	s_cbranch_scc1 .Lvd_last7_Lvq_kB
	v_readlane_b32 s48, v152, s80
	v_readlane_b32 s49, v152, s81
	v_readlane_b32 s50, v152, s82
	v_readlane_b32 s51, v152, s83
	v_readlane_b32 s52, v152, s84
	v_readlane_b32 s53, v152, s85
	v_readlane_b32 s54, v152, s86
	v_readlane_b32 s55, v152, s87
	s_add_u32 s32, s0, s48
	s_addc_u32 s33, s1, 0
	s_add_u32 s34, s0, s49
	s_addc_u32 s35, s1, 0
	s_add_u32 s36, s0, s50
	s_addc_u32 s37, s1, 0
	s_add_u32 s38, s0, s51
	s_addc_u32 s39, s1, 0
	s_add_u32 s40, s0, s52
	s_addc_u32 s41, s1, 0
	s_add_u32 s42, s0, s53
	s_addc_u32 s43, s1, 0
	s_add_u32 s44, s0, s54
	s_addc_u32 s45, s1, 0
	s_add_u32 s46, s0, s55
	s_addc_u32 s47, s1, 0
	global_load_dwordx4 v[0:3], v240, s[32:33]
	global_load_dwordx4 v[4:7], v240, s[34:35]
	global_load_dwordx4 v[8:11], v240, s[36:37]
	global_load_dwordx4 v[12:15], v240, s[38:39]
	global_load_dwordx4 v[16:19], v240, s[40:41]
	global_load_dwordx4 v[20:23], v240, s[42:43]
	global_load_dwordx4 v[24:27], v240, s[44:45]
	global_load_dwordx4 v[28:31], v240, s[46:47]
	s_waitcnt vmcnt(24)
	s_branch .Lvd_cons7_Lvq_kB

; DI void peer_item_v(const Params& p, int item) {
;     ...
;     V_ISSUE(vqa, 0)
; #pragma unroll 1
;     for (int g = 0; g < 16; g += 2) {
;       V_ISSUE(vqb, g + 1)
;       V_CONSUME(vqa, g)
;       if (g + 2 < 16) V_ISSUE(vqa, g + 2)
;       V_CONSUME(vqb, g + 1)
;     }
.Lvd_cons7_Lvq_kB:
	v_cvt_pk_f32_fp8_e32 v[224:225], v32
	v_cvt_pk_f32_fp8_sdwa v[226:227], v32 src0_sel:WORD_1
	v_cvt_pk_f32_fp8_e32 v[228:229], v33
	v_cvt_pk_f32_fp8_sdwa v[230:231], v33 src0_sel:WORD_1
	v_cvt_pk_f32_fp8_e32 v[232:233], v34
	v_cvt_pk_f32_fp8_sdwa v[234:235], v34 src0_sel:WORD_1
	v_cvt_pk_f32_fp8_e32 v[236:237], v35
	v_cvt_pk_f32_fp8_sdwa v[238:239], v35 src0_sel:WORD_1
	v_pk_fma_f32 v[112:113], v[224:225], s[16:17], v[112:113] op_sel_hi:[1,0,1]
	v_pk_fma_f32 v[114:115], v[226:227], s[16:17], v[114:115] op_sel_hi:[1,0,1]
	v_pk_fma_f32 v[116:117], v[228:229], s[16:17], v[116:117] op_sel_hi:[1,0,1]
	v_pk_fma_f32 v[118:119], v[230:231], s[16:17], v[118:119] op_sel_hi:[1,0,1]
	v_pk_fma_f32 v[120:121], v[232:233], s[16:17], v[120:121] op_sel_hi:[1,0,1]
	v_pk_fma_f32 v[122:123], v[234:235], s[16:17], v[122:123] op_sel_hi:[1,0,1]
	v_pk_fma_f32 v[124:125], v[236:237], s[16:17], v[124:125] op_sel_hi:[1,0,1]
	v_pk_fma_f32 v[126:127], v[238:239], s[16:17], v[126:127] op_sel_hi:[1,0,1]
	v_cvt_pk_f32_fp8_e32 v[224:225], v36
	v_cvt_pk_f32_fp8_sdwa v[226:227], v36 src0_sel:WORD_1
	v_cvt_pk_f32_fp8_e32 v[228:229], v37
	v_cvt_pk_f32_fp8_sdwa v[230:231], v37 src0_sel:WORD_1
	v_cvt_pk_f32_fp8_e32 v[232:233], v38
	v_cvt_pk_f32_fp8_sdwa v[234:235], v38 src0_sel:WORD_1
	v_cvt_pk_f32_fp8_e32 v[236:237], v39
	v_cvt_pk_f32_fp8_sdwa v[238:239], v39 src0_sel:WORD_1
	v_pk_fma_f32 v[112:113], v[224:225], s[18:19], v[112:113] op_sel_hi:[1,0,1]
	v_pk_fma_f32 v[114:115], v[226:227], s[18:19], v[114:115] op_sel_hi:[1,0,1]
	v_pk_fma_f32 v[116:117], v[228:229], s[18:19], v[116:117] op_sel_hi:[1,0,1]
	v_pk_fma_f32 v[118:119], v[230:231], s[18:19], v[118:119] op_sel_hi:[1,0,1]
	v_pk_fma_f32 v[120:121], v[232:233], s[18:19], v[120:121] op_sel_hi:[1,0,1]
	v_pk_fma_f32 v[122:123], v[234:235], s[18:19], v[122:123] op_sel_hi:[1,0,1]
	v_pk_fma_f32 v[124:125], v[236:237], s[18:19], v[124:125] op_sel_hi:[1,0,1]
	v_pk_fma_f32 v[126:127], v[238:239], s[18:19], v[126:127] op_sel_hi:[1,0,1]
	v_cvt_pk_f32_fp8_e32 v[224:225], v40
	v_cvt_pk_f32_fp8_sdwa v[226:227], v40 src0_sel:WORD_1
	v_cvt_pk_f32_fp8_e32 v[228:229], v41
	v_cvt_pk_f32_fp8_sdwa v[230:231], v41 src0_sel:WORD_1
	v_cvt_pk_f32_fp8_e32 v[232:233], v42
	v_cvt_pk_f32_fp8_sdwa v[234:235], v42 src0_sel:WORD_1
	v_cvt_pk_f32_fp8_e32 v[236:237], v43
	v_cvt_pk_f32_fp8_sdwa v[238:239], v43 src0_sel:WORD_1
	v_pk_fma_f32 v[112:113], v[224:225], s[20:21], v[112:113] op_sel_hi:[1,0,1]
	v_pk_fma_f32 v[114:115], v[226:227], s[20:21], v[114:115] op_sel_hi:[1,0,1]
	v_pk_fma_f32 v[116:117], v[228:229], s[20:21], v[116:117] op_sel_hi:[1,0,1]
	v_pk_fma_f32 v[118:119], v[230:231], s[20:21], v[118:119] op_sel_hi:[1,0,1]
	v_pk_fma_f32 v[120:121], v[232:233], s[20:21], v[120:121] op_sel_hi:[1,0,1]
	v_pk_fma_f32 v[122:123], v[234:235], s[20:21], v[122:123] op_sel_hi:[1,0,1]
	v_pk_fma_f32 v[124:125], v[236:237], s[20:21], v[124:125] op_sel_hi:[1,0,1]
	v_pk_fma_f32 v[126:127], v[238:239], s[20:21], v[126:127] op_sel_hi:[1,0,1]
	v_cvt_pk_f32_fp8_e32 v[224:225], v44
	v_cvt_pk_f32_fp8_sdwa v[226:227], v44 src0_sel:WORD_1
	v_cvt_pk_f32_fp8_e32 v[228:229], v45
	v_cvt_pk_f32_fp8_sdwa v[230:231], v45 src0_sel:WORD_1
	v_cvt_pk_f32_fp8_e32 v[232:233], v46
	v_cvt_pk_f32_fp8_sdwa v[234:235], v46 src0_sel:WORD_1
	v_cvt_pk_f32_fp8_e32 v[236:237], v47
	v_cvt_pk_f32_fp8_sdwa v[238:239], v47 src0_sel:WORD_1
	v_pk_fma_f32 v[112:113], v[224:225], s[22:23], v[112:113] op_sel_hi:[1,0,1]
	v_pk_fma_f32 v[114:115], v[226:227], s[22:23], v[114:115] op_sel_hi:[1,0,1]
	v_pk_fma_f32 v[116:117], v[228:229], s[22:23], v[116:117] op_sel_hi:[1,0,1]
	v_pk_fma_f32 v[118:119], v[230:231], s[22:23], v[118:119] op_sel_hi:[1,0,1]
	v_pk_fma_f32 v[120:121], v[232:233], s[22:23], v[120:121] op_sel_hi:[1,0,1]
	v_pk_fma_f32 v[122:123], v[234:235], s[22:23], v[122:123] op_sel_hi:[1,0,1]
	v_pk_fma_f32 v[124:125], v[236:237], s[22:23], v[124:125] op_sel_hi:[1,0,1]
	v_pk_fma_f32 v[126:127], v[238:239], s[22:23], v[126:127] op_sel_hi:[1,0,1]
	v_cvt_pk_f32_fp8_e32 v[224:225], v48
	v_cvt_pk_f32_fp8_sdwa v[226:227], v48 src0_sel:WORD_1
	v_cvt_pk_f32_fp8_e32 v[228:229], v49
	v_cvt_pk_f32_fp8_sdwa v[230:231], v49 src0_sel:WORD_1
	v_cvt_pk_f32_fp8_e32 v[232:233], v50
	v_cvt_pk_f32_fp8_sdwa v[234:235], v50 src0_sel:WORD_1
	v_cvt_pk_f32_fp8_e32 v[236:237], v51
	v_cvt_pk_f32_fp8_sdwa v[238:239], v51 src0_sel:WORD_1
	v_pk_fma_f32 v[112:113], v[224:225], s[24:25], v[112:113] op_sel_hi:[1,0,1]
	v_pk_fma_f32 v[114:115], v[226:227], s[24:25], v[114:115] op_sel_hi:[1,0,1]
	v_pk_fma_f32 v[116:117], v[228:229], s[24:25], v[116:117] op_sel_hi:[1,0,1]
	v_pk_fma_f32 v[118:119], v[230:231], s[24:25], v[118:119] op_sel_hi:[1,0,1]
	v_pk_fma_f32 v[120:121], v[232:233], s[24:25], v[120:121] op_sel_hi:[1,0,1]
	v_pk_fma_f32 v[122:123], v[234:235], s[24:25], v[122:123] op_sel_hi:[1,0,1]
	v_pk_fma_f32 v[124:125], v[236:237], s[24:25], v[124:125] op_sel_hi:[1,0,1]
	v_pk_fma_f32 v[126:127], v[238:239], s[24:25], v[126:127] op_sel_hi:[1,0,1]
	v_cvt_pk_f32_fp8_e32 v[224:225], v52
	v_cvt_pk_f32_fp8_sdwa v[226:227], v52 src0_sel:WORD_1
	v_cvt_pk_f32_fp8_e32 v[228:229], v53
	v_cvt_pk_f32_fp8_sdwa v[230:231], v53 src0_sel:WORD_1
	v_cvt_pk_f32_fp8_e32 v[232:233], v54
	v_cvt_pk_f32_fp8_sdwa v[234:235], v54 src0_sel:WORD_1
	v_cvt_pk_f32_fp8_e32 v[236:237], v55
	v_cvt_pk_f32_fp8_sdwa v[238:239], v55 src0_sel:WORD_1
	v_pk_fma_f32 v[112:113], v[224:225], s[26:27], v[112:113] op_sel_hi:[1,0,1]
	v_pk_fma_f32 v[114:115], v[226:227], s[26:27], v[114:115] op_sel_hi:[1,0,1]
	v_pk_fma_f32 v[116:117], v[228:229], s[26:27], v[116:117] op_sel_hi:[1,0,1]
	v_pk_fma_f32 v[118:119], v[230:231], s[26:27], v[118:119] op_sel_hi:[1,0,1]
; DI void peer_item_v(const Params& p, int item) {
;     ...
;     V_ISSUE(vqa, 0)
; #pragma unroll 1
;     for (int g = 0; g < 16; g += 2) {
;       V_ISSUE(vqb, g + 1)
;       V_CONSUME(vqa, g)
;       if (g + 2 < 16) V_ISSUE(vqa, g + 2)
;       V_CONSUME(vqb, g + 1)
;     }
;     ...
;     float* orow = p.out + tok * 1024 + lane * 4;
;     float4 y[4];
;     float ss = 0.f;
; #pragma unroll
;     for (int i = 0; i < 4; ++i) {
;       y[i] = *(const float4*)(orow + 256 * i);
;       y[i].x += out[4 * i]; y[i].y += out[4 * i + 1]; y[i].z += out[4 * i + 2]; y[i].w += out[4 * i + 3];
;       ss += y[i].x * y[i].x + y[i].y * y[i].y + y[i].z * y[i].z + y[i].w * y[i].w;
;     }
;     ss = wave_sum(ss);
;     const float r = rsqrtf(ss * (1.f / 1024.f) + 1e-6f);
	v_pk_fma_f32 v[120:121], v[232:233], s[26:27], v[120:121] op_sel_hi:[1,0,1]
	v_pk_fma_f32 v[122:123], v[234:235], s[26:27], v[122:123] op_sel_hi:[1,0,1]
	v_pk_fma_f32 v[124:125], v[236:237], s[26:27], v[124:125] op_sel_hi:[1,0,1]
	v_pk_fma_f32 v[126:127], v[238:239], s[26:27], v[126:127] op_sel_hi:[1,0,1]
	v_cvt_pk_f32_fp8_e32 v[224:225], v56
	v_cvt_pk_f32_fp8_sdwa v[226:227], v56 src0_sel:WORD_1
	v_cvt_pk_f32_fp8_e32 v[228:229], v57
	v_cvt_pk_f32_fp8_sdwa v[230:231], v57 src0_sel:WORD_1
	v_cvt_pk_f32_fp8_e32 v[232:233], v58
	v_cvt_pk_f32_fp8_sdwa v[234:235], v58 src0_sel:WORD_1
	v_cvt_pk_f32_fp8_e32 v[236:237], v59
	v_cvt_pk_f32_fp8_sdwa v[238:239], v59 src0_sel:WORD_1
	v_pk_fma_f32 v[112:113], v[224:225], s[28:29], v[112:113] op_sel_hi:[1,0,1]
	v_pk_fma_f32 v[114:115], v[226:227], s[28:29], v[114:115] op_sel_hi:[1,0,1]
	v_pk_fma_f32 v[116:117], v[228:229], s[28:29], v[116:117] op_sel_hi:[1,0,1]
	v_pk_fma_f32 v[118:119], v[230:231], s[28:29], v[118:119] op_sel_hi:[1,0,1]
	v_pk_fma_f32 v[120:121], v[232:233], s[28:29], v[120:121] op_sel_hi:[1,0,1]
	v_pk_fma_f32 v[122:123], v[234:235], s[28:29], v[122:123] op_sel_hi:[1,0,1]
	v_pk_fma_f32 v[124:125], v[236:237], s[28:29], v[124:125] op_sel_hi:[1,0,1]
	v_pk_fma_f32 v[126:127], v[238:239], s[28:29], v[126:127] op_sel_hi:[1,0,1]
	v_cvt_pk_f32_fp8_e32 v[224:225], v60
	v_cvt_pk_f32_fp8_sdwa v[226:227], v60 src0_sel:WORD_1
	v_cvt_pk_f32_fp8_e32 v[228:229], v61
	v_cvt_pk_f32_fp8_sdwa v[230:231], v61 src0_sel:WORD_1
	v_cvt_pk_f32_fp8_e32 v[232:233], v62
	v_cvt_pk_f32_fp8_sdwa v[234:235], v62 src0_sel:WORD_1
	v_cvt_pk_f32_fp8_e32 v[236:237], v63
	v_cvt_pk_f32_fp8_sdwa v[238:239], v63 src0_sel:WORD_1
	v_pk_fma_f32 v[112:113], v[224:225], s[30:31], v[112:113] op_sel_hi:[1,0,1]
	v_pk_fma_f32 v[114:115], v[226:227], s[30:31], v[114:115] op_sel_hi:[1,0,1]
	v_pk_fma_f32 v[116:117], v[228:229], s[30:31], v[116:117] op_sel_hi:[1,0,1]
	v_pk_fma_f32 v[118:119], v[230:231], s[30:31], v[118:119] op_sel_hi:[1,0,1]
	v_pk_fma_f32 v[120:121], v[232:233], s[30:31], v[120:121] op_sel_hi:[1,0,1]
	v_pk_fma_f32 v[122:123], v[234:235], s[30:31], v[122:123] op_sel_hi:[1,0,1]
	v_pk_fma_f32 v[124:125], v[236:237], s[30:31], v[124:125] op_sel_hi:[1,0,1]
	v_pk_fma_f32 v[126:127], v[238:239], s[30:31], v[126:127] op_sel_hi:[1,0,1]
	s_mov_b32 s72, s80
	s_mov_b32 s73, s81
	s_mov_b32 s74, s82
	s_mov_b32 s75, s83
	s_mov_b32 s76, s84
	s_mov_b32 s77, s85
	s_mov_b32 s78, s86
	s_mov_b32 s79, s87
	s_add_u32 s80, s80, 8
	s_add_u32 s81, s81, 8
	s_add_u32 s82, s82, 8
	s_add_u32 s83, s83, 8
	s_add_u32 s84, s84, 8
	s_add_u32 s85, s85, 8
	s_add_u32 s86, s86, 8
	s_add_u32 s87, s87, 8
	s_and_b32 s80, s80, 63
	s_and_b32 s81, s81, 63
	s_and_b32 s82, s82, 63
	s_and_b32 s83, s83, 63
	s_and_b32 s84, s84, 63
	s_and_b32 s85, s85, 63
	s_and_b32 s86, s86, 63
	s_and_b32 s87, s87, 63
	s_add_u32 s12, s12, 1
	s_cmp_lt_u32 s12, 8
	s_cbranch_scc1 .Lvq_kB
	s_waitcnt vmcnt(0)
	s_add_u32 s32, s62, 16384
	s_addc_u32 s33, s63, 0
	s_add_u32 s34, s62, 20480
	s_addc_u32 s35, s63, 0
	s_add_u32 s36, s62, 24576
	s_addc_u32 s37, s63, 0
	s_add_u32 s38, s62, 28672
	s_addc_u32 s39, s63, 0
	v_pk_add_f32 v[160:161], v[160:161], v[64:65]
	v_pk_add_f32 v[162:163], v[162:163], v[66:67]
	v_pk_add_f32 v[164:165], v[164:165], v[68:69]
	v_pk_add_f32 v[166:167], v[166:167], v[70:71]
	v_pk_add_f32 v[168:169], v[168:169], v[72:73]
	v_pk_add_f32 v[170:171], v[170:171], v[74:75]
	v_pk_add_f32 v[172:173], v[172:173], v[76:77]
	v_pk_add_f32 v[174:175], v[174:175], v[78:79]
	v_pk_mul_f32 v[224:225], v[160:161], v[160:161]
	v_pk_mul_f32 v[226:227], v[162:163], v[162:163]
	v_pk_fma_f32 v[224:225], v[164:165], v[164:165], v[224:225]
	v_pk_fma_f32 v[226:227], v[166:167], v[166:167], v[226:227]
	v_pk_fma_f32 v[224:225], v[168:169], v[168:169], v[224:225]
	v_pk_fma_f32 v[226:227], v[170:171], v[170:171], v[226:227]
	v_pk_fma_f32 v[224:225], v[172:173], v[172:173], v[224:225]
	v_pk_fma_f32 v[226:227], v[174:175], v[174:175], v[226:227]
	v_pk_add_f32 v[224:225], v[224:225], v[226:227]
	s_nop 0
	v_add_f32_e32 v224, v224, v225
	ds_bpermute_b32 v225, v242, v224
	s_waitcnt lgkmcnt(0)
	v_add_f32_e32 v224, v224, v225
	ds_bpermute_b32 v225, v243, v224
	s_waitcnt lgkmcnt(0)
	v_add_f32_e32 v224, v224, v225
	ds_bpermute_b32 v225, v244, v224
	s_waitcnt lgkmcnt(0)
	v_add_f32_e32 v224, v224, v225
	ds_bpermute_b32 v225, v245, v224
	s_waitcnt lgkmcnt(0)
	v_add_f32_e32 v224, v224, v225
	ds_bpermute_b32 v225, v246, v224
	s_waitcnt lgkmcnt(0)
	v_add_f32_e32 v224, v224, v225
	ds_bpermute_b32 v225, v247, v224
	s_waitcnt lgkmcnt(0)
	v_add_f32_e32 v224, v224, v225
	v_fmamk_f32 v224, v224, 0x3a800000, v248
	v_rsq_f32_e32 v224, v224
	s_nop 1
	v_pk_mul_f32 v[226:227], v[128:129], v[224:225] op_sel_hi:[1,0]
	v_pk_mul_f32 v[160:161], v[160:161], v[226:227]
	v_pk_mul_f32 v[228:229], v[130:131], v[224:225] op_sel_hi:[1,0]
	v_pk_mul_f32 v[162:163], v[162:163], v[228:229]
	v_pk_mul_f32 v[230:231], v[132:133], v[224:225] op_sel_hi:[1,0]
	v_pk_mul_f32 v[164:165], v[164:165], v[230:231]
	v_pk_mul_f32 v[232:233], v[134:135], v[224:225] op_sel_hi:[1,0]
	v_pk_mul_f32 v[166:167], v[166:167], v[232:233]
	v_pk_mul_f32 v[226:227], v[136:137], v[224:225] op_sel_hi:[1,0]
	v_pk_mul_f32 v[168:169], v[168:169], v[226:227]
	v_pk_mul_f32 v[228:229], v[138:139], v[224:225] op_sel_hi:[1,0]
	v_pk_mul_f32 v[170:171], v[170:171], v[228:229]
	v_pk_mul_f32 v[230:231], v[140:141], v[224:225] op_sel_hi:[1,0]
	v_pk_mul_f32 v[172:173], v[172:173], v[230:231]
	v_pk_mul_f32 v[232:233], v[142:143], v[224:225] op_sel_hi:[1,0]
	v_pk_mul_f32 v[174:175], v[174:175], v[232:233]
	v_pk_add_f32 v[176:177], v[176:177], v[80:81]
	v_pk_add_f32 v[178:179], v[178:179], v[82:83]
	v_pk_add_f32 v[180:181], v[180:181], v[84:85]
	v_pk_add_f32 v[182:183], v[182:183], v[86:87]
	v_pk_add_f32 v[184:185], v[184:185], v[88:89]
	v_pk_add_f32 v[186:187], v[186:187], v[90:91]
	v_pk_add_f32 v[188:189], v[188:189], v[92:93]
	v_pk_add_f32 v[190:191], v[190:191], v[94:95]
	v_pk_mul_f32 v[224:225], v[176:177], v[176:177]
	v_pk_mul_f32 v[226:227], v[178:179], v[178:179]
	v_pk_fma_f32 v[224:225], v[180:181], v[180:181], v[224:225]
	v_pk_fma_f32 v[226:227], v[182:183], v[182:183], v[226:227]
	v_pk_fma_f32 v[224:225], v[184:185], v[184:185], v[224:225]
	v_pk_fma_f32 v[226:227], v[186:187], v[186:187], v[226:227]
	v_pk_fma_f32 v[224:225], v[188:189], v[188:189], v[224:225]
	v_pk_fma_f32 v[226:227], v[190:191], v[190:191], v[226:227]
	v_pk_add_f32 v[224:225], v[224:225], v[226:227]
	s_nop 0
	v_add_f32_e32 v224, v224, v225
	ds_bpermute_b32 v225, v242, v224
	s_waitcnt lgkmcnt(0)
; DI void peer_item_v(const Params& p, int item) {
;     ...
;     float ss = 0.f;
; #pragma unroll
;     for (int i = 0; i < 4; ++i) {
;       y[i] = *(const float4*)(orow + 256 * i);
;       y[i].x += out[4 * i]; y[i].y += out[4 * i + 1]; y[i].z += out[4 * i + 2]; y[i].w += out[4 * i + 3];
;       ss += y[i].x * y[i].x + y[i].y * y[i].y + y[i].z * y[i].z + y[i].w * y[i].w;
;     }
;     ss = wave_sum(ss);
;     const float r = rsqrtf(ss * (1.f / 1024.f) + 1e-6f);
; #pragma unroll
;     for (int i = 0; i < 4; ++i) {
;       float4 g = *(const float4*)(p.g_final + 256 * i + lane * 4);
;       y[i].x *= r * g.x; y[i].y *= r * g.y; y[i].z *= r * g.z; y[i].w *= r * g.w;
	v_add_f32_e32 v224, v224, v225
	ds_bpermute_b32 v225, v243, v224
	s_waitcnt lgkmcnt(0)
	v_add_f32_e32 v224, v224, v225
	ds_bpermute_b32 v225, v244, v224
	s_waitcnt lgkmcnt(0)
	v_add_f32_e32 v224, v224, v225
	ds_bpermute_b32 v225, v245, v224
	s_waitcnt lgkmcnt(0)
	v_add_f32_e32 v224, v224, v225
	ds_bpermute_b32 v225, v246, v224
	s_waitcnt lgkmcnt(0)
	v_add_f32_e32 v224, v224, v225
	ds_bpermute_b32 v225, v247, v224
	s_waitcnt lgkmcnt(0)
	v_add_f32_e32 v224, v224, v225
	v_fmamk_f32 v224, v224, 0x3a800000, v248
	v_rsq_f32_e32 v224, v224
	s_nop 1
	v_pk_mul_f32 v[226:227], v[128:129], v[224:225] op_sel_hi:[1,0]
	v_pk_mul_f32 v[176:177], v[176:177], v[226:227]
	v_pk_mul_f32 v[228:229], v[130:131], v[224:225] op_sel_hi:[1,0]
	v_pk_mul_f32 v[178:179], v[178:179], v[228:229]
	v_pk_mul_f32 v[230:231], v[132:133], v[224:225] op_sel_hi:[1,0]
	v_pk_mul_f32 v[180:181], v[180:181], v[230:231]
	v_pk_mul_f32 v[232:233], v[134:135], v[224:225] op_sel_hi:[1,0]
	v_pk_mul_f32 v[182:183], v[182:183], v[232:233]
	v_pk_mul_f32 v[226:227], v[136:137], v[224:225] op_sel_hi:[1,0]
	v_pk_mul_f32 v[184:185], v[184:185], v[226:227]
	v_pk_mul_f32 v[228:229], v[138:139], v[224:225] op_sel_hi:[1,0]
	v_pk_mul_f32 v[186:187], v[186:187], v[228:229]
	v_pk_mul_f32 v[230:231], v[140:141], v[224:225] op_sel_hi:[1,0]
	v_pk_mul_f32 v[188:189], v[188:189], v[230:231]
	v_pk_mul_f32 v[232:233], v[142:143], v[224:225] op_sel_hi:[1,0]
	v_pk_mul_f32 v[190:191], v[190:191], v[232:233]
	v_pk_add_f32 v[192:193], v[192:193], v[96:97]
	v_pk_add_f32 v[194:195], v[194:195], v[98:99]
	v_pk_add_f32 v[196:197], v[196:197], v[100:101]
	v_pk_add_f32 v[198:199], v[198:199], v[102:103]
	v_pk_add_f32 v[200:201], v[200:201], v[104:105]
	v_pk_add_f32 v[202:203], v[202:203], v[106:107]
	v_pk_add_f32 v[204:205], v[204:205], v[108:109]
	v_pk_add_f32 v[206:207], v[206:207], v[110:111]
	v_pk_mul_f32 v[224:225], v[192:193], v[192:193]
	v_pk_mul_f32 v[226:227], v[194:195], v[194:195]
	v_pk_fma_f32 v[224:225], v[196:197], v[196:197], v[224:225]
	v_pk_fma_f32 v[226:227], v[198:199], v[198:199], v[226:227]
	v_pk_fma_f32 v[224:225], v[200:201], v[200:201], v[224:225]
	v_pk_fma_f32 v[226:227], v[202:203], v[202:203], v[226:227]
	v_pk_fma_f32 v[224:225], v[204:205], v[204:205], v[224:225]
	v_pk_fma_f32 v[226:227], v[206:207], v[206:207], v[226:227]
	v_pk_add_f32 v[224:225], v[224:225], v[226:227]
	s_nop 0
	v_add_f32_e32 v224, v224, v225
	ds_bpermute_b32 v225, v242, v224
	s_waitcnt lgkmcnt(0)
	v_add_f32_e32 v224, v224, v225
	ds_bpermute_b32 v225, v243, v224
	s_waitcnt lgkmcnt(0)
	v_add_f32_e32 v224, v224, v225
	ds_bpermute_b32 v225, v244, v224
	s_waitcnt lgkmcnt(0)
	v_add_f32_e32 v224, v224, v225
	ds_bpermute_b32 v225, v245, v224
	s_waitcnt lgkmcnt(0)
	v_add_f32_e32 v224, v224, v225
	ds_bpermute_b32 v225, v246, v224
	s_waitcnt lgkmcnt(0)
	v_add_f32_e32 v224, v224, v225
	ds_bpermute_b32 v225, v247, v224
	s_waitcnt lgkmcnt(0)
; DI void peer_item_v(const Params& p, int item) {
;     ...
;     float* orow = p.out + tok * 1024 + lane * 4;
;     float4 y[4];
;     float ss = 0.f;
; #pragma unroll
;     for (int i = 0; i < 4; ++i) {
;       y[i] = *(const float4*)(orow + 256 * i);
;       y[i].x += out[4 * i]; y[i].y += out[4 * i + 1]; y[i].z += out[4 * i + 2]; y[i].w += out[4 * i + 3];
;       ss += y[i].x * y[i].x + y[i].y * y[i].y + y[i].z * y[i].z + y[i].w * y[i].w;
;     }
;     ss = wave_sum(ss);
;     const float r = rsqrtf(ss * (1.f / 1024.f) + 1e-6f);
; #pragma unroll
;     for (int i = 0; i < 4; ++i) {
;       float4 g = *(const float4*)(p.g_final + 256 * i + lane * 4);
;       y[i].x *= r * g.x; y[i].y *= r * g.y; y[i].z *= r * g.z; y[i].w *= r * g.w;
;       *(float4*)(orow + 256 * i) = y[i];
;     }
	v_add_f32_e32 v224, v224, v225
	v_fmamk_f32 v224, v224, 0x3a800000, v248
	v_rsq_f32_e32 v224, v224
	s_nop 1
	v_pk_mul_f32 v[226:227], v[128:129], v[224:225] op_sel_hi:[1,0]
	v_pk_mul_f32 v[192:193], v[192:193], v[226:227]
	v_pk_mul_f32 v[228:229], v[130:131], v[224:225] op_sel_hi:[1,0]
	v_pk_mul_f32 v[194:195], v[194:195], v[228:229]
	v_pk_mul_f32 v[230:231], v[132:133], v[224:225] op_sel_hi:[1,0]
	v_pk_mul_f32 v[196:197], v[196:197], v[230:231]
	v_pk_mul_f32 v[232:233], v[134:135], v[224:225] op_sel_hi:[1,0]
	v_pk_mul_f32 v[198:199], v[198:199], v[232:233]
	v_pk_mul_f32 v[226:227], v[136:137], v[224:225] op_sel_hi:[1,0]
	v_pk_mul_f32 v[200:201], v[200:201], v[226:227]
	v_pk_mul_f32 v[228:229], v[138:139], v[224:225] op_sel_hi:[1,0]
	v_pk_mul_f32 v[202:203], v[202:203], v[228:229]
	v_pk_mul_f32 v[230:231], v[140:141], v[224:225] op_sel_hi:[1,0]
	v_pk_mul_f32 v[204:205], v[204:205], v[230:231]
	v_pk_mul_f32 v[232:233], v[142:143], v[224:225] op_sel_hi:[1,0]
	v_pk_mul_f32 v[206:207], v[206:207], v[232:233]
	v_pk_add_f32 v[208:209], v[208:209], v[112:113]
	v_pk_add_f32 v[210:211], v[210:211], v[114:115]
	v_pk_add_f32 v[212:213], v[212:213], v[116:117]
	v_pk_add_f32 v[214:215], v[214:215], v[118:119]
	v_pk_add_f32 v[216:217], v[216:217], v[120:121]
	v_pk_add_f32 v[218:219], v[218:219], v[122:123]
	v_pk_add_f32 v[220:221], v[220:221], v[124:125]
	v_pk_add_f32 v[222:223], v[222:223], v[126:127]
	v_pk_mul_f32 v[224:225], v[208:209], v[208:209]
	v_pk_mul_f32 v[226:227], v[210:211], v[210:211]
	v_pk_fma_f32 v[224:225], v[212:213], v[212:213], v[224:225]
	v_pk_fma_f32 v[226:227], v[214:215], v[214:215], v[226:227]
	v_pk_fma_f32 v[224:225], v[216:217], v[216:217], v[224:225]
	v_pk_fma_f32 v[226:227], v[218:219], v[218:219], v[226:227]
	v_pk_fma_f32 v[224:225], v[220:221], v[220:221], v[224:225]
	v_pk_fma_f32 v[226:227], v[222:223], v[222:223], v[226:227]
	v_pk_add_f32 v[224:225], v[224:225], v[226:227]
	s_nop 0
	v_add_f32_e32 v224, v224, v225
	ds_bpermute_b32 v225, v242, v224
	s_waitcnt lgkmcnt(0)
	v_add_f32_e32 v224, v224, v225
	ds_bpermute_b32 v225, v243, v224
	s_waitcnt lgkmcnt(0)
	v_add_f32_e32 v224, v224, v225
	ds_bpermute_b32 v225, v244, v224
	s_waitcnt lgkmcnt(0)
	v_add_f32_e32 v224, v224, v225
	ds_bpermute_b32 v225, v245, v224
	s_waitcnt lgkmcnt(0)
	v_add_f32_e32 v224, v224, v225
	ds_bpermute_b32 v225, v246, v224
	s_waitcnt lgkmcnt(0)
	v_add_f32_e32 v224, v224, v225
	ds_bpermute_b32 v225, v247, v224
	s_waitcnt lgkmcnt(0)
	v_add_f32_e32 v224, v224, v225
	v_fmamk_f32 v224, v224, 0x3a800000, v248
	v_rsq_f32_e32 v224, v224
	s_nop 1
	v_pk_mul_f32 v[226:227], v[128:129], v[224:225] op_sel_hi:[1,0]
	v_pk_mul_f32 v[208:209], v[208:209], v[226:227]
	v_pk_mul_f32 v[228:229], v[130:131], v[224:225] op_sel_hi:[1,0]
	v_pk_mul_f32 v[210:211], v[210:211], v[228:229]
	v_pk_mul_f32 v[230:231], v[132:133], v[224:225] op_sel_hi:[1,0]
	v_pk_mul_f32 v[212:213], v[212:213], v[230:231]
	v_pk_mul_f32 v[232:233], v[134:135], v[224:225] op_sel_hi:[1,0]
	v_pk_mul_f32 v[214:215], v[214:215], v[232:233]
	v_pk_mul_f32 v[226:227], v[136:137], v[224:225] op_sel_hi:[1,0]
	v_pk_mul_f32 v[216:217], v[216:217], v[226:227]
	v_pk_mul_f32 v[228:229], v[138:139], v[224:225] op_sel_hi:[1,0]
	v_pk_mul_f32 v[218:219], v[218:219], v[228:229]
	v_pk_mul_f32 v[230:231], v[140:141], v[224:225] op_sel_hi:[1,0]
	v_pk_mul_f32 v[220:221], v[220:221], v[230:231]
	v_pk_mul_f32 v[232:233], v[142:143], v[224:225] op_sel_hi:[1,0]
	v_pk_mul_f32 v[222:223], v[222:223], v[232:233]
	global_store_dwordx4 v240, v[160:163], s[32:33]
	global_store_dwordx4 v240, v[164:167], s[32:33] offset:1024
	global_store_dwordx4 v240, v[168:171], s[32:33] offset:2048
	global_store_dwordx4 v240, v[172:175], s[32:33] offset:3072
	global_store_dwordx4 v240, v[176:179], s[34:35]
	global_store_dwordx4 v240, v[180:183], s[34:35] offset:1024
	global_store_dwordx4 v240, v[184:187], s[34:35] offset:2048
	global_store_dwordx4 v240, v[188:191], s[34:35] offset:3072
	global_store_dwordx4 v240, v[192:195], s[36:37]
	global_store_dwordx4 v240, v[196:199], s[36:37] offset:1024
	global_store_dwordx4 v240, v[200:203], s[36:37] offset:2048
	global_store_dwordx4 v240, v[204:207], s[36:37] offset:3072
	global_store_dwordx4 v240, v[208:211], s[38:39]
	global_store_dwordx4 v240, v[212:215], s[38:39] offset:1024
	global_store_dwordx4 v240, v[216:219], s[38:39] offset:2048
	global_store_dwordx4 v240, v[220:223], s[38:39] offset:3072
	s_nop 1
	s_add_i32 s10, s10, s11
	s_cmpk_lt_i32 s10, 0x200
	s_cbranch_scc1 .Lvq_item
